# v24: v23 + epilogue operands (per-row rinv, first-row cos/sin) requested from inside the last k-iteration of each tile in both input-projection GEMMs, so the epilogue starts without an exposed load ro
# baseline (speedup 1.0000x reference)
.Lb1_ph3:
	s_add_i32 s50, 16, 0x18000
	v_add_u32_e32 v151, s50, v176
	s_add_i32 s51, 16, 0x1c000
	ds_read_b128 v[132:135], v151
	ds_read_b128 v[152:155], v151 offset:1024
	ds_read_b128 v[156:159], v151 offset:2048
	ds_read_b128 v[160:163], v151 offset:3072
	v_add_u32_e32 v151, s51, v176
	ds_read_b128 v[164:167], v151
	ds_read_b128 v[168:171], v151 offset:1024
	ds_read_b128 v[172:175], v151 offset:2048
	ds_read_b128 v[180:183], v151 offset:3072
	s_mov_b32 m0, s37
	s_nop 0
	global_load_lds_dwordx4 v[220:221], off
	s_mov_b32 m0, s38
	s_nop 0
	global_load_lds_dwordx4 v[224:225], off
	s_add_u32 s8, s8, 0x40000
	s_addc_u32 s9, s9, 0
	s_mov_b32 m0, s39
	v_lshl_add_u64 v[226:227], s[8:9], 0, v[140:141]
	ds_read_b128 v[184:187], v178 offset:32768
	ds_read_b128 v[188:191], v178 offset:33792
	ds_read_b128 v[192:195], v178 offset:34816
	ds_read_b128 v[196:199], v178 offset:35840
	ds_read_b128 v[200:203], v178 offset:36864
	ds_read_b128 v[204:207], v178 offset:37888
	ds_read_b128 v[208:211], v178 offset:38912
	ds_read_b128 v[212:215], v178 offset:39936
	global_load_lds_dwordx4 v[226:227], off
	v_lshl_add_u64 v[226:227], s[8:9], 0, v[136:137]
	s_mov_b32 m0, s40
	s_nop 0
	global_load_lds_dwordx4 v[226:227], off
	s_waitcnt vmcnt(8)
	s_cmp_eq_u32 s49, 12
	s_cbranch_scc0 .Lb1pf_skip
	v_lshl_add_u32 v251, s2, 8, v3
	v_lshlrev_b32_e32 v230, 7, v251
	v_lshlrev_b32_e32 v251, 2, v251
	global_load_dword v228, v251, s[16:17]
	global_load_dword v229, v251, s[16:17] offset:64
	global_load_dword v244, v251, s[16:17] offset:128
	global_load_dword v245, v251, s[16:17] offset:192
	global_load_dword v246, v251, s[16:17] offset:512
	global_load_dword v248, v251, s[16:17] offset:576
	global_load_dword v249, v251, s[16:17] offset:640
	global_load_dword v250, v251, s[16:17] offset:704
	v_add_co_u32_e32 v252, vcc, v144, v230
	s_nop 1
	v_addc_co_u32_e32 v253, vcc, 0, v145, vcc
	global_load_dwordx4 v[236:239], v[252:253], off
	v_add_co_u32_e32 v252, vcc, 0x200000, v252
	s_nop 1
	v_addc_co_u32_e32 v253, vcc, 0, v253, vcc
	global_load_dwordx4 v[240:243], v[252:253], off
.Lb1pf_skip:
	s_waitcnt lgkmcnt(0)
	s_barrier
	s_setprio 1
	s_waitcnt lgkmcnt(0)
	v_mfma_f32_16x16x32_bf16 v[128:131], v[132:135], v[184:187], v[128:131]
	v_mfma_f32_16x16x32_bf16 v[124:127], v[156:159], v[184:187], v[124:127]
	v_mfma_f32_16x16x32_bf16 v[112:115], v[132:135], v[192:195], v[112:115]
	v_mfma_f32_16x16x32_bf16 v[108:111], v[156:159], v[192:195], v[108:111]
	v_mfma_f32_16x16x32_bf16 v[96:99], v[132:135], v[200:203], v[96:99]
	v_mfma_f32_16x16x32_bf16 v[92:95], v[156:159], v[200:203], v[92:95]
	v_mfma_f32_16x16x32_bf16 v[80:83], v[132:135], v[208:211], v[80:83]
	v_mfma_f32_16x16x32_bf16 v[76:79], v[156:159], v[208:211], v[76:79]
	v_mfma_f32_16x16x32_bf16 v[128:131], v[152:155], v[188:191], v[128:131]
	v_mfma_f32_16x16x32_bf16 v[124:127], v[160:163], v[188:191], v[124:127]
	v_mfma_f32_16x16x32_bf16 v[112:115], v[152:155], v[196:199], v[112:115]
	v_mfma_f32_16x16x32_bf16 v[108:111], v[160:163], v[196:199], v[108:111]
	v_mfma_f32_16x16x32_bf16 v[96:99], v[152:155], v[204:207], v[96:99]
	v_mfma_f32_16x16x32_bf16 v[92:95], v[160:163], v[204:207], v[92:95]
	v_mfma_f32_16x16x32_bf16 v[80:83], v[152:155], v[212:215], v[80:83]
	v_mfma_f32_16x16x32_bf16 v[76:79], v[160:163], v[212:215], v[76:79]
	s_setprio 0
	s_setprio 1
	v_mfma_f32_16x16x32_bf16 v[120:123], v[164:167], v[184:187], v[120:123]
	v_mfma_f32_16x16x32_bf16 v[116:119], v[172:175], v[184:187], v[116:119]
	v_mfma_f32_16x16x32_bf16 v[104:107], v[164:167], v[192:195], v[104:107]
	v_mfma_f32_16x16x32_bf16 v[100:103], v[172:175], v[192:195], v[100:103]
	v_mfma_f32_16x16x32_bf16 v[88:91], v[164:167], v[200:203], v[88:91]
	v_mfma_f32_16x16x32_bf16 v[84:87], v[172:175], v[200:203], v[84:87]
	v_mfma_f32_16x16x32_bf16 v[72:75], v[164:167], v[208:211], v[72:75]
	v_mfma_f32_16x16x32_bf16 v[68:71], v[172:175], v[208:211], v[68:71]
	v_mfma_f32_16x16x32_bf16 v[120:123], v[168:171], v[188:191], v[120:123]
	v_mfma_f32_16x16x32_bf16 v[116:119], v[180:183], v[188:191], v[116:119]
	v_mfma_f32_16x16x32_bf16 v[104:107], v[168:171], v[196:199], v[104:107]
	v_mfma_f32_16x16x32_bf16 v[100:103], v[180:183], v[196:199], v[100:103]
	v_mfma_f32_16x16x32_bf16 v[88:91], v[168:171], v[204:207], v[88:91]
	v_mfma_f32_16x16x32_bf16 v[84:87], v[180:183], v[204:207], v[84:87]
	v_mfma_f32_16x16x32_bf16 v[72:75], v[168:171], v[212:215], v[72:75]
	v_mfma_f32_16x16x32_bf16 v[68:71], v[180:183], v[212:215], v[68:71]
	s_setprio 0
	s_barrier
	s_add_i32 s8, s50, s36
	v_lshl_add_u64 v[216:217], v[216:217], 0, s[84:85]
	s_mov_b32 m0, s8
	ds_read_b128 v[184:187], v178 offset:49152
	ds_read_b128 v[188:191], v178 offset:50176
	ds_read_b128 v[192:195], v178 offset:51200
	ds_read_b128 v[196:199], v178 offset:52224
	ds_read_b128 v[200:203], v178 offset:53248
	ds_read_b128 v[204:207], v178 offset:54272
	ds_read_b128 v[208:211], v178 offset:55296
	ds_read_b128 v[212:215], v178 offset:56320
	global_load_lds_dwordx4 v[216:217], off
	s_add_i32 m0, s8, 0x2000
	s_add_u32 s6, s6, 0x40080
	v_lshl_add_u64 v[216:217], v[218:219], 0, s[84:85]
	s_addc_u32 s7, s7, 0
	s_add_i32 s8, s51, s36
	global_load_lds_dwordx4 v[216:217], off
	v_lshl_add_u64 v[216:217], s[6:7], 0, v[138:139]
	s_mov_b32 m0, s8
	s_nop 0
	global_load_lds_dwordx4 v[216:217], off
	v_lshl_add_u64 v[216:217], s[6:7], 0, v[0:1]
	s_add_i32 m0, s8, 0x2000
	s_nop 0
	global_load_lds_dwordx4 v[216:217], off
	v_lshl_add_u64 v[216:217], v[220:221], 0, s[84:85]
	s_mov_b32 m0, s44
	s_nop 0
	global_load_lds_dwordx4 v[216:217], off
	v_lshl_add_u64 v[216:217], v[224:225], 0, s[84:85]
	s_mov_b32 m0, s45
	s_nop 0
	global_load_lds_dwordx4 v[216:217], off
	s_cmp_eq_u32 s49, 12
	s_cbranch_scc1 .Lb1w4_last
	s_waitcnt vmcnt(8)
	s_branch .Lb1w4_j
.Lb1w4_last:
	s_waitcnt vmcnt(18)
.Lb1w4_j:
	s_waitcnt lgkmcnt(0)
	s_barrier
	s_setprio 1
	s_waitcnt lgkmcnt(0)
	v_mfma_f32_16x16x32_bf16 v[64:67], v[132:135], v[184:187], v[64:67]
	v_mfma_f32_16x16x32_bf16 v[60:63], v[156:159], v[184:187], v[60:63]
	v_mfma_f32_16x16x32_bf16 v[48:51], v[132:135], v[192:195], v[48:51]
	v_mfma_f32_16x16x32_bf16 v[44:47], v[156:159], v[192:195], v[44:47]
	v_mfma_f32_16x16x32_bf16 v[32:35], v[132:135], v[200:203], v[32:35]
	v_mfma_f32_16x16x32_bf16 v[28:31], v[156:159], v[200:203], v[28:31]
	v_mfma_f32_16x16x32_bf16 v[16:19], v[132:135], v[208:211], v[16:19]
	v_mfma_f32_16x16x32_bf16 v[12:15], v[156:159], v[208:211], v[12:15]
	v_mfma_f32_16x16x32_bf16 v[64:67], v[152:155], v[188:191], v[64:67]
	v_mfma_f32_16x16x32_bf16 v[60:63], v[160:163], v[188:191], v[60:63]
	v_mfma_f32_16x16x32_bf16 v[48:51], v[152:155], v[196:199], v[48:51]
	v_mfma_f32_16x16x32_bf16 v[44:47], v[160:163], v[196:199], v[44:47]
	v_mfma_f32_16x16x32_bf16 v[32:35], v[152:155], v[204:207], v[32:35]
	v_mfma_f32_16x16x32_bf16 v[28:31], v[160:163], v[204:207], v[28:31]
	v_mfma_f32_16x16x32_bf16 v[16:19], v[152:155], v[212:215], v[16:19]
	v_mfma_f32_16x16x32_bf16 v[12:15], v[160:163], v[212:215], v[12:15]
	s_setprio 0
	s_setprio 1
	v_mfma_f32_16x16x32_bf16 v[56:59], v[164:167], v[184:187], v[56:59]
	v_mfma_f32_16x16x32_bf16 v[52:55], v[172:175], v[184:187], v[52:55]
	v_mfma_f32_16x16x32_bf16 v[40:43], v[164:167], v[192:195], v[40:43]
	v_mfma_f32_16x16x32_bf16 v[36:39], v[172:175], v[192:195], v[36:39]
	v_mfma_f32_16x16x32_bf16 v[24:27], v[164:167], v[200:203], v[24:27]
	v_mfma_f32_16x16x32_bf16 v[20:23], v[172:175], v[200:203], v[20:23]
	v_mfma_f32_16x16x32_bf16 v[8:11], v[164:167], v[208:211], v[8:11]
	v_mfma_f32_16x16x32_bf16 v[4:7], v[172:175], v[208:211], v[4:7]
	v_mfma_f32_16x16x32_bf16 v[56:59], v[168:171], v[188:191], v[56:59]
	v_mfma_f32_16x16x32_bf16 v[52:55], v[180:183], v[188:191], v[52:55]
	v_mfma_f32_16x16x32_bf16 v[40:43], v[168:171], v[196:199], v[40:43]
	v_mfma_f32_16x16x32_bf16 v[36:39], v[180:183], v[196:199], v[36:39]
	v_mfma_f32_16x16x32_bf16 v[24:27], v[168:171], v[204:207], v[24:27]
	v_mfma_f32_16x16x32_bf16 v[20:23], v[180:183], v[204:207], v[20:23]
	v_mfma_f32_16x16x32_bf16 v[8:11], v[168:171], v[212:215], v[8:11]
	v_mfma_f32_16x16x32_bf16 v[4:7], v[180:183], v[212:215], v[4:7]
	s_setprio 0
	s_barrier
	s_add_i32 s49, s49, 2
	s_add_u32 s0, s0, 0x100
	s_addc_u32 s1, s1, 0
	s_add_u32 s29, s29, 0x100
	s_addc_u32 s42, s42, 0
	s_cmp_gt_u32 s49, 13
	s_cbranch_scc0 .LBB0_156
	s_and_b64 vcc, exec, s[18:19]
	s_cbranch_vccz .LBB0_159
	s_barrier

.LBB0_163:
	s_mul_hi_i32 s6, s48, 0x2aaaaaab
	s_lshr_b32 s7, s6, 31
	s_ashr_i32 s6, s6, 1
	s_add_i32 s9, s6, s7
	s_mul_i32 s6, s9, 12
	s_sub_i32 s6, s48, s6
	s_ashr_i32 s21, s6, 2
	s_sub_u32 s0, s41, 0x4d00000
	s_subb_u32 s1, s43, 0
	s_add_u32 s2, s0, 0x200000
	s_addc_u32 s3, s1, 0
	s_cmp_gt_i32 s21, 1
	s_cbranch_scc1 .Lb1q_vonly
	v_subrev_u32_e32 v154, s0, v144
	v_lshl_add_u32 v155, v152, 7, v154
	v_add_u32_e32 v156, 0x1000, v155
	global_load_dwordx4 v[196:199], v155, s[0:1] offset:2048
	global_load_dwordx4 v[200:203], v155, s[2:3] offset:2048
	global_load_dwordx4 v[204:207], v156, s[0:1]
	global_load_dwordx4 v[208:211], v156, s[2:3]
	global_load_dwordx4 v[212:215], v156, s[0:1] offset:2048
	global_load_dwordx4 v[216:219], v156, s[2:3] offset:2048
	s_lshl_b32 s23, s48, 2
	s_and_b32 s23, s23, 12
	s_or_b32 s23, s23, s46
	s_lshl_b32 s28, s9, 1
	s_sub_i32 s29, 14, s28
	s_cmp_eq_u32 s21, 2
	s_cselect_b32 s7, 1, 0
	s_or_b32 s7, s28, s7
	s_cmp_eq_u32 s21, 0
	s_cselect_b32 s6, s9, s7
	s_cselect_b32 s8, 0, 0x6000000
	s_cselect_b32 s7, 0x3e38aa3b, 1.0
	v_mov_b32_e32 v179, s7
	s_add_u32 s8, s41, s8
	s_addc_u32 s9, s43, 0
	s_mov_b32 s7, 0
	s_lshl_b64 s[6:7], s[6:7], 25
	s_add_u32 s6, s8, s6
	s_addc_u32 s7, s9, s7
	s_lshl_b32 s8, s23, 21
	s_add_u32 s6, s6, s8
	s_addc_u32 s7, s7, 0
	s_add_u32 s8, s6, 0x400000
	s_addc_u32 s9, s7, 0
	v_lshlrev_b32_e32 v151, s29, v152
	v_and_b32_e32 v151, 0x3fff, v151
	v_lshrrev_b32_e32 v159, s28, v152
	v_add_u32_e32 v151, v151, v159
	v_lshl_add_u32 v160, v151, 7, v150
	s_lshr_b32 s21, 0x800, s28
	s_lshr_b32 s23, 0x4000, s28
	v_add_u32_e32 v161, s21, v160
	v_add_u32_e32 v162, s21, v161
	v_add_u32_e32 v163, s21, v162
	v_add_u32_e32 v164, s23, v160
	v_add_u32_e32 v165, s21, v164
	v_add_u32_e32 v166, s21, v165
	v_add_u32_e32 v167, s21, v166
	v_add_u32_e32 v157, 0x4000, v155
	v_add_u32_e32 v158, 0x5000, v155
	s_waitcnt vmcnt(6)
	v_mul_f32_e32 v220, v179, v228
	v_pk_mul_f32 v[236:237], v[220:221], v[236:237] op_sel_hi:[0,1]
	v_pk_mul_f32 v[238:239], v[220:221], v[238:239] op_sel_hi:[0,1]
	v_pk_mul_f32 v[240:241], v[220:221], v[240:241] op_sel_hi:[0,1]
	v_pk_mul_f32 v[242:243], v[220:221], v[242:243] op_sel_hi:[0,1]
	v_pk_mul_f32 v[132:133], v[128:129], v[236:237]
	v_pk_mul_f32 v[134:135], v[130:131], v[238:239]
	v_pk_mul_f32 v[224:225], v[124:125], v[236:237]
	v_pk_mul_f32 v[226:227], v[126:127], v[238:239]
	v_pk_fma_f32 v[132:133], v[124:125], v[240:241], v[132:133] neg_lo:[1,0,0] neg_hi:[1,0,0]
	v_pk_fma_f32 v[134:135], v[126:127], v[242:243], v[134:135] neg_lo:[1,0,0] neg_hi:[1,0,0]
	v_pk_fma_f32 v[224:225], v[128:129], v[240:241], v[224:225]
	v_pk_fma_f32 v[226:227], v[130:131], v[242:243], v[226:227]
	v_cvt_pk_bf16_f32 v128, v132, v133
	v_cvt_pk_bf16_f32 v129, v134, v135
	v_cvt_pk_bf16_f32 v130, v224, v225
	v_cvt_pk_bf16_f32 v131, v226, v227
	global_store_dwordx4 v160, v[128:131], s[6:7]
	v_pk_mul_f32 v[168:169], v[120:121], v[236:237]
	v_pk_mul_f32 v[170:171], v[122:123], v[238:239]
	v_pk_mul_f32 v[172:173], v[116:117], v[236:237]
	v_pk_mul_f32 v[174:175], v[118:119], v[238:239]
	v_pk_fma_f32 v[168:169], v[116:117], v[240:241], v[168:169] neg_lo:[1,0,0] neg_hi:[1,0,0]
	v_pk_fma_f32 v[170:171], v[118:119], v[242:243], v[170:171] neg_lo:[1,0,0] neg_hi:[1,0,0]
	v_pk_fma_f32 v[172:173], v[120:121], v[240:241], v[172:173]
	v_pk_fma_f32 v[174:175], v[122:123], v[242:243], v[174:175]
	v_cvt_pk_bf16_f32 v120, v168, v169
	v_cvt_pk_bf16_f32 v121, v170, v171
	v_cvt_pk_bf16_f32 v122, v172, v173
	v_cvt_pk_bf16_f32 v123, v174, v175
	global_store_dwordx4 v160, v[120:123], s[8:9]
	s_waitcnt vmcnt(6)
	v_mul_f32_e32 v220, v179, v229
	v_pk_mul_f32 v[196:197], v[220:221], v[196:197] op_sel_hi:[0,1]
	v_pk_mul_f32 v[198:199], v[220:221], v[198:199] op_sel_hi:[0,1]
	v_pk_mul_f32 v[200:201], v[220:221], v[200:201] op_sel_hi:[0,1]
	v_pk_mul_f32 v[202:203], v[220:221], v[202:203] op_sel_hi:[0,1]
	v_pk_mul_f32 v[132:133], v[112:113], v[196:197]
	v_pk_mul_f32 v[134:135], v[114:115], v[198:199]
	v_pk_mul_f32 v[224:225], v[108:109], v[196:197]
	v_pk_mul_f32 v[226:227], v[110:111], v[198:199]
	v_pk_fma_f32 v[132:133], v[108:109], v[200:201], v[132:133] neg_lo:[1,0,0] neg_hi:[1,0,0]
	v_pk_fma_f32 v[134:135], v[110:111], v[202:203], v[134:135] neg_lo:[1,0,0] neg_hi:[1,0,0]
	v_pk_fma_f32 v[224:225], v[112:113], v[200:201], v[224:225]
	v_pk_fma_f32 v[226:227], v[114:115], v[202:203], v[226:227]
	v_cvt_pk_bf16_f32 v112, v132, v133
	v_cvt_pk_bf16_f32 v113, v134, v135
	v_cvt_pk_bf16_f32 v114, v224, v225
	v_cvt_pk_bf16_f32 v115, v226, v227
	global_store_dwordx4 v161, v[112:115], s[6:7]
	v_pk_mul_f32 v[168:169], v[104:105], v[196:197]
	v_pk_mul_f32 v[170:171], v[106:107], v[198:199]
	v_pk_mul_f32 v[172:173], v[100:101], v[196:197]
	v_pk_mul_f32 v[174:175], v[102:103], v[198:199]
	v_pk_fma_f32 v[168:169], v[100:101], v[200:201], v[168:169] neg_lo:[1,0,0] neg_hi:[1,0,0]
	v_pk_fma_f32 v[170:171], v[102:103], v[202:203], v[170:171] neg_lo:[1,0,0] neg_hi:[1,0,0]
	v_pk_fma_f32 v[172:173], v[104:105], v[200:201], v[172:173]
	v_pk_fma_f32 v[174:175], v[106:107], v[202:203], v[174:175]
	v_cvt_pk_bf16_f32 v104, v168, v169
	v_cvt_pk_bf16_f32 v105, v170, v171
	v_cvt_pk_bf16_f32 v106, v172, v173
	v_cvt_pk_bf16_f32 v107, v174, v175
	global_store_dwordx4 v161, v[104:107], s[8:9]
	global_load_dwordx4 v[100:103], v157, s[0:1]
	global_load_dwordx4 v[104:107], v157, s[2:3]
	global_load_dwordx4 v[108:111], v157, s[0:1] offset:2048
	global_load_dwordx4 v[112:115], v157, s[2:3] offset:2048
	global_load_dwordx4 v[116:119], v158, s[0:1]
	global_load_dwordx4 v[120:123], v158, s[2:3]
	global_load_dwordx4 v[124:127], v158, s[0:1] offset:2048
	global_load_dwordx4 v[128:131], v158, s[2:3] offset:2048
	s_waitcnt vmcnt(14)
	v_mul_f32_e32 v220, v179, v244
	v_pk_mul_f32 v[204:205], v[220:221], v[204:205] op_sel_hi:[0,1]
	v_pk_mul_f32 v[206:207], v[220:221], v[206:207] op_sel_hi:[0,1]
	v_pk_mul_f32 v[208:209], v[220:221], v[208:209] op_sel_hi:[0,1]
	v_pk_mul_f32 v[210:211], v[220:221], v[210:211] op_sel_hi:[0,1]
	v_pk_mul_f32 v[132:133], v[96:97], v[204:205]
	v_pk_mul_f32 v[134:135], v[98:99], v[206:207]
	v_pk_mul_f32 v[224:225], v[92:93], v[204:205]
	v_pk_mul_f32 v[226:227], v[94:95], v[206:207]
	v_pk_fma_f32 v[132:133], v[92:93], v[208:209], v[132:133] neg_lo:[1,0,0] neg_hi:[1,0,0]
	v_pk_fma_f32 v[134:135], v[94:95], v[210:211], v[134:135] neg_lo:[1,0,0] neg_hi:[1,0,0]
	v_pk_fma_f32 v[224:225], v[96:97], v[208:209], v[224:225]
	v_pk_fma_f32 v[226:227], v[98:99], v[210:211], v[226:227]
	v_cvt_pk_bf16_f32 v96, v132, v133
	v_cvt_pk_bf16_f32 v97, v134, v135
	v_cvt_pk_bf16_f32 v98, v224, v225
	v_cvt_pk_bf16_f32 v99, v226, v227
	global_store_dwordx4 v162, v[96:99], s[6:7]
	v_pk_mul_f32 v[168:169], v[88:89], v[204:205]
	v_pk_mul_f32 v[170:171], v[90:91], v[206:207]
	v_pk_mul_f32 v[172:173], v[84:85], v[204:205]
	v_pk_mul_f32 v[174:175], v[86:87], v[206:207]
	v_pk_fma_f32 v[168:169], v[84:85], v[208:209], v[168:169] neg_lo:[1,0,0] neg_hi:[1,0,0]
	v_pk_fma_f32 v[170:171], v[86:87], v[210:211], v[170:171] neg_lo:[1,0,0] neg_hi:[1,0,0]
	v_pk_fma_f32 v[172:173], v[88:89], v[208:209], v[172:173]
	v_pk_fma_f32 v[174:175], v[90:91], v[210:211], v[174:175]
	v_cvt_pk_bf16_f32 v88, v168, v169
	v_cvt_pk_bf16_f32 v89, v170, v171
	v_cvt_pk_bf16_f32 v90, v172, v173
	v_cvt_pk_bf16_f32 v91, v174, v175
	global_store_dwordx4 v162, v[88:91], s[8:9]
	s_waitcnt vmcnt(14)
	v_mul_f32_e32 v220, v179, v245
	v_pk_mul_f32 v[212:213], v[220:221], v[212:213] op_sel_hi:[0,1]
	v_pk_mul_f32 v[214:215], v[220:221], v[214:215] op_sel_hi:[0,1]
	v_pk_mul_f32 v[216:217], v[220:221], v[216:217] op_sel_hi:[0,1]
	v_pk_mul_f32 v[218:219], v[220:221], v[218:219] op_sel_hi:[0,1]
	v_pk_mul_f32 v[132:133], v[80:81], v[212:213]
	v_pk_mul_f32 v[134:135], v[82:83], v[214:215]
	v_pk_mul_f32 v[224:225], v[76:77], v[212:213]
	v_pk_mul_f32 v[226:227], v[78:79], v[214:215]
	v_pk_fma_f32 v[132:133], v[76:77], v[216:217], v[132:133] neg_lo:[1,0,0] neg_hi:[1,0,0]
	v_pk_fma_f32 v[134:135], v[78:79], v[218:219], v[134:135] neg_lo:[1,0,0] neg_hi:[1,0,0]
	v_pk_fma_f32 v[224:225], v[80:81], v[216:217], v[224:225]
	v_pk_fma_f32 v[226:227], v[82:83], v[218:219], v[226:227]
	v_cvt_pk_bf16_f32 v80, v132, v133
	v_cvt_pk_bf16_f32 v81, v134, v135
	v_cvt_pk_bf16_f32 v82, v224, v225
	v_cvt_pk_bf16_f32 v83, v226, v227
	global_store_dwordx4 v163, v[80:83], s[6:7]
	v_pk_mul_f32 v[168:169], v[72:73], v[212:213]
	v_pk_mul_f32 v[170:171], v[74:75], v[214:215]
	v_pk_mul_f32 v[172:173], v[68:69], v[212:213]
	v_pk_mul_f32 v[174:175], v[70:71], v[214:215]
	v_pk_fma_f32 v[168:169], v[68:69], v[216:217], v[168:169] neg_lo:[1,0,0] neg_hi:[1,0,0]
	v_pk_fma_f32 v[170:171], v[70:71], v[218:219], v[170:171] neg_lo:[1,0,0] neg_hi:[1,0,0]
	v_pk_fma_f32 v[172:173], v[72:73], v[216:217], v[172:173]
	v_pk_fma_f32 v[174:175], v[74:75], v[218:219], v[174:175]
	v_cvt_pk_bf16_f32 v72, v168, v169
	v_cvt_pk_bf16_f32 v73, v170, v171
	v_cvt_pk_bf16_f32 v74, v172, v173
	v_cvt_pk_bf16_f32 v75, v174, v175
	global_store_dwordx4 v163, v[72:75], s[8:9]
	s_waitcnt vmcnt(10)
	v_mul_f32_e32 v220, v179, v246
	v_pk_mul_f32 v[100:101], v[220:221], v[100:101] op_sel_hi:[0,1]
	v_pk_mul_f32 v[102:103], v[220:221], v[102:103] op_sel_hi:[0,1]
	v_pk_mul_f32 v[104:105], v[220:221], v[104:105] op_sel_hi:[0,1]
	v_pk_mul_f32 v[106:107], v[220:221], v[106:107] op_sel_hi:[0,1]
	v_pk_mul_f32 v[132:133], v[64:65], v[100:101]
	v_pk_mul_f32 v[134:135], v[66:67], v[102:103]
	v_pk_mul_f32 v[224:225], v[60:61], v[100:101]
	v_pk_mul_f32 v[226:227], v[62:63], v[102:103]
	v_pk_fma_f32 v[132:133], v[60:61], v[104:105], v[132:133] neg_lo:[1,0,0] neg_hi:[1,0,0]
	v_pk_fma_f32 v[134:135], v[62:63], v[106:107], v[134:135] neg_lo:[1,0,0] neg_hi:[1,0,0]
	v_pk_fma_f32 v[224:225], v[64:65], v[104:105], v[224:225]
	v_pk_fma_f32 v[226:227], v[66:67], v[106:107], v[226:227]
	v_cvt_pk_bf16_f32 v64, v132, v133
	v_cvt_pk_bf16_f32 v65, v134, v135
	v_cvt_pk_bf16_f32 v66, v224, v225
	v_cvt_pk_bf16_f32 v67, v226, v227
	global_store_dwordx4 v164, v[64:67], s[6:7]
	v_pk_mul_f32 v[168:169], v[56:57], v[100:101]
	v_pk_mul_f32 v[170:171], v[58:59], v[102:103]
	v_pk_mul_f32 v[172:173], v[52:53], v[100:101]
	v_pk_mul_f32 v[174:175], v[54:55], v[102:103]
	v_pk_fma_f32 v[168:169], v[52:53], v[104:105], v[168:169] neg_lo:[1,0,0] neg_hi:[1,0,0]
	v_pk_fma_f32 v[170:171], v[54:55], v[106:107], v[170:171] neg_lo:[1,0,0] neg_hi:[1,0,0]
	v_pk_fma_f32 v[172:173], v[56:57], v[104:105], v[172:173]
	v_pk_fma_f32 v[174:175], v[58:59], v[106:107], v[174:175]
	v_cvt_pk_bf16_f32 v56, v168, v169
	v_cvt_pk_bf16_f32 v57, v170, v171
	v_cvt_pk_bf16_f32 v58, v172, v173
	v_cvt_pk_bf16_f32 v59, v174, v175
	global_store_dwordx4 v164, v[56:59], s[8:9]
	s_waitcnt vmcnt(10)
	v_mul_f32_e32 v220, v179, v248
	v_pk_mul_f32 v[108:109], v[220:221], v[108:109] op_sel_hi:[0,1]
	v_pk_mul_f32 v[110:111], v[220:221], v[110:111] op_sel_hi:[0,1]
	v_pk_mul_f32 v[112:113], v[220:221], v[112:113] op_sel_hi:[0,1]
	v_pk_mul_f32 v[114:115], v[220:221], v[114:115] op_sel_hi:[0,1]
	v_pk_mul_f32 v[132:133], v[48:49], v[108:109]
	v_pk_mul_f32 v[134:135], v[50:51], v[110:111]
	v_pk_mul_f32 v[224:225], v[44:45], v[108:109]
	v_pk_mul_f32 v[226:227], v[46:47], v[110:111]
	v_pk_fma_f32 v[132:133], v[44:45], v[112:113], v[132:133] neg_lo:[1,0,0] neg_hi:[1,0,0]
	v_pk_fma_f32 v[134:135], v[46:47], v[114:115], v[134:135] neg_lo:[1,0,0] neg_hi:[1,0,0]
	v_pk_fma_f32 v[224:225], v[48:49], v[112:113], v[224:225]
	v_pk_fma_f32 v[226:227], v[50:51], v[114:115], v[226:227]
	v_cvt_pk_bf16_f32 v48, v132, v133
	v_cvt_pk_bf16_f32 v49, v134, v135
	v_cvt_pk_bf16_f32 v50, v224, v225
	v_cvt_pk_bf16_f32 v51, v226, v227
	global_store_dwordx4 v165, v[48:51], s[6:7]
	v_pk_mul_f32 v[168:169], v[40:41], v[108:109]
	v_pk_mul_f32 v[170:171], v[42:43], v[110:111]
	v_pk_mul_f32 v[172:173], v[36:37], v[108:109]
	v_pk_mul_f32 v[174:175], v[38:39], v[110:111]
	v_pk_fma_f32 v[168:169], v[36:37], v[112:113], v[168:169] neg_lo:[1,0,0] neg_hi:[1,0,0]
	v_pk_fma_f32 v[170:171], v[38:39], v[114:115], v[170:171] neg_lo:[1,0,0] neg_hi:[1,0,0]
	v_pk_fma_f32 v[172:173], v[40:41], v[112:113], v[172:173]
	v_pk_fma_f32 v[174:175], v[42:43], v[114:115], v[174:175]
	v_cvt_pk_bf16_f32 v40, v168, v169
	v_cvt_pk_bf16_f32 v41, v170, v171
	v_cvt_pk_bf16_f32 v42, v172, v173
	v_cvt_pk_bf16_f32 v43, v174, v175
	global_store_dwordx4 v165, v[40:43], s[8:9]
	s_waitcnt vmcnt(10)
	v_mul_f32_e32 v220, v179, v249
	v_pk_mul_f32 v[116:117], v[220:221], v[116:117] op_sel_hi:[0,1]
	v_pk_mul_f32 v[118:119], v[220:221], v[118:119] op_sel_hi:[0,1]
	v_pk_mul_f32 v[120:121], v[220:221], v[120:121] op_sel_hi:[0,1]
	v_pk_mul_f32 v[122:123], v[220:221], v[122:123] op_sel_hi:[0,1]
	v_pk_mul_f32 v[132:133], v[32:33], v[116:117]
	v_pk_mul_f32 v[134:135], v[34:35], v[118:119]
	v_pk_mul_f32 v[224:225], v[28:29], v[116:117]
	v_pk_mul_f32 v[226:227], v[30:31], v[118:119]
	v_pk_fma_f32 v[132:133], v[28:29], v[120:121], v[132:133] neg_lo:[1,0,0] neg_hi:[1,0,0]
	v_pk_fma_f32 v[134:135], v[30:31], v[122:123], v[134:135] neg_lo:[1,0,0] neg_hi:[1,0,0]
	v_pk_fma_f32 v[224:225], v[32:33], v[120:121], v[224:225]
	v_pk_fma_f32 v[226:227], v[34:35], v[122:123], v[226:227]
	v_cvt_pk_bf16_f32 v32, v132, v133
	v_cvt_pk_bf16_f32 v33, v134, v135
	v_cvt_pk_bf16_f32 v34, v224, v225
	v_cvt_pk_bf16_f32 v35, v226, v227
	global_store_dwordx4 v166, v[32:35], s[6:7]
	v_pk_mul_f32 v[168:169], v[24:25], v[116:117]
	v_pk_mul_f32 v[170:171], v[26:27], v[118:119]
	v_pk_mul_f32 v[172:173], v[20:21], v[116:117]
	v_pk_mul_f32 v[174:175], v[22:23], v[118:119]
	v_pk_fma_f32 v[168:169], v[20:21], v[120:121], v[168:169] neg_lo:[1,0,0] neg_hi:[1,0,0]
	v_pk_fma_f32 v[170:171], v[22:23], v[122:123], v[170:171] neg_lo:[1,0,0] neg_hi:[1,0,0]
	v_pk_fma_f32 v[172:173], v[24:25], v[120:121], v[172:173]
	v_pk_fma_f32 v[174:175], v[26:27], v[122:123], v[174:175]
	v_cvt_pk_bf16_f32 v24, v168, v169
	v_cvt_pk_bf16_f32 v25, v170, v171
	v_cvt_pk_bf16_f32 v26, v172, v173
	v_cvt_pk_bf16_f32 v27, v174, v175
	global_store_dwordx4 v166, v[24:27], s[8:9]
	s_waitcnt vmcnt(10)
	v_mul_f32_e32 v220, v179, v250
	v_pk_mul_f32 v[124:125], v[220:221], v[124:125] op_sel_hi:[0,1]
	v_pk_mul_f32 v[126:127], v[220:221], v[126:127] op_sel_hi:[0,1]
	v_pk_mul_f32 v[128:129], v[220:221], v[128:129] op_sel_hi:[0,1]
	v_pk_mul_f32 v[130:131], v[220:221], v[130:131] op_sel_hi:[0,1]
	v_pk_mul_f32 v[132:133], v[16:17], v[124:125]
	v_pk_mul_f32 v[134:135], v[18:19], v[126:127]
	v_pk_mul_f32 v[224:225], v[12:13], v[124:125]
	v_pk_mul_f32 v[226:227], v[14:15], v[126:127]
	v_pk_fma_f32 v[132:133], v[12:13], v[128:129], v[132:133] neg_lo:[1,0,0] neg_hi:[1,0,0]
	v_pk_fma_f32 v[134:135], v[14:15], v[130:131], v[134:135] neg_lo:[1,0,0] neg_hi:[1,0,0]
	v_pk_fma_f32 v[224:225], v[16:17], v[128:129], v[224:225]
	v_pk_fma_f32 v[226:227], v[18:19], v[130:131], v[226:227]
	v_cvt_pk_bf16_f32 v16, v132, v133
	v_cvt_pk_bf16_f32 v17, v134, v135
	v_cvt_pk_bf16_f32 v18, v224, v225
	v_cvt_pk_bf16_f32 v19, v226, v227
	global_store_dwordx4 v167, v[16:19], s[6:7]
	v_pk_mul_f32 v[168:169], v[8:9], v[124:125]
	v_pk_mul_f32 v[170:171], v[10:11], v[126:127]
	v_pk_mul_f32 v[172:173], v[4:5], v[124:125]
	v_pk_mul_f32 v[174:175], v[6:7], v[126:127]
	v_pk_fma_f32 v[168:169], v[4:5], v[128:129], v[168:169] neg_lo:[1,0,0] neg_hi:[1,0,0]
	v_pk_fma_f32 v[170:171], v[6:7], v[130:131], v[170:171] neg_lo:[1,0,0] neg_hi:[1,0,0]
	v_pk_fma_f32 v[172:173], v[8:9], v[128:129], v[172:173]
	v_pk_fma_f32 v[174:175], v[10:11], v[130:131], v[174:175]
	v_cvt_pk_bf16_f32 v8, v168, v169
	v_cvt_pk_bf16_f32 v9, v170, v171
	v_cvt_pk_bf16_f32 v10, v172, v173
	v_cvt_pk_bf16_f32 v11, v174, v175
	global_store_dwordx4 v167, v[8:11], s[8:9]
	s_branch .Lb1q_done
.Lb1q_vonly:
	s_lshl_b32 s23, s48, 2
	s_and_b32 s23, s23, 12
	s_or_b32 s23, s23, s46
	s_lshl_b32 s28, s9, 1
	s_sub_i32 s29, 14, s28
	s_cmp_eq_u32 s21, 2
	s_cselect_b32 s7, 1, 0
	s_or_b32 s7, s28, s7
	s_cmp_eq_u32 s21, 0
	s_cselect_b32 s6, s9, s7
	s_cselect_b32 s8, 0, 0x6000000
	s_cselect_b32 s7, 0x3e38aa3b, 1.0
	v_mov_b32_e32 v179, s7
	s_add_u32 s8, s41, s8
	s_addc_u32 s9, s43, 0
	s_mov_b32 s7, 0
	s_lshl_b64 s[6:7], s[6:7], 25
	s_add_u32 s6, s8, s6
	s_addc_u32 s7, s9, s7
	s_lshl_b32 s8, s23, 21
	s_add_u32 s6, s6, s8
	s_addc_u32 s7, s7, 0
	s_add_u32 s8, s6, 0x400000
	s_addc_u32 s9, s7, 0
	v_lshlrev_b32_e32 v151, s29, v152
	v_and_b32_e32 v151, 0x3fff, v151
	v_lshrrev_b32_e32 v159, s28, v152
	v_add_u32_e32 v151, v151, v159
	v_lshl_add_u32 v160, v151, 7, v150
	s_lshr_b32 s21, 0x800, s28
	s_lshr_b32 s23, 0x4000, s28
	v_add_u32_e32 v161, s21, v160
	v_add_u32_e32 v162, s21, v161
	v_add_u32_e32 v163, s21, v162
	v_add_u32_e32 v164, s23, v160
	v_add_u32_e32 v165, s21, v164
	v_add_u32_e32 v166, s21, v165
	v_add_u32_e32 v167, s21, v166
	s_waitcnt vmcnt(0)
	v_mul_f32_e32 v220, v179, v228
	v_pk_mul_f32 v[128:129], v[128:129], v[220:221] op_sel_hi:[1,0]
	v_pk_mul_f32 v[130:131], v[130:131], v[220:221] op_sel_hi:[1,0]
	v_pk_mul_f32 v[124:125], v[124:125], v[220:221] op_sel_hi:[1,0]
	v_pk_mul_f32 v[126:127], v[126:127], v[220:221] op_sel_hi:[1,0]
	v_cvt_pk_bf16_f32 v128, v128, v129
	v_cvt_pk_bf16_f32 v129, v130, v131
	v_cvt_pk_bf16_f32 v130, v124, v125
	v_cvt_pk_bf16_f32 v131, v126, v127
	global_store_dwordx4 v160, v[128:131], s[6:7]
	v_pk_mul_f32 v[120:121], v[120:121], v[220:221] op_sel_hi:[1,0]
	v_pk_mul_f32 v[122:123], v[122:123], v[220:221] op_sel_hi:[1,0]
	v_pk_mul_f32 v[116:117], v[116:117], v[220:221] op_sel_hi:[1,0]
	v_pk_mul_f32 v[118:119], v[118:119], v[220:221] op_sel_hi:[1,0]
	v_cvt_pk_bf16_f32 v120, v120, v121
	v_cvt_pk_bf16_f32 v121, v122, v123
	v_cvt_pk_bf16_f32 v122, v116, v117
	v_cvt_pk_bf16_f32 v123, v118, v119
	global_store_dwordx4 v160, v[120:123], s[8:9]
	v_mul_f32_e32 v220, v179, v229
	v_pk_mul_f32 v[112:113], v[112:113], v[220:221] op_sel_hi:[1,0]
	v_pk_mul_f32 v[114:115], v[114:115], v[220:221] op_sel_hi:[1,0]
	v_pk_mul_f32 v[108:109], v[108:109], v[220:221] op_sel_hi:[1,0]
	v_pk_mul_f32 v[110:111], v[110:111], v[220:221] op_sel_hi:[1,0]
	v_cvt_pk_bf16_f32 v112, v112, v113
	v_cvt_pk_bf16_f32 v113, v114, v115
	v_cvt_pk_bf16_f32 v114, v108, v109
	v_cvt_pk_bf16_f32 v115, v110, v111
	global_store_dwordx4 v161, v[112:115], s[6:7]
	v_pk_mul_f32 v[104:105], v[104:105], v[220:221] op_sel_hi:[1,0]
	v_pk_mul_f32 v[106:107], v[106:107], v[220:221] op_sel_hi:[1,0]
	v_pk_mul_f32 v[100:101], v[100:101], v[220:221] op_sel_hi:[1,0]
	v_pk_mul_f32 v[102:103], v[102:103], v[220:221] op_sel_hi:[1,0]
	v_cvt_pk_bf16_f32 v104, v104, v105
	v_cvt_pk_bf16_f32 v105, v106, v107
	v_cvt_pk_bf16_f32 v106, v100, v101
	v_cvt_pk_bf16_f32 v107, v102, v103
	global_store_dwordx4 v161, v[104:107], s[8:9]
	v_mul_f32_e32 v220, v179, v244
	v_pk_mul_f32 v[96:97], v[96:97], v[220:221] op_sel_hi:[1,0]
	v_pk_mul_f32 v[98:99], v[98:99], v[220:221] op_sel_hi:[1,0]
	v_pk_mul_f32 v[92:93], v[92:93], v[220:221] op_sel_hi:[1,0]
	v_pk_mul_f32 v[94:95], v[94:95], v[220:221] op_sel_hi:[1,0]
	v_cvt_pk_bf16_f32 v96, v96, v97
	v_cvt_pk_bf16_f32 v97, v98, v99
	v_cvt_pk_bf16_f32 v98, v92, v93
	v_cvt_pk_bf16_f32 v99, v94, v95
	global_store_dwordx4 v162, v[96:99], s[6:7]
	v_pk_mul_f32 v[88:89], v[88:89], v[220:221] op_sel_hi:[1,0]
	v_pk_mul_f32 v[90:91], v[90:91], v[220:221] op_sel_hi:[1,0]
	v_pk_mul_f32 v[84:85], v[84:85], v[220:221] op_sel_hi:[1,0]
	v_pk_mul_f32 v[86:87], v[86:87], v[220:221] op_sel_hi:[1,0]
	v_cvt_pk_bf16_f32 v88, v88, v89
	v_cvt_pk_bf16_f32 v89, v90, v91
	v_cvt_pk_bf16_f32 v90, v84, v85
	v_cvt_pk_bf16_f32 v91, v86, v87
	global_store_dwordx4 v162, v[88:91], s[8:9]
	v_mul_f32_e32 v220, v179, v245
	v_pk_mul_f32 v[80:81], v[80:81], v[220:221] op_sel_hi:[1,0]
	v_pk_mul_f32 v[82:83], v[82:83], v[220:221] op_sel_hi:[1,0]
	v_pk_mul_f32 v[76:77], v[76:77], v[220:221] op_sel_hi:[1,0]
	v_pk_mul_f32 v[78:79], v[78:79], v[220:221] op_sel_hi:[1,0]
	v_cvt_pk_bf16_f32 v80, v80, v81
	v_cvt_pk_bf16_f32 v81, v82, v83
	v_cvt_pk_bf16_f32 v82, v76, v77
	v_cvt_pk_bf16_f32 v83, v78, v79
	global_store_dwordx4 v163, v[80:83], s[6:7]
	v_pk_mul_f32 v[72:73], v[72:73], v[220:221] op_sel_hi:[1,0]
	v_pk_mul_f32 v[74:75], v[74:75], v[220:221] op_sel_hi:[1,0]
	v_pk_mul_f32 v[68:69], v[68:69], v[220:221] op_sel_hi:[1,0]
	v_pk_mul_f32 v[70:71], v[70:71], v[220:221] op_sel_hi:[1,0]
	v_cvt_pk_bf16_f32 v72, v72, v73
	v_cvt_pk_bf16_f32 v73, v74, v75
	v_cvt_pk_bf16_f32 v74, v68, v69
	v_cvt_pk_bf16_f32 v75, v70, v71
	global_store_dwordx4 v163, v[72:75], s[8:9]
	v_mul_f32_e32 v220, v179, v246
	v_pk_mul_f32 v[64:65], v[64:65], v[220:221] op_sel_hi:[1,0]
	v_pk_mul_f32 v[66:67], v[66:67], v[220:221] op_sel_hi:[1,0]
	v_pk_mul_f32 v[60:61], v[60:61], v[220:221] op_sel_hi:[1,0]
	v_pk_mul_f32 v[62:63], v[62:63], v[220:221] op_sel_hi:[1,0]
	v_cvt_pk_bf16_f32 v64, v64, v65
	v_cvt_pk_bf16_f32 v65, v66, v67
	v_cvt_pk_bf16_f32 v66, v60, v61
	v_cvt_pk_bf16_f32 v67, v62, v63
	global_store_dwordx4 v164, v[64:67], s[6:7]
	v_pk_mul_f32 v[56:57], v[56:57], v[220:221] op_sel_hi:[1,0]
	v_pk_mul_f32 v[58:59], v[58:59], v[220:221] op_sel_hi:[1,0]
	v_pk_mul_f32 v[52:53], v[52:53], v[220:221] op_sel_hi:[1,0]
	v_pk_mul_f32 v[54:55], v[54:55], v[220:221] op_sel_hi:[1,0]
	v_cvt_pk_bf16_f32 v56, v56, v57
	v_cvt_pk_bf16_f32 v57, v58, v59
	v_cvt_pk_bf16_f32 v58, v52, v53
	v_cvt_pk_bf16_f32 v59, v54, v55
	global_store_dwordx4 v164, v[56:59], s[8:9]
	v_mul_f32_e32 v220, v179, v248
	v_pk_mul_f32 v[48:49], v[48:49], v[220:221] op_sel_hi:[1,0]
	v_pk_mul_f32 v[50:51], v[50:51], v[220:221] op_sel_hi:[1,0]
	v_pk_mul_f32 v[44:45], v[44:45], v[220:221] op_sel_hi:[1,0]
	v_pk_mul_f32 v[46:47], v[46:47], v[220:221] op_sel_hi:[1,0]
	v_cvt_pk_bf16_f32 v48, v48, v49
	v_cvt_pk_bf16_f32 v49, v50, v51
	v_cvt_pk_bf16_f32 v50, v44, v45
	v_cvt_pk_bf16_f32 v51, v46, v47
	global_store_dwordx4 v165, v[48:51], s[6:7]
	v_pk_mul_f32 v[40:41], v[40:41], v[220:221] op_sel_hi:[1,0]
	v_pk_mul_f32 v[42:43], v[42:43], v[220:221] op_sel_hi:[1,0]
	v_pk_mul_f32 v[36:37], v[36:37], v[220:221] op_sel_hi:[1,0]
	v_pk_mul_f32 v[38:39], v[38:39], v[220:221] op_sel_hi:[1,0]
	v_cvt_pk_bf16_f32 v40, v40, v41
	v_cvt_pk_bf16_f32 v41, v42, v43
	v_cvt_pk_bf16_f32 v42, v36, v37
	v_cvt_pk_bf16_f32 v43, v38, v39
	global_store_dwordx4 v165, v[40:43], s[8:9]
	v_mul_f32_e32 v220, v179, v249
	v_pk_mul_f32 v[32:33], v[32:33], v[220:221] op_sel_hi:[1,0]
	v_pk_mul_f32 v[34:35], v[34:35], v[220:221] op_sel_hi:[1,0]
	v_pk_mul_f32 v[28:29], v[28:29], v[220:221] op_sel_hi:[1,0]
	v_pk_mul_f32 v[30:31], v[30:31], v[220:221] op_sel_hi:[1,0]
	v_cvt_pk_bf16_f32 v32, v32, v33
	v_cvt_pk_bf16_f32 v33, v34, v35
	v_cvt_pk_bf16_f32 v34, v28, v29
	v_cvt_pk_bf16_f32 v35, v30, v31
	global_store_dwordx4 v166, v[32:35], s[6:7]
	v_pk_mul_f32 v[24:25], v[24:25], v[220:221] op_sel_hi:[1,0]
	v_pk_mul_f32 v[26:27], v[26:27], v[220:221] op_sel_hi:[1,0]
	v_pk_mul_f32 v[20:21], v[20:21], v[220:221] op_sel_hi:[1,0]
	v_pk_mul_f32 v[22:23], v[22:23], v[220:221] op_sel_hi:[1,0]
	v_cvt_pk_bf16_f32 v24, v24, v25
	v_cvt_pk_bf16_f32 v25, v26, v27
	v_cvt_pk_bf16_f32 v26, v20, v21
	v_cvt_pk_bf16_f32 v27, v22, v23
	global_store_dwordx4 v166, v[24:27], s[8:9]
	v_mul_f32_e32 v220, v179, v250
	v_pk_mul_f32 v[16:17], v[16:17], v[220:221] op_sel_hi:[1,0]
	v_pk_mul_f32 v[18:19], v[18:19], v[220:221] op_sel_hi:[1,0]
	v_pk_mul_f32 v[12:13], v[12:13], v[220:221] op_sel_hi:[1,0]
	v_pk_mul_f32 v[14:15], v[14:15], v[220:221] op_sel_hi:[1,0]
	v_cvt_pk_bf16_f32 v16, v16, v17
	v_cvt_pk_bf16_f32 v17, v18, v19
	v_cvt_pk_bf16_f32 v18, v12, v13
	v_cvt_pk_bf16_f32 v19, v14, v15
	global_store_dwordx4 v167, v[16:19], s[6:7]
	v_pk_mul_f32 v[8:9], v[8:9], v[220:221] op_sel_hi:[1,0]
	v_pk_mul_f32 v[10:11], v[10:11], v[220:221] op_sel_hi:[1,0]
	v_pk_mul_f32 v[4:5], v[4:5], v[220:221] op_sel_hi:[1,0]
	v_pk_mul_f32 v[6:7], v[6:7], v[220:221] op_sel_hi:[1,0]
	v_cvt_pk_bf16_f32 v8, v8, v9
	v_cvt_pk_bf16_f32 v9, v10, v11
	v_cvt_pk_bf16_f32 v10, v4, v5
	v_cvt_pk_bf16_f32 v11, v6, v7
	global_store_dwordx4 v167, v[8:11], s[8:9]

.La1_ph3:
	s_add_i32 s52, 16, 0x18000
	v_add_u32_e32 v3, s52, v175
	s_add_i32 s53, 16, 0x1c000
	ds_read_b128 v[142:145], v3
	ds_read_b128 v[146:149], v3 offset:1024
	ds_read_b128 v[150:153], v3 offset:2048
	ds_read_b128 v[154:157], v3 offset:3072
	v_add_u32_e32 v3, s53, v175
	ds_read_b128 v[158:161], v3
	ds_read_b128 v[162:165], v3 offset:1024
	ds_read_b128 v[166:169], v3 offset:2048
	ds_read_b128 v[170:173], v3 offset:3072
	s_mov_b32 m0, s39
	s_nop 0
	global_load_lds_dwordx4 v[214:215], off
	s_mov_b32 m0, s40
	s_nop 0
	global_load_lds_dwordx4 v[216:217], off
	s_add_u32 s30, s30, 0x40000
	s_addc_u32 s31, s31, 0
	s_mov_b32 m0, s41
	v_lshl_add_u64 v[218:219], s[30:31], 0, v[136:137]
	ds_read_b128 v[178:181], v177 offset:32768
	ds_read_b128 v[182:185], v177 offset:33792
	ds_read_b128 v[186:189], v177 offset:34816
	ds_read_b128 v[190:193], v177 offset:35840
	ds_read_b128 v[194:197], v177 offset:36864
	ds_read_b128 v[198:201], v177 offset:37888
	ds_read_b128 v[202:205], v177 offset:38912
	ds_read_b128 v[206:209], v177 offset:39936
	global_load_lds_dwordx4 v[218:219], off
	v_lshl_add_u64 v[218:219], s[30:31], 0, v[132:133]
	s_mov_b32 m0, s42
	s_nop 0
	global_load_lds_dwordx4 v[218:219], off
	s_waitcnt vmcnt(8)
	s_cmp_eq_u32 s51, 12
	s_cbranch_scc0 .La1pf_skip
	v_lshl_add_u32 v235, s2, 8, v174
	v_lshlrev_b32_e32 v235, 2, v235
	global_load_dword v236, v235, s[16:17]
	global_load_dword v238, v235, s[16:17] offset:64
	global_load_dword v240, v235, s[16:17] offset:128
	global_load_dword v242, v235, s[16:17] offset:192
	global_load_dword v244, v235, s[16:17] offset:512
	global_load_dword v246, v235, s[16:17] offset:576
	global_load_dword v248, v235, s[16:17] offset:640
	global_load_dword v250, v235, s[16:17] offset:704
.La1pf_skip:
	s_waitcnt lgkmcnt(0)
	s_barrier
	s_setprio 1
	s_waitcnt lgkmcnt(0)
	v_mfma_f32_16x16x32_bf16 v[128:131], v[142:145], v[178:181], v[128:131]
	v_mfma_f32_16x16x32_bf16 v[120:123], v[150:153], v[178:181], v[120:123]
	v_mfma_f32_16x16x32_bf16 v[112:115], v[142:145], v[186:189], v[112:115]
	v_mfma_f32_16x16x32_bf16 v[104:107], v[150:153], v[186:189], v[104:107]
	v_mfma_f32_16x16x32_bf16 v[96:99], v[142:145], v[194:197], v[96:99]
	v_mfma_f32_16x16x32_bf16 v[88:91], v[150:153], v[194:197], v[88:91]
	v_mfma_f32_16x16x32_bf16 v[80:83], v[142:145], v[202:205], v[80:83]
	v_mfma_f32_16x16x32_bf16 v[72:75], v[150:153], v[202:205], v[72:75]
	v_mfma_f32_16x16x32_bf16 v[128:131], v[146:149], v[182:185], v[128:131]
	v_mfma_f32_16x16x32_bf16 v[120:123], v[154:157], v[182:185], v[120:123]
	v_mfma_f32_16x16x32_bf16 v[112:115], v[146:149], v[190:193], v[112:115]
	v_mfma_f32_16x16x32_bf16 v[104:107], v[154:157], v[190:193], v[104:107]
	v_mfma_f32_16x16x32_bf16 v[96:99], v[146:149], v[198:201], v[96:99]
	v_mfma_f32_16x16x32_bf16 v[88:91], v[154:157], v[198:201], v[88:91]
	v_mfma_f32_16x16x32_bf16 v[80:83], v[146:149], v[206:209], v[80:83]
	v_mfma_f32_16x16x32_bf16 v[72:75], v[154:157], v[206:209], v[72:75]
	s_setprio 0
	s_setprio 1
	v_mfma_f32_16x16x32_bf16 v[124:127], v[158:161], v[178:181], v[124:127]
	v_mfma_f32_16x16x32_bf16 v[116:119], v[166:169], v[178:181], v[116:119]
	v_mfma_f32_16x16x32_bf16 v[108:111], v[158:161], v[186:189], v[108:111]
	v_mfma_f32_16x16x32_bf16 v[100:103], v[166:169], v[186:189], v[100:103]
	v_mfma_f32_16x16x32_bf16 v[92:95], v[158:161], v[194:197], v[92:95]
	v_mfma_f32_16x16x32_bf16 v[84:87], v[166:169], v[194:197], v[84:87]
	v_mfma_f32_16x16x32_bf16 v[76:79], v[158:161], v[202:205], v[76:79]
	v_mfma_f32_16x16x32_bf16 v[68:71], v[166:169], v[202:205], v[68:71]
	v_mfma_f32_16x16x32_bf16 v[124:127], v[162:165], v[182:185], v[124:127]
	v_mfma_f32_16x16x32_bf16 v[116:119], v[170:173], v[182:185], v[116:119]
	v_mfma_f32_16x16x32_bf16 v[108:111], v[162:165], v[190:193], v[108:111]
	v_mfma_f32_16x16x32_bf16 v[100:103], v[170:173], v[190:193], v[100:103]
	v_mfma_f32_16x16x32_bf16 v[92:95], v[162:165], v[198:201], v[92:95]
	v_mfma_f32_16x16x32_bf16 v[84:87], v[170:173], v[198:201], v[84:87]
	v_mfma_f32_16x16x32_bf16 v[76:79], v[162:165], v[206:209], v[76:79]
	v_mfma_f32_16x16x32_bf16 v[68:71], v[170:173], v[206:209], v[68:71]
	s_setprio 0
	s_barrier
	s_add_i32 s30, s52, s38
	v_lshl_add_u64 v[210:211], v[210:211], 0, s[84:85]
	s_mov_b32 m0, s30
	ds_read_b128 v[178:181], v177 offset:49152
	ds_read_b128 v[182:185], v177 offset:50176
	ds_read_b128 v[186:189], v177 offset:51200
	ds_read_b128 v[190:193], v177 offset:52224
	ds_read_b128 v[194:197], v177 offset:53248
	ds_read_b128 v[198:201], v177 offset:54272
	ds_read_b128 v[202:205], v177 offset:55296
	ds_read_b128 v[206:209], v177 offset:56320
	global_load_lds_dwordx4 v[210:211], off
	s_add_i32 m0, s30, 0x2000
	s_add_u32 s28, s28, 0x40080
	v_lshl_add_u64 v[210:211], v[212:213], 0, s[84:85]
	s_addc_u32 s29, s29, 0
	s_add_i32 s30, s53, s38
	global_load_lds_dwordx4 v[210:211], off
	v_lshl_add_u64 v[210:211], s[28:29], 0, v[134:135]
	s_mov_b32 m0, s30
	s_nop 0
	global_load_lds_dwordx4 v[210:211], off
	v_lshl_add_u64 v[210:211], s[28:29], 0, v[0:1]
	s_add_i32 m0, s30, 0x2000
	s_nop 0
	global_load_lds_dwordx4 v[210:211], off
	v_lshl_add_u64 v[210:211], v[214:215], 0, s[84:85]
	s_mov_b32 m0, s44
	s_nop 0
	global_load_lds_dwordx4 v[210:211], off
	v_lshl_add_u64 v[210:211], v[216:217], 0, s[84:85]
	s_mov_b32 m0, s45
	s_nop 0
	global_load_lds_dwordx4 v[210:211], off
	s_cmp_eq_u32 s51, 12
	s_cbranch_scc1 .La1w4_last
	s_waitcnt vmcnt(8)
	s_branch .La1w4_j
.La1w4_last:
	s_waitcnt vmcnt(16)
.La1w4_j:
	s_waitcnt lgkmcnt(0)
	s_barrier
	s_setprio 1
	s_waitcnt lgkmcnt(0)
	v_mfma_f32_16x16x32_bf16 v[64:67], v[142:145], v[178:181], v[64:67]
	v_mfma_f32_16x16x32_bf16 v[56:59], v[150:153], v[178:181], v[56:59]
	v_mfma_f32_16x16x32_bf16 v[48:51], v[142:145], v[186:189], v[48:51]
	v_mfma_f32_16x16x32_bf16 v[40:43], v[150:153], v[186:189], v[40:43]
	v_mfma_f32_16x16x32_bf16 v[32:35], v[142:145], v[194:197], v[32:35]
	v_mfma_f32_16x16x32_bf16 v[24:27], v[150:153], v[194:197], v[24:27]
	v_mfma_f32_16x16x32_bf16 v[16:19], v[142:145], v[202:205], v[16:19]
	v_mfma_f32_16x16x32_bf16 v[8:11], v[150:153], v[202:205], v[8:11]
	v_mfma_f32_16x16x32_bf16 v[64:67], v[146:149], v[182:185], v[64:67]
	v_mfma_f32_16x16x32_bf16 v[56:59], v[154:157], v[182:185], v[56:59]
	v_mfma_f32_16x16x32_bf16 v[48:51], v[146:149], v[190:193], v[48:51]
	v_mfma_f32_16x16x32_bf16 v[40:43], v[154:157], v[190:193], v[40:43]
	v_mfma_f32_16x16x32_bf16 v[32:35], v[146:149], v[198:201], v[32:35]
	v_mfma_f32_16x16x32_bf16 v[24:27], v[154:157], v[198:201], v[24:27]
	v_mfma_f32_16x16x32_bf16 v[16:19], v[146:149], v[206:209], v[16:19]
	v_mfma_f32_16x16x32_bf16 v[8:11], v[154:157], v[206:209], v[8:11]
	s_setprio 0
	s_setprio 1
	v_mfma_f32_16x16x32_bf16 v[60:63], v[158:161], v[178:181], v[60:63]
	v_mfma_f32_16x16x32_bf16 v[52:55], v[166:169], v[178:181], v[52:55]
	v_mfma_f32_16x16x32_bf16 v[44:47], v[158:161], v[186:189], v[44:47]
	v_mfma_f32_16x16x32_bf16 v[36:39], v[166:169], v[186:189], v[36:39]
	v_mfma_f32_16x16x32_bf16 v[28:31], v[158:161], v[194:197], v[28:31]
	v_mfma_f32_16x16x32_bf16 v[20:23], v[166:169], v[194:197], v[20:23]
	v_mfma_f32_16x16x32_bf16 v[12:15], v[158:161], v[202:205], v[12:15]
	v_mfma_f32_16x16x32_bf16 v[4:7], v[166:169], v[202:205], v[4:7]
	v_mfma_f32_16x16x32_bf16 v[60:63], v[162:165], v[182:185], v[60:63]
	v_mfma_f32_16x16x32_bf16 v[52:55], v[170:173], v[182:185], v[52:55]
	v_mfma_f32_16x16x32_bf16 v[44:47], v[162:165], v[190:193], v[44:47]
	v_mfma_f32_16x16x32_bf16 v[36:39], v[170:173], v[190:193], v[36:39]
	v_mfma_f32_16x16x32_bf16 v[28:31], v[162:165], v[198:201], v[28:31]
	v_mfma_f32_16x16x32_bf16 v[20:23], v[170:173], v[198:201], v[20:23]
	v_mfma_f32_16x16x32_bf16 v[12:15], v[162:165], v[206:209], v[12:15]
	v_mfma_f32_16x16x32_bf16 v[4:7], v[170:173], v[206:209], v[4:7]
	s_setprio 0
	s_barrier
	s_add_i32 s51, s51, 2
	s_add_u32 s0, s0, 0x100
	s_addc_u32 s1, s1, 0
	s_add_u32 s49, s49, 0x100
	s_addc_u32 s50, s50, 0
	s_cmp_gt_u32 s51, 13
	s_cbranch_scc0 .LBB0_446
	s_and_b64 vcc, exec, s[18:19]
	s_cbranch_vccz .LBB0_449
	s_barrier

.LBB0_452:
	v_and_b32_e32 v145, 64, v223
	v_xor_b32_e32 v144, 16, v223
	v_add_u32_e32 v145, 64, v145
	v_cmp_lt_i32_e32 vcc, v144, v145
	s_add_i32 s0, s47, -16
	v_lshl_or_b32 v3, s0, 8, v176
	v_cndmask_b32_e32 v144, v223, v144, vcc
	v_lshlrev_b32_e32 v179, 2, v144
	v_xor_b32_e32 v144, 32, v223
	v_cmp_lt_i32_e32 vcc, v144, v145
	s_lshl_b32 s0, s0, 2
	s_or_b32 s94, s0, s43
	v_cndmask_b32_e32 v144, v223, v144, vcc
	v_lshlrev_b32_e32 v178, 2, v144
	v_lshl_add_u64 v[144:145], v[142:143], 2, s[16:17]
	s_mov_b32 s0, 0xbb7be14b
	s_mov_b32 s2, 0xbc40d0ac
	s_mov_b32 s28, 0x3cb76c34
	s_mov_b32 s30, 0xbd17b858
	s_mov_b32 s48, 0x3d6537d1
	s_mov_b32 s50, 0xbdacab04
	s_mov_b32 s52, 0x3e342bfa
	v_lshlrev_b64 v[146:147], 12, v[142:143]
	v_lshl_add_u64 v[148:149], s[12:13], 0, v[146:147]
	v_lshlrev_b32_e32 v146, 1, v3
	v_mov_b32_e32 v147, v2
	v_lshl_add_u64 v[148:149], v[148:149], 0, v[146:147]
	s_waitcnt vmcnt(0)
	v_mov_b32_e32 v150, v236
	v_pk_mul_f32 v[156:157], v[128:129], v[150:151] op_sel_hi:[1,0]
	s_nop 0
	v_med3_f32 v158, v156, -4.0, 4.0
	v_med3_f32 v159, v157, -4.0, 4.0
	v_pk_mul_f32 v[152:153], v[158:159], v[158:159]
	v_pk_mul_f32 v[154:155], v[130:131], v[150:151] op_sel_hi:[1,0]
	v_pk_fma_f32 v[160:161], v[152:153], s[72:73], -1.0 op_sel_hi:[1,0,0]
	v_mov_b64_e32 v[152:153], s[0:1]
	v_pk_fma_f32 v[162:163], v[160:161], s[74:75], v[152:153] op_sel_hi:[1,0,0]
	s_mov_b32 s0, 0x3bcff2a2
	v_pk_fma_f32 v[162:163], v[160:161], v[162:163], s[0:1] op_sel_hi:[1,1,0]
	s_nop 0
	v_pk_fma_f32 v[162:163], v[160:161], v[162:163], s[2:3] op_sel_hi:[1,1,0]
	s_nop 0
	v_pk_fma_f32 v[162:163], v[160:161], v[162:163], s[28:29] op_sel_hi:[1,1,0]
	s_nop 0
	v_pk_fma_f32 v[162:163], v[160:161], v[162:163], s[30:31] op_sel_hi:[1,1,0]
	s_nop 0
	v_pk_fma_f32 v[162:163], v[160:161], v[162:163], s[48:49] op_sel_hi:[1,1,0]
	s_nop 0
	v_pk_fma_f32 v[162:163], v[160:161], v[162:163], s[50:51] op_sel_hi:[1,1,0]
	s_nop 0
	v_pk_fma_f32 v[160:161], v[160:161], v[162:163], s[52:53] op_sel_hi:[1,1,0]
	s_nop 0
	v_pk_fma_f32 v[158:159], v[158:159], v[160:161], 0.5 op_sel_hi:[1,1,0]
	s_nop 0
	v_pk_mul_f32 v[166:167], v[156:157], v[158:159]
	v_med3_f32 v156, v154, -4.0, 4.0
	v_med3_f32 v157, v155, -4.0, 4.0
	v_pk_mul_f32 v[158:159], v[156:157], v[156:157]
	s_nop 0
	v_pk_fma_f32 v[158:159], v[158:159], s[72:73], -1.0 op_sel_hi:[1,0,0]
	s_nop 0
	v_pk_fma_f32 v[160:161], v[158:159], s[74:75], v[152:153] op_sel_hi:[1,0,0]
	s_nop 0
	v_pk_fma_f32 v[160:161], v[158:159], v[160:161], s[0:1] op_sel_hi:[1,1,0]
	s_nop 0
	v_pk_fma_f32 v[160:161], v[158:159], v[160:161], s[2:3] op_sel_hi:[1,1,0]
	s_nop 0
	v_pk_fma_f32 v[160:161], v[158:159], v[160:161], s[28:29] op_sel_hi:[1,1,0]
	s_nop 0
	v_pk_fma_f32 v[160:161], v[158:159], v[160:161], s[30:31] op_sel_hi:[1,1,0]
	s_nop 0
	v_pk_fma_f32 v[160:161], v[158:159], v[160:161], s[48:49] op_sel_hi:[1,1,0]
	s_nop 0
	v_pk_fma_f32 v[160:161], v[158:159], v[160:161], s[50:51] op_sel_hi:[1,1,0]
	s_nop 0
	v_pk_fma_f32 v[158:159], v[158:159], v[160:161], s[52:53] op_sel_hi:[1,1,0]
	s_nop 0
	v_pk_fma_f32 v[156:157], v[156:157], v[158:159], 0.5 op_sel_hi:[1,1,0]
	s_nop 0
	v_pk_mul_f32 v[168:169], v[154:155], v[156:157]
	v_pk_mul_f32 v[156:157], v[120:121], v[150:151] op_sel_hi:[1,0]
	v_pk_mul_f32 v[154:155], v[122:123], v[150:151] op_sel_hi:[1,0]
	v_med3_f32 v158, v156, -4.0, 4.0
	v_med3_f32 v159, v157, -4.0, 4.0
	v_pk_mul_f32 v[160:161], v[158:159], v[158:159]
	s_nop 0
	v_pk_fma_f32 v[160:161], v[160:161], s[72:73], -1.0 op_sel_hi:[1,0,0]
	s_nop 0
	v_pk_fma_f32 v[162:163], v[160:161], s[74:75], v[152:153] op_sel_hi:[1,0,0]
	s_nop 0
	v_pk_fma_f32 v[162:163], v[160:161], v[162:163], s[0:1] op_sel_hi:[1,1,0]
	s_nop 0
	v_pk_fma_f32 v[162:163], v[160:161], v[162:163], s[2:3] op_sel_hi:[1,1,0]
	s_nop 0
	v_pk_fma_f32 v[162:163], v[160:161], v[162:163], s[28:29] op_sel_hi:[1,1,0]
	s_nop 0
	v_pk_fma_f32 v[162:163], v[160:161], v[162:163], s[30:31] op_sel_hi:[1,1,0]
	s_nop 0
	v_pk_fma_f32 v[162:163], v[160:161], v[162:163], s[48:49] op_sel_hi:[1,1,0]
	s_nop 0
	v_pk_fma_f32 v[162:163], v[160:161], v[162:163], s[50:51] op_sel_hi:[1,1,0]
	s_nop 0
	v_pk_fma_f32 v[160:161], v[160:161], v[162:163], s[52:53] op_sel_hi:[1,1,0]
	s_nop 0
	v_pk_fma_f32 v[160:161], v[158:159], v[160:161], 0.5 op_sel_hi:[1,1,0]
	v_med3_f32 v158, v154, -4.0, 4.0
	v_med3_f32 v159, v155, -4.0, 4.0
	v_pk_mul_f32 v[162:163], v[158:159], v[158:159]
	v_pk_mul_f32 v[170:171], v[156:157], v[160:161]
	v_pk_fma_f32 v[162:163], v[162:163], s[72:73], -1.0 op_sel_hi:[1,0,0]
	v_pk_fma_f32 v[156:157], v[156:157], v[160:161], v[170:171] op_sel:[0,0,1] op_sel_hi:[1,1,0]
	v_pk_fma_f32 v[164:165], v[162:163], s[74:75], v[152:153] op_sel_hi:[1,0,0]
	s_nop 0
	v_pk_fma_f32 v[164:165], v[162:163], v[164:165], s[0:1] op_sel_hi:[1,1,0]
	s_nop 0
	v_pk_fma_f32 v[164:165], v[162:163], v[164:165], s[2:3] op_sel_hi:[1,1,0]
	s_nop 0
	v_pk_fma_f32 v[164:165], v[162:163], v[164:165], s[28:29] op_sel_hi:[1,1,0]
	s_nop 0
	v_pk_fma_f32 v[164:165], v[162:163], v[164:165], s[30:31] op_sel_hi:[1,1,0]
	s_nop 0
	v_pk_fma_f32 v[164:165], v[162:163], v[164:165], s[48:49] op_sel_hi:[1,1,0]
	s_nop 0
	v_pk_fma_f32 v[164:165], v[162:163], v[164:165], s[50:51] op_sel_hi:[1,1,0]
	s_nop 0
	v_pk_fma_f32 v[162:163], v[162:163], v[164:165], s[52:53] op_sel_hi:[1,1,0]
	v_mov_b32_e32 v164, v167
	v_mov_b32_e32 v165, v169
	v_pk_fma_f32 v[158:159], v[158:159], v[162:163], 0.5 op_sel_hi:[1,1,0]
	v_mov_b32_e32 v162, v166
	v_mov_b32_e32 v163, v168
	v_pk_mul_f32 v[160:161], v[164:165], v[164:165]
	v_pk_mul_f32 v[158:159], v[154:155], v[158:159]
	v_pk_fma_f32 v[160:161], v[162:163], v[162:163], v[160:161]
	v_cvt_pk_bf16_f32 v166, v166, v167
	v_pk_add_f32 v[160:161], v[160:161], v[160:161] op_sel_hi:[0,1]
	v_cvt_pk_bf16_f32 v167, v168, v169
	v_cvt_pk_bf16_f32 v168, v170, v171
	v_cvt_pk_bf16_f32 v169, v158, v159
	v_mul_f32_e32 v160, v170, v170
	global_store_dwordx4 v[148:149], v[166:169], off
	v_pk_add_f32 v[154:155], v[162:163], v[164:165]
	v_pk_fma_f32 v[162:163], v[170:171], v[170:171], v[160:161] op_sel_hi:[1,1,0]
	v_pk_mul_f32 v[168:169], v[124:125], v[150:151] op_sel_hi:[1,0]
	v_pk_mul_f32 v[166:167], v[126:127], v[150:151] op_sel_hi:[1,0]
	v_med3_f32 v170, v168, -4.0, 4.0
	v_med3_f32 v171, v169, -4.0, 4.0
	v_pk_mul_f32 v[172:173], v[170:171], v[170:171]
	v_pk_mul_f32 v[164:165], v[158:159], v[158:159]
	v_pk_fma_f32 v[172:173], v[172:173], s[72:73], -1.0 op_sel_hi:[1,0,0]
	v_pk_add_f32 v[154:155], v[154:155], v[154:155] op_sel:[0,1] op_sel_hi:[1,0]
	v_pk_fma_f32 v[180:181], v[172:173], s[74:75], v[152:153] op_sel_hi:[1,0,0]
	s_nop 0
	v_pk_fma_f32 v[180:181], v[172:173], v[180:181], s[0:1] op_sel_hi:[1,1,0]
	s_nop 0
	v_pk_fma_f32 v[180:181], v[172:173], v[180:181], s[2:3] op_sel_hi:[1,1,0]
	s_nop 0
	v_pk_fma_f32 v[180:181], v[172:173], v[180:181], s[28:29] op_sel_hi:[1,1,0]
	s_nop 0
	v_pk_fma_f32 v[180:181], v[172:173], v[180:181], s[30:31] op_sel_hi:[1,1,0]
	s_nop 0
	v_pk_fma_f32 v[180:181], v[172:173], v[180:181], s[48:49] op_sel_hi:[1,1,0]
	s_nop 0
	v_pk_fma_f32 v[180:181], v[172:173], v[180:181], s[50:51] op_sel_hi:[1,1,0]
	s_nop 0
	v_pk_fma_f32 v[172:173], v[172:173], v[180:181], s[52:53] op_sel_hi:[1,1,0]
	s_nop 0
	v_pk_fma_f32 v[170:171], v[170:171], v[172:173], 0.5 op_sel_hi:[1,1,0]
	s_nop 0
	v_pk_mul_f32 v[168:169], v[168:169], v[170:171]
	v_med3_f32 v170, v166, -4.0, 4.0
	v_med3_f32 v171, v167, -4.0, 4.0
	v_pk_mul_f32 v[172:173], v[170:171], v[170:171]
	s_nop 0
	v_pk_fma_f32 v[172:173], v[172:173], s[72:73], -1.0 op_sel_hi:[1,0,0]
	s_nop 0
	v_pk_fma_f32 v[180:181], v[172:173], s[74:75], v[152:153] op_sel_hi:[1,0,0]
	s_nop 0
	v_pk_fma_f32 v[180:181], v[172:173], v[180:181], s[0:1] op_sel_hi:[1,1,0]
	s_nop 0
	v_pk_fma_f32 v[180:181], v[172:173], v[180:181], s[2:3] op_sel_hi:[1,1,0]
	s_nop 0
	v_pk_fma_f32 v[180:181], v[172:173], v[180:181], s[28:29] op_sel_hi:[1,1,0]
	s_nop 0
	v_pk_fma_f32 v[180:181], v[172:173], v[180:181], s[30:31] op_sel_hi:[1,1,0]
	s_nop 0
	v_pk_fma_f32 v[180:181], v[172:173], v[180:181], s[48:49] op_sel_hi:[1,1,0]
	s_nop 0
	v_pk_fma_f32 v[180:181], v[172:173], v[180:181], s[50:51] op_sel_hi:[1,1,0]
	s_nop 0
	v_pk_fma_f32 v[172:173], v[172:173], v[180:181], s[52:53] op_sel_hi:[1,1,0]
	s_nop 0
	v_pk_fma_f32 v[170:171], v[170:171], v[172:173], 0.5 op_sel_hi:[1,1,0]
	s_nop 0
	v_pk_mul_f32 v[166:167], v[166:167], v[170:171]
	v_pk_mul_f32 v[170:171], v[118:119], v[150:151] op_sel_hi:[1,0]
	v_pk_mul_f32 v[150:151], v[116:117], v[150:151] op_sel_hi:[1,0]
	s_nop 0
	v_med3_f32 v172, v150, -4.0, 4.0
	v_med3_f32 v173, v151, -4.0, 4.0
	v_pk_mul_f32 v[180:181], v[172:173], v[172:173]
	s_nop 0
	v_pk_fma_f32 v[180:181], v[180:181], s[72:73], -1.0 op_sel_hi:[1,0,0]
	s_nop 0
	v_pk_fma_f32 v[182:183], v[180:181], s[74:75], v[152:153] op_sel_hi:[1,0,0]
	s_nop 0
	v_pk_fma_f32 v[182:183], v[180:181], v[182:183], s[0:1] op_sel_hi:[1,1,0]
	s_nop 0
	v_pk_fma_f32 v[182:183], v[180:181], v[182:183], s[2:3] op_sel_hi:[1,1,0]
	s_nop 0
	v_pk_fma_f32 v[182:183], v[180:181], v[182:183], s[28:29] op_sel_hi:[1,1,0]
	s_nop 0
	v_pk_fma_f32 v[182:183], v[180:181], v[182:183], s[30:31] op_sel_hi:[1,1,0]
	s_nop 0
	v_pk_fma_f32 v[182:183], v[180:181], v[182:183], s[48:49] op_sel_hi:[1,1,0]
	s_nop 0
	v_pk_fma_f32 v[182:183], v[180:181], v[182:183], s[50:51] op_sel_hi:[1,1,0]
	s_nop 0
	v_pk_fma_f32 v[180:181], v[180:181], v[182:183], s[52:53] op_sel_hi:[1,1,0]
	v_med3_f32 v182, v170, -4.0, 4.0
	v_med3_f32 v183, v171, -4.0, 4.0
	v_pk_mul_f32 v[184:185], v[182:183], v[182:183]
	v_pk_fma_f32 v[172:173], v[172:173], v[180:181], 0.5 op_sel_hi:[1,1,0]
	v_pk_fma_f32 v[184:185], v[184:185], s[72:73], -1.0 op_sel_hi:[1,0,0]
	v_pk_mul_f32 v[180:181], v[150:151], v[172:173]
	v_pk_fma_f32 v[152:153], v[184:185], s[74:75], v[152:153] op_sel_hi:[1,0,0]
	v_pk_fma_f32 v[172:173], v[150:151], v[172:173], v[180:181] op_sel:[0,0,1] op_sel_hi:[1,1,0]
	v_pk_fma_f32 v[152:153], v[184:185], v[152:153], s[0:1] op_sel_hi:[1,1,0]
	v_mul_f32_e32 v150, v168, v168
	v_pk_fma_f32 v[152:153], v[184:185], v[152:153], s[2:3] op_sel_hi:[1,1,0]
	v_pk_mul_f32 v[188:189], v[180:181], v[180:181]
	v_pk_fma_f32 v[152:153], v[184:185], v[152:153], s[28:29] op_sel_hi:[1,1,0]
	v_mov_b32_e32 v173, v164
	v_pk_fma_f32 v[152:153], v[184:185], v[152:153], s[30:31] op_sel_hi:[1,1,0]
	v_mov_b32_e32 v157, v188
	v_pk_fma_f32 v[152:153], v[184:185], v[152:153], s[48:49] op_sel_hi:[1,1,0]
	v_mov_b32_e32 v155, v189
	v_pk_fma_f32 v[152:153], v[184:185], v[152:153], s[50:51] op_sel_hi:[1,1,0]
	s_nop 0
	v_pk_fma_f32 v[152:153], v[184:185], v[152:153], s[52:53] op_sel_hi:[1,1,0]
	v_pk_fma_f32 v[184:185], v[168:169], v[168:169], v[150:151] op_sel_hi:[1,1,0]
	v_pk_fma_f32 v[152:153], v[182:183], v[152:153], 0.5 op_sel_hi:[1,1,0]
	v_mov_b32_e32 v182, v169
	v_pk_mul_f32 v[170:171], v[170:171], v[152:153]
	v_mov_b32_e32 v152, v168
	v_mov_b32_e32 v153, v166
	v_mov_b32_e32 v183, v167
	v_pk_add_f32 v[152:153], v[152:153], v[182:183]
	v_mul_f32_e32 v150, v166, v166
	v_pk_add_f32 v[182:183], v[152:153], v[152:153] op_sel:[0,1] op_sel_hi:[1,0]
	v_pk_fma_f32 v[186:187], v[166:167], v[166:167], v[150:151] op_sel_hi:[1,1,0]
	v_mul_f32_e32 v150, v170, v170
	v_pk_fma_f32 v[190:191], v[170:171], v[170:171], v[150:151] op_sel_hi:[1,1,0]
	v_cvt_pk_bf16_f32 v150, v168, v169
	v_cvt_pk_bf16_f32 v151, v166, v167
	v_cvt_pk_bf16_f32 v152, v180, v181
	v_cvt_pk_bf16_f32 v153, v170, v171
	v_mov_b32_e32 v183, v165
	v_mov_b32_e32 v162, v170
	v_mov_b32_e32 v160, v171
	global_store_dwordx4 v[148:149], v[150:153], off offset:256
	v_pk_add_f32 v[148:149], v[172:173], v[182:183]
	v_mov_b32_e32 v184, v158
	v_pk_add_f32 v[150:151], v[162:163], v[160:161]
	v_mov_b32_e32 v186, v159
	v_pk_add_f32 v[148:149], v[148:149], v[150:151]
	v_pk_add_f32 v[150:151], v[184:185], v[186:187]
	v_pk_add_f32 v[152:153], v[156:157], v[154:155]
	v_mov_b32_e32 v3, v191
	v_pk_add_f32 v[150:151], v[152:153], v[150:151]
	s_nop 0
	v_pk_add_f32 v[150:151], v[150:151], v[2:3]
	s_nop 0
	v_pk_add_f32 v[148:149], v[148:149], v[150:151]
	ds_bpermute_b32 v150, v179, v148
	ds_bpermute_b32 v151, v179, v149
	s_waitcnt lgkmcnt(0)
	v_pk_add_f32 v[148:149], v[148:149], v[150:151]
	ds_bpermute_b32 v150, v178, v148
	ds_bpermute_b32 v151, v178, v149
	s_and_saveexec_b64 s[0:1], s[4:5]
	s_cbranch_execz .LBB0_454
	v_lshlrev_b64 v[152:153], 8, v[142:143]
	s_waitcnt lgkmcnt(0)
	v_pk_add_f32 v[148:149], v[148:149], v[150:151]
	v_lshl_add_u64 v[150:151], s[14:15], 0, v[152:153]
	v_lshl_add_u64 v[150:151], s[94:95], 3, v[150:151]
	global_store_dwordx2 v[150:151], v[148:149], off
.LBB0_454:
	s_or_b64 exec, exec, s[0:1]
	v_or_b32_e32 v148, 16, v142
	v_ashrrev_i32_e32 v149, 31, v148
	s_waitcnt lgkmcnt(0)
	v_lshl_add_u64 v[150:151], v[148:149], 2, s[16:17]
	s_nop 1
	v_mov_b32_e32 v152, v238
	s_mov_b32 s0, 0xbb7be14b
	v_lshlrev_b64 v[150:151], 12, v[148:149]
	v_lshl_add_u64 v[150:151], s[12:13], 0, v[150:151]
	v_lshl_add_u64 v[150:151], v[150:151], 0, v[146:147]
	v_pk_mul_f32 v[158:159], v[112:113], v[152:153] op_sel_hi:[1,0]
	s_nop 0
	v_med3_f32 v160, v158, -4.0, 4.0
	v_med3_f32 v161, v159, -4.0, 4.0
	v_pk_mul_f32 v[154:155], v[160:161], v[160:161]
	v_pk_mul_f32 v[156:157], v[114:115], v[152:153] op_sel_hi:[1,0]
	v_pk_fma_f32 v[162:163], v[154:155], s[72:73], -1.0 op_sel_hi:[1,0,0]
	v_mov_b64_e32 v[154:155], s[0:1]
	v_pk_fma_f32 v[164:165], v[162:163], s[74:75], v[154:155] op_sel_hi:[1,0,0]
	s_mov_b32 s0, 0x3bcff2a2
	v_pk_fma_f32 v[164:165], v[162:163], v[164:165], s[0:1] op_sel_hi:[1,1,0]
	s_nop 0
	v_pk_fma_f32 v[164:165], v[162:163], v[164:165], s[2:3] op_sel_hi:[1,1,0]
	s_nop 0
	v_pk_fma_f32 v[164:165], v[162:163], v[164:165], s[28:29] op_sel_hi:[1,1,0]
	s_nop 0
	v_pk_fma_f32 v[164:165], v[162:163], v[164:165], s[30:31] op_sel_hi:[1,1,0]
	s_nop 0
	v_pk_fma_f32 v[164:165], v[162:163], v[164:165], s[48:49] op_sel_hi:[1,1,0]
	s_nop 0
	v_pk_fma_f32 v[164:165], v[162:163], v[164:165], s[50:51] op_sel_hi:[1,1,0]
	s_nop 0
	v_pk_fma_f32 v[162:163], v[162:163], v[164:165], s[52:53] op_sel_hi:[1,1,0]
	s_nop 0
	v_pk_fma_f32 v[160:161], v[160:161], v[162:163], 0.5 op_sel_hi:[1,1,0]
	s_nop 0
	v_pk_mul_f32 v[168:169], v[158:159], v[160:161]
	v_med3_f32 v158, v156, -4.0, 4.0
	v_med3_f32 v159, v157, -4.0, 4.0
	v_pk_mul_f32 v[160:161], v[158:159], v[158:159]
	s_nop 0
	v_pk_fma_f32 v[160:161], v[160:161], s[72:73], -1.0 op_sel_hi:[1,0,0]
	s_nop 0
	v_pk_fma_f32 v[162:163], v[160:161], s[74:75], v[154:155] op_sel_hi:[1,0,0]
	s_nop 0
	v_pk_fma_f32 v[162:163], v[160:161], v[162:163], s[0:1] op_sel_hi:[1,1,0]
	s_nop 0
	v_pk_fma_f32 v[162:163], v[160:161], v[162:163], s[2:3] op_sel_hi:[1,1,0]
	s_nop 0
	v_pk_fma_f32 v[162:163], v[160:161], v[162:163], s[28:29] op_sel_hi:[1,1,0]
	s_nop 0
	v_pk_fma_f32 v[162:163], v[160:161], v[162:163], s[30:31] op_sel_hi:[1,1,0]
	s_nop 0
	v_pk_fma_f32 v[162:163], v[160:161], v[162:163], s[48:49] op_sel_hi:[1,1,0]
	s_nop 0
	v_pk_fma_f32 v[162:163], v[160:161], v[162:163], s[50:51] op_sel_hi:[1,1,0]
	s_nop 0
	v_pk_fma_f32 v[160:161], v[160:161], v[162:163], s[52:53] op_sel_hi:[1,1,0]
	s_nop 0
	v_pk_fma_f32 v[158:159], v[158:159], v[160:161], 0.5 op_sel_hi:[1,1,0]
	s_nop 0
	v_pk_mul_f32 v[170:171], v[156:157], v[158:159]
	v_pk_mul_f32 v[158:159], v[104:105], v[152:153] op_sel_hi:[1,0]
	v_pk_mul_f32 v[156:157], v[106:107], v[152:153] op_sel_hi:[1,0]
	v_med3_f32 v160, v158, -4.0, 4.0
	v_med3_f32 v161, v159, -4.0, 4.0
	v_pk_mul_f32 v[162:163], v[160:161], v[160:161]
	s_nop 0
	v_pk_fma_f32 v[162:163], v[162:163], s[72:73], -1.0 op_sel_hi:[1,0,0]
	s_nop 0
	v_pk_fma_f32 v[164:165], v[162:163], s[74:75], v[154:155] op_sel_hi:[1,0,0]
	s_nop 0
	v_pk_fma_f32 v[164:165], v[162:163], v[164:165], s[0:1] op_sel_hi:[1,1,0]
	s_nop 0
	v_pk_fma_f32 v[164:165], v[162:163], v[164:165], s[2:3] op_sel_hi:[1,1,0]
	s_nop 0
	v_pk_fma_f32 v[164:165], v[162:163], v[164:165], s[28:29] op_sel_hi:[1,1,0]
	s_nop 0
	v_pk_fma_f32 v[164:165], v[162:163], v[164:165], s[30:31] op_sel_hi:[1,1,0]
	s_nop 0
	v_pk_fma_f32 v[164:165], v[162:163], v[164:165], s[48:49] op_sel_hi:[1,1,0]
	s_nop 0
	v_pk_fma_f32 v[164:165], v[162:163], v[164:165], s[50:51] op_sel_hi:[1,1,0]
	s_nop 0
	v_pk_fma_f32 v[162:163], v[162:163], v[164:165], s[52:53] op_sel_hi:[1,1,0]
	s_nop 0
	v_pk_fma_f32 v[162:163], v[160:161], v[162:163], 0.5 op_sel_hi:[1,1,0]
	v_med3_f32 v160, v156, -4.0, 4.0
	v_med3_f32 v161, v157, -4.0, 4.0
	v_pk_mul_f32 v[164:165], v[160:161], v[160:161]
	v_pk_mul_f32 v[172:173], v[158:159], v[162:163]
	v_pk_fma_f32 v[164:165], v[164:165], s[72:73], -1.0 op_sel_hi:[1,0,0]
	v_pk_fma_f32 v[158:159], v[158:159], v[162:163], v[172:173] op_sel:[0,0,1] op_sel_hi:[1,1,0]
	v_pk_fma_f32 v[166:167], v[164:165], s[74:75], v[154:155] op_sel_hi:[1,0,0]
	s_nop 0
	v_pk_fma_f32 v[166:167], v[164:165], v[166:167], s[0:1] op_sel_hi:[1,1,0]
	s_nop 0
	v_pk_fma_f32 v[166:167], v[164:165], v[166:167], s[2:3] op_sel_hi:[1,1,0]
	s_nop 0
	v_pk_fma_f32 v[166:167], v[164:165], v[166:167], s[28:29] op_sel_hi:[1,1,0]
	s_nop 0
	v_pk_fma_f32 v[166:167], v[164:165], v[166:167], s[30:31] op_sel_hi:[1,1,0]
	s_nop 0
	v_pk_fma_f32 v[166:167], v[164:165], v[166:167], s[48:49] op_sel_hi:[1,1,0]
	s_nop 0
	v_pk_fma_f32 v[166:167], v[164:165], v[166:167], s[50:51] op_sel_hi:[1,1,0]
	s_nop 0
	v_pk_fma_f32 v[164:165], v[164:165], v[166:167], s[52:53] op_sel_hi:[1,1,0]
	v_mov_b32_e32 v166, v169
	v_mov_b32_e32 v167, v171
	v_pk_fma_f32 v[160:161], v[160:161], v[164:165], 0.5 op_sel_hi:[1,1,0]
	v_mov_b32_e32 v164, v168
	v_mov_b32_e32 v165, v170
	v_pk_mul_f32 v[162:163], v[166:167], v[166:167]
	v_pk_mul_f32 v[160:161], v[156:157], v[160:161]
	v_pk_fma_f32 v[162:163], v[164:165], v[164:165], v[162:163]
	v_cvt_pk_bf16_f32 v168, v168, v169
	v_pk_add_f32 v[162:163], v[162:163], v[162:163] op_sel_hi:[0,1]
	v_cvt_pk_bf16_f32 v169, v170, v171
	v_cvt_pk_bf16_f32 v170, v172, v173
	v_cvt_pk_bf16_f32 v171, v160, v161
	v_mul_f32_e32 v162, v172, v172
	global_store_dwordx4 v[150:151], v[168:171], off
	v_pk_add_f32 v[156:157], v[164:165], v[166:167]
	v_pk_fma_f32 v[164:165], v[172:173], v[172:173], v[162:163] op_sel_hi:[1,1,0]
	v_pk_mul_f32 v[168:169], v[108:109], v[152:153] op_sel_hi:[1,0]
	v_pk_mul_f32 v[170:171], v[110:111], v[152:153] op_sel_hi:[1,0]
	v_med3_f32 v172, v168, -4.0, 4.0
	v_med3_f32 v173, v169, -4.0, 4.0
	v_pk_mul_f32 v[180:181], v[172:173], v[172:173]
	v_pk_mul_f32 v[166:167], v[160:161], v[160:161]
	v_pk_fma_f32 v[180:181], v[180:181], s[72:73], -1.0 op_sel_hi:[1,0,0]
	v_pk_add_f32 v[156:157], v[156:157], v[156:157] op_sel:[0,1] op_sel_hi:[1,0]
	v_pk_fma_f32 v[182:183], v[180:181], s[74:75], v[154:155] op_sel_hi:[1,0,0]
	s_nop 0
	v_pk_fma_f32 v[182:183], v[180:181], v[182:183], s[0:1] op_sel_hi:[1,1,0]
	s_nop 0
	v_pk_fma_f32 v[182:183], v[180:181], v[182:183], s[2:3] op_sel_hi:[1,1,0]
	s_nop 0
	v_pk_fma_f32 v[182:183], v[180:181], v[182:183], s[28:29] op_sel_hi:[1,1,0]
	s_nop 0
	v_pk_fma_f32 v[182:183], v[180:181], v[182:183], s[30:31] op_sel_hi:[1,1,0]
	s_nop 0
	v_pk_fma_f32 v[182:183], v[180:181], v[182:183], s[48:49] op_sel_hi:[1,1,0]
	s_nop 0
	v_pk_fma_f32 v[182:183], v[180:181], v[182:183], s[50:51] op_sel_hi:[1,1,0]
	s_nop 0
	v_pk_fma_f32 v[180:181], v[180:181], v[182:183], s[52:53] op_sel_hi:[1,1,0]
	s_nop 0
	v_pk_fma_f32 v[172:173], v[172:173], v[180:181], 0.5 op_sel_hi:[1,1,0]
	s_nop 0
	v_pk_mul_f32 v[168:169], v[168:169], v[172:173]
	v_med3_f32 v172, v170, -4.0, 4.0
	v_med3_f32 v173, v171, -4.0, 4.0
	v_pk_mul_f32 v[180:181], v[172:173], v[172:173]
	s_nop 0
	v_pk_fma_f32 v[180:181], v[180:181], s[72:73], -1.0 op_sel_hi:[1,0,0]
	s_nop 0
	v_pk_fma_f32 v[182:183], v[180:181], s[74:75], v[154:155] op_sel_hi:[1,0,0]
	s_nop 0
	v_pk_fma_f32 v[182:183], v[180:181], v[182:183], s[0:1] op_sel_hi:[1,1,0]
	s_nop 0
	v_pk_fma_f32 v[182:183], v[180:181], v[182:183], s[2:3] op_sel_hi:[1,1,0]
	s_nop 0
	v_pk_fma_f32 v[182:183], v[180:181], v[182:183], s[28:29] op_sel_hi:[1,1,0]
	s_nop 0
	v_pk_fma_f32 v[182:183], v[180:181], v[182:183], s[30:31] op_sel_hi:[1,1,0]
	s_nop 0
	v_pk_fma_f32 v[182:183], v[180:181], v[182:183], s[48:49] op_sel_hi:[1,1,0]
	s_nop 0
	v_pk_fma_f32 v[182:183], v[180:181], v[182:183], s[50:51] op_sel_hi:[1,1,0]
	s_nop 0
	v_pk_fma_f32 v[180:181], v[180:181], v[182:183], s[52:53] op_sel_hi:[1,1,0]
	s_nop 0
	v_pk_fma_f32 v[172:173], v[172:173], v[180:181], 0.5 op_sel_hi:[1,1,0]
	s_nop 0
	v_pk_mul_f32 v[170:171], v[170:171], v[172:173]
	v_pk_mul_f32 v[172:173], v[102:103], v[152:153] op_sel_hi:[1,0]
	v_pk_mul_f32 v[152:153], v[100:101], v[152:153] op_sel_hi:[1,0]
	s_nop 0
	v_med3_f32 v180, v152, -4.0, 4.0
	v_med3_f32 v181, v153, -4.0, 4.0
	v_pk_mul_f32 v[182:183], v[180:181], v[180:181]
	s_nop 0
	v_pk_fma_f32 v[182:183], v[182:183], s[72:73], -1.0 op_sel_hi:[1,0,0]
	s_nop 0
	v_pk_fma_f32 v[184:185], v[182:183], s[74:75], v[154:155] op_sel_hi:[1,0,0]
	s_nop 0
	v_pk_fma_f32 v[184:185], v[182:183], v[184:185], s[0:1] op_sel_hi:[1,1,0]
	s_nop 0
	v_pk_fma_f32 v[184:185], v[182:183], v[184:185], s[2:3] op_sel_hi:[1,1,0]
	s_nop 0
	v_pk_fma_f32 v[184:185], v[182:183], v[184:185], s[28:29] op_sel_hi:[1,1,0]
	s_nop 0
	v_pk_fma_f32 v[184:185], v[182:183], v[184:185], s[30:31] op_sel_hi:[1,1,0]
	s_nop 0
	v_pk_fma_f32 v[184:185], v[182:183], v[184:185], s[48:49] op_sel_hi:[1,1,0]
	s_nop 0
	v_pk_fma_f32 v[184:185], v[182:183], v[184:185], s[50:51] op_sel_hi:[1,1,0]
	s_nop 0
	v_pk_fma_f32 v[182:183], v[182:183], v[184:185], s[52:53] op_sel_hi:[1,1,0]
	v_med3_f32 v184, v172, -4.0, 4.0
	v_med3_f32 v185, v173, -4.0, 4.0
	v_pk_mul_f32 v[186:187], v[184:185], v[184:185]
	v_pk_fma_f32 v[180:181], v[180:181], v[182:183], 0.5 op_sel_hi:[1,1,0]
	v_pk_fma_f32 v[186:187], v[186:187], s[72:73], -1.0 op_sel_hi:[1,0,0]
	v_pk_mul_f32 v[182:183], v[152:153], v[180:181]
	v_pk_fma_f32 v[154:155], v[186:187], s[74:75], v[154:155] op_sel_hi:[1,0,0]
	v_pk_fma_f32 v[180:181], v[152:153], v[180:181], v[182:183] op_sel:[0,0,1] op_sel_hi:[1,1,0]
	v_pk_fma_f32 v[154:155], v[186:187], v[154:155], s[0:1] op_sel_hi:[1,1,0]
	v_mul_f32_e32 v152, v168, v168
	v_pk_fma_f32 v[154:155], v[186:187], v[154:155], s[2:3] op_sel_hi:[1,1,0]
	v_pk_mul_f32 v[190:191], v[182:183], v[182:183]
	v_pk_fma_f32 v[154:155], v[186:187], v[154:155], s[28:29] op_sel_hi:[1,1,0]
	v_mov_b32_e32 v181, v166
	v_pk_fma_f32 v[154:155], v[186:187], v[154:155], s[30:31] op_sel_hi:[1,1,0]
	v_mov_b32_e32 v159, v190
	v_pk_fma_f32 v[154:155], v[186:187], v[154:155], s[48:49] op_sel_hi:[1,1,0]
	v_mov_b32_e32 v157, v191
	v_pk_fma_f32 v[154:155], v[186:187], v[154:155], s[50:51] op_sel_hi:[1,1,0]
	s_nop 0
	v_pk_fma_f32 v[154:155], v[186:187], v[154:155], s[52:53] op_sel_hi:[1,1,0]
	v_pk_fma_f32 v[186:187], v[168:169], v[168:169], v[152:153] op_sel_hi:[1,1,0]
	v_pk_fma_f32 v[154:155], v[184:185], v[154:155], 0.5 op_sel_hi:[1,1,0]
	v_mov_b32_e32 v184, v169
	v_pk_mul_f32 v[172:173], v[172:173], v[154:155]
	v_mov_b32_e32 v154, v168
	v_mov_b32_e32 v155, v170
	v_mov_b32_e32 v185, v171
	v_pk_add_f32 v[154:155], v[154:155], v[184:185]
	v_mul_f32_e32 v152, v170, v170
	v_pk_add_f32 v[184:185], v[154:155], v[154:155] op_sel:[0,1] op_sel_hi:[1,0]
	v_pk_fma_f32 v[188:189], v[170:171], v[170:171], v[152:153] op_sel_hi:[1,1,0]
	v_mul_f32_e32 v152, v172, v172
	v_pk_fma_f32 v[192:193], v[172:173], v[172:173], v[152:153] op_sel_hi:[1,1,0]
	v_cvt_pk_bf16_f32 v152, v168, v169
	v_cvt_pk_bf16_f32 v153, v170, v171
	v_cvt_pk_bf16_f32 v154, v182, v183
	v_cvt_pk_bf16_f32 v155, v172, v173
	v_mov_b32_e32 v185, v167
	v_mov_b32_e32 v164, v172
	v_mov_b32_e32 v162, v173
	global_store_dwordx4 v[150:151], v[152:155], off offset:256
	v_pk_add_f32 v[150:151], v[180:181], v[184:185]
	v_mov_b32_e32 v186, v160
	v_pk_add_f32 v[152:153], v[164:165], v[162:163]
	v_mov_b32_e32 v188, v161
	v_pk_add_f32 v[150:151], v[150:151], v[152:153]
	v_pk_add_f32 v[152:153], v[186:187], v[188:189]
	v_pk_add_f32 v[154:155], v[158:159], v[156:157]
	v_mov_b32_e32 v3, v193
	v_pk_add_f32 v[152:153], v[154:155], v[152:153]
	s_nop 0
	v_pk_add_f32 v[152:153], v[152:153], v[2:3]
	s_nop 0
	v_pk_add_f32 v[150:151], v[150:151], v[152:153]
	ds_bpermute_b32 v152, v179, v150
	ds_bpermute_b32 v153, v179, v151
	s_waitcnt lgkmcnt(0)
	v_pk_add_f32 v[150:151], v[150:151], v[152:153]
	ds_bpermute_b32 v152, v178, v150
	ds_bpermute_b32 v153, v178, v151
	s_and_saveexec_b64 s[0:1], s[4:5]
	s_cbranch_execz .LBB0_456
	v_lshlrev_b64 v[148:149], 8, v[148:149]
	v_lshl_add_u64 v[148:149], s[14:15], 0, v[148:149]
	s_waitcnt lgkmcnt(0)
	v_pk_add_f32 v[150:151], v[150:151], v[152:153]
	v_lshl_add_u64 v[148:149], s[94:95], 3, v[148:149]
	global_store_dwordx2 v[148:149], v[150:151], off
.LBB0_456:
	s_or_b64 exec, exec, s[0:1]
	v_or_b32_e32 v148, 32, v142
	v_ashrrev_i32_e32 v149, 31, v148
	v_lshl_add_u64 v[150:151], v[148:149], 2, s[16:17]
	s_waitcnt lgkmcnt(1)
	s_nop 1
	v_mov_b32_e32 v152, v240
	s_mov_b32 s0, 0xbb7be14b
	v_lshlrev_b64 v[150:151], 12, v[148:149]
	v_lshl_add_u64 v[150:151], s[12:13], 0, v[150:151]
	v_mov_b32_e32 v147, v2
	v_lshl_add_u64 v[150:151], v[150:151], 0, v[146:147]
	s_waitcnt lgkmcnt(0)
	v_pk_mul_f32 v[158:159], v[96:97], v[152:153] op_sel_hi:[1,0]
	s_nop 0
	v_med3_f32 v160, v158, -4.0, 4.0
	v_med3_f32 v161, v159, -4.0, 4.0
	v_pk_mul_f32 v[154:155], v[160:161], v[160:161]
	v_pk_mul_f32 v[156:157], v[98:99], v[152:153] op_sel_hi:[1,0]
	v_pk_fma_f32 v[162:163], v[154:155], s[72:73], -1.0 op_sel_hi:[1,0,0]
	v_mov_b64_e32 v[154:155], s[0:1]
	v_pk_fma_f32 v[164:165], v[162:163], s[74:75], v[154:155] op_sel_hi:[1,0,0]
	s_mov_b32 s0, 0x3bcff2a2
	v_pk_fma_f32 v[164:165], v[162:163], v[164:165], s[0:1] op_sel_hi:[1,1,0]
	s_nop 0
	v_pk_fma_f32 v[164:165], v[162:163], v[164:165], s[2:3] op_sel_hi:[1,1,0]
	s_nop 0
	v_pk_fma_f32 v[164:165], v[162:163], v[164:165], s[28:29] op_sel_hi:[1,1,0]
	s_nop 0
	v_pk_fma_f32 v[164:165], v[162:163], v[164:165], s[30:31] op_sel_hi:[1,1,0]
	s_nop 0
	v_pk_fma_f32 v[164:165], v[162:163], v[164:165], s[48:49] op_sel_hi:[1,1,0]
	s_nop 0
	v_pk_fma_f32 v[164:165], v[162:163], v[164:165], s[50:51] op_sel_hi:[1,1,0]
	s_nop 0
	v_pk_fma_f32 v[162:163], v[162:163], v[164:165], s[52:53] op_sel_hi:[1,1,0]
	s_nop 0
	v_pk_fma_f32 v[160:161], v[160:161], v[162:163], 0.5 op_sel_hi:[1,1,0]
	s_nop 0
	v_pk_mul_f32 v[168:169], v[158:159], v[160:161]
	v_med3_f32 v158, v156, -4.0, 4.0
	v_med3_f32 v159, v157, -4.0, 4.0
	v_pk_mul_f32 v[160:161], v[158:159], v[158:159]
	s_nop 0
	v_pk_fma_f32 v[160:161], v[160:161], s[72:73], -1.0 op_sel_hi:[1,0,0]
	s_nop 0
	v_pk_fma_f32 v[162:163], v[160:161], s[74:75], v[154:155] op_sel_hi:[1,0,0]
	s_nop 0
	v_pk_fma_f32 v[162:163], v[160:161], v[162:163], s[0:1] op_sel_hi:[1,1,0]
	s_nop 0
	v_pk_fma_f32 v[162:163], v[160:161], v[162:163], s[2:3] op_sel_hi:[1,1,0]
	s_nop 0
	v_pk_fma_f32 v[162:163], v[160:161], v[162:163], s[28:29] op_sel_hi:[1,1,0]
	s_nop 0
	v_pk_fma_f32 v[162:163], v[160:161], v[162:163], s[30:31] op_sel_hi:[1,1,0]
	s_nop 0
	v_pk_fma_f32 v[162:163], v[160:161], v[162:163], s[48:49] op_sel_hi:[1,1,0]
	s_nop 0
	v_pk_fma_f32 v[162:163], v[160:161], v[162:163], s[50:51] op_sel_hi:[1,1,0]
	s_nop 0
	v_pk_fma_f32 v[160:161], v[160:161], v[162:163], s[52:53] op_sel_hi:[1,1,0]
	s_nop 0
	v_pk_fma_f32 v[158:159], v[158:159], v[160:161], 0.5 op_sel_hi:[1,1,0]
	s_nop 0
	v_pk_mul_f32 v[170:171], v[156:157], v[158:159]
	v_pk_mul_f32 v[158:159], v[88:89], v[152:153] op_sel_hi:[1,0]
	v_pk_mul_f32 v[156:157], v[90:91], v[152:153] op_sel_hi:[1,0]
	v_med3_f32 v160, v158, -4.0, 4.0
	v_med3_f32 v161, v159, -4.0, 4.0
	v_pk_mul_f32 v[162:163], v[160:161], v[160:161]
	s_nop 0
	v_pk_fma_f32 v[162:163], v[162:163], s[72:73], -1.0 op_sel_hi:[1,0,0]
	s_nop 0
	v_pk_fma_f32 v[164:165], v[162:163], s[74:75], v[154:155] op_sel_hi:[1,0,0]
	s_nop 0
	v_pk_fma_f32 v[164:165], v[162:163], v[164:165], s[0:1] op_sel_hi:[1,1,0]
	s_nop 0
	v_pk_fma_f32 v[164:165], v[162:163], v[164:165], s[2:3] op_sel_hi:[1,1,0]
	s_nop 0
	v_pk_fma_f32 v[164:165], v[162:163], v[164:165], s[28:29] op_sel_hi:[1,1,0]
	s_nop 0
	v_pk_fma_f32 v[164:165], v[162:163], v[164:165], s[30:31] op_sel_hi:[1,1,0]
	s_nop 0
	v_pk_fma_f32 v[164:165], v[162:163], v[164:165], s[48:49] op_sel_hi:[1,1,0]
	s_nop 0
	v_pk_fma_f32 v[164:165], v[162:163], v[164:165], s[50:51] op_sel_hi:[1,1,0]
	s_nop 0
	v_pk_fma_f32 v[162:163], v[162:163], v[164:165], s[52:53] op_sel_hi:[1,1,0]
	s_nop 0
	v_pk_fma_f32 v[162:163], v[160:161], v[162:163], 0.5 op_sel_hi:[1,1,0]
	v_med3_f32 v160, v156, -4.0, 4.0
	v_med3_f32 v161, v157, -4.0, 4.0
	v_pk_mul_f32 v[164:165], v[160:161], v[160:161]
	v_pk_mul_f32 v[172:173], v[158:159], v[162:163]
	v_pk_fma_f32 v[164:165], v[164:165], s[72:73], -1.0 op_sel_hi:[1,0,0]
	v_pk_fma_f32 v[158:159], v[158:159], v[162:163], v[172:173] op_sel:[0,0,1] op_sel_hi:[1,1,0]
	v_pk_fma_f32 v[166:167], v[164:165], s[74:75], v[154:155] op_sel_hi:[1,0,0]
	s_nop 0
	v_pk_fma_f32 v[166:167], v[164:165], v[166:167], s[0:1] op_sel_hi:[1,1,0]
	s_nop 0
	v_pk_fma_f32 v[166:167], v[164:165], v[166:167], s[2:3] op_sel_hi:[1,1,0]
	s_nop 0
	v_pk_fma_f32 v[166:167], v[164:165], v[166:167], s[28:29] op_sel_hi:[1,1,0]
	s_nop 0
	v_pk_fma_f32 v[166:167], v[164:165], v[166:167], s[30:31] op_sel_hi:[1,1,0]
	s_nop 0
	v_pk_fma_f32 v[166:167], v[164:165], v[166:167], s[48:49] op_sel_hi:[1,1,0]
	s_nop 0
	v_pk_fma_f32 v[166:167], v[164:165], v[166:167], s[50:51] op_sel_hi:[1,1,0]
	s_nop 0
	v_pk_fma_f32 v[164:165], v[164:165], v[166:167], s[52:53] op_sel_hi:[1,1,0]
	v_mov_b32_e32 v166, v169
	v_mov_b32_e32 v167, v171
	v_pk_fma_f32 v[160:161], v[160:161], v[164:165], 0.5 op_sel_hi:[1,1,0]
	v_mov_b32_e32 v164, v168
	v_mov_b32_e32 v165, v170
	v_pk_mul_f32 v[162:163], v[166:167], v[166:167]
	v_pk_mul_f32 v[160:161], v[156:157], v[160:161]
	v_pk_fma_f32 v[162:163], v[164:165], v[164:165], v[162:163]
	v_cvt_pk_bf16_f32 v168, v168, v169
	v_pk_add_f32 v[162:163], v[162:163], v[162:163] op_sel_hi:[0,1]
	v_cvt_pk_bf16_f32 v169, v170, v171
	v_cvt_pk_bf16_f32 v170, v172, v173
	v_cvt_pk_bf16_f32 v171, v160, v161
	v_mul_f32_e32 v162, v172, v172
	global_store_dwordx4 v[150:151], v[168:171], off
	v_pk_add_f32 v[156:157], v[164:165], v[166:167]
	v_pk_fma_f32 v[164:165], v[172:173], v[172:173], v[162:163] op_sel_hi:[1,1,0]
	v_pk_mul_f32 v[168:169], v[92:93], v[152:153] op_sel_hi:[1,0]
	v_pk_mul_f32 v[170:171], v[94:95], v[152:153] op_sel_hi:[1,0]
	v_med3_f32 v172, v168, -4.0, 4.0
	v_med3_f32 v173, v169, -4.0, 4.0
	v_pk_mul_f32 v[180:181], v[172:173], v[172:173]
	v_pk_mul_f32 v[166:167], v[160:161], v[160:161]
	v_pk_fma_f32 v[180:181], v[180:181], s[72:73], -1.0 op_sel_hi:[1,0,0]
	v_pk_add_f32 v[156:157], v[156:157], v[156:157] op_sel:[0,1] op_sel_hi:[1,0]
	v_pk_fma_f32 v[182:183], v[180:181], s[74:75], v[154:155] op_sel_hi:[1,0,0]
	s_nop 0
	v_pk_fma_f32 v[182:183], v[180:181], v[182:183], s[0:1] op_sel_hi:[1,1,0]
	s_nop 0
	v_pk_fma_f32 v[182:183], v[180:181], v[182:183], s[2:3] op_sel_hi:[1,1,0]
	s_nop 0
	v_pk_fma_f32 v[182:183], v[180:181], v[182:183], s[28:29] op_sel_hi:[1,1,0]
	s_nop 0
	v_pk_fma_f32 v[182:183], v[180:181], v[182:183], s[30:31] op_sel_hi:[1,1,0]
	s_nop 0
	v_pk_fma_f32 v[182:183], v[180:181], v[182:183], s[48:49] op_sel_hi:[1,1,0]
	s_nop 0
	v_pk_fma_f32 v[182:183], v[180:181], v[182:183], s[50:51] op_sel_hi:[1,1,0]
	s_nop 0
	v_pk_fma_f32 v[180:181], v[180:181], v[182:183], s[52:53] op_sel_hi:[1,1,0]
	s_nop 0
	v_pk_fma_f32 v[172:173], v[172:173], v[180:181], 0.5 op_sel_hi:[1,1,0]
	s_nop 0
	v_pk_mul_f32 v[168:169], v[168:169], v[172:173]
	v_med3_f32 v172, v170, -4.0, 4.0
	v_med3_f32 v173, v171, -4.0, 4.0
	v_pk_mul_f32 v[180:181], v[172:173], v[172:173]
	s_nop 0
	v_pk_fma_f32 v[180:181], v[180:181], s[72:73], -1.0 op_sel_hi:[1,0,0]
	s_nop 0
	v_pk_fma_f32 v[182:183], v[180:181], s[74:75], v[154:155] op_sel_hi:[1,0,0]
	s_nop 0
	v_pk_fma_f32 v[182:183], v[180:181], v[182:183], s[0:1] op_sel_hi:[1,1,0]
	s_nop 0
	v_pk_fma_f32 v[182:183], v[180:181], v[182:183], s[2:3] op_sel_hi:[1,1,0]
	s_nop 0
	v_pk_fma_f32 v[182:183], v[180:181], v[182:183], s[28:29] op_sel_hi:[1,1,0]
	s_nop 0
	v_pk_fma_f32 v[182:183], v[180:181], v[182:183], s[30:31] op_sel_hi:[1,1,0]
	s_nop 0
	v_pk_fma_f32 v[182:183], v[180:181], v[182:183], s[48:49] op_sel_hi:[1,1,0]
	s_nop 0
	v_pk_fma_f32 v[182:183], v[180:181], v[182:183], s[50:51] op_sel_hi:[1,1,0]
	s_nop 0
	v_pk_fma_f32 v[180:181], v[180:181], v[182:183], s[52:53] op_sel_hi:[1,1,0]
	s_nop 0
	v_pk_fma_f32 v[172:173], v[172:173], v[180:181], 0.5 op_sel_hi:[1,1,0]
	s_nop 0
	v_pk_mul_f32 v[170:171], v[170:171], v[172:173]
	v_pk_mul_f32 v[172:173], v[86:87], v[152:153] op_sel_hi:[1,0]
	v_pk_mul_f32 v[152:153], v[84:85], v[152:153] op_sel_hi:[1,0]
	s_nop 0
	v_med3_f32 v180, v152, -4.0, 4.0
	v_med3_f32 v181, v153, -4.0, 4.0
	v_pk_mul_f32 v[182:183], v[180:181], v[180:181]
	s_nop 0
	v_pk_fma_f32 v[182:183], v[182:183], s[72:73], -1.0 op_sel_hi:[1,0,0]
	s_nop 0
	v_pk_fma_f32 v[184:185], v[182:183], s[74:75], v[154:155] op_sel_hi:[1,0,0]
	s_nop 0
	v_pk_fma_f32 v[184:185], v[182:183], v[184:185], s[0:1] op_sel_hi:[1,1,0]
	s_nop 0
	v_pk_fma_f32 v[184:185], v[182:183], v[184:185], s[2:3] op_sel_hi:[1,1,0]
	s_nop 0
	v_pk_fma_f32 v[184:185], v[182:183], v[184:185], s[28:29] op_sel_hi:[1,1,0]
	s_nop 0
	v_pk_fma_f32 v[184:185], v[182:183], v[184:185], s[30:31] op_sel_hi:[1,1,0]
	s_nop 0
	v_pk_fma_f32 v[184:185], v[182:183], v[184:185], s[48:49] op_sel_hi:[1,1,0]
	s_nop 0
	v_pk_fma_f32 v[184:185], v[182:183], v[184:185], s[50:51] op_sel_hi:[1,1,0]
	s_nop 0
	v_pk_fma_f32 v[182:183], v[182:183], v[184:185], s[52:53] op_sel_hi:[1,1,0]
	v_med3_f32 v184, v172, -4.0, 4.0
	v_med3_f32 v185, v173, -4.0, 4.0
	v_pk_mul_f32 v[186:187], v[184:185], v[184:185]
	v_pk_fma_f32 v[180:181], v[180:181], v[182:183], 0.5 op_sel_hi:[1,1,0]
	v_pk_fma_f32 v[186:187], v[186:187], s[72:73], -1.0 op_sel_hi:[1,0,0]
	v_pk_mul_f32 v[182:183], v[152:153], v[180:181]
	v_pk_fma_f32 v[154:155], v[186:187], s[74:75], v[154:155] op_sel_hi:[1,0,0]
	v_pk_fma_f32 v[180:181], v[152:153], v[180:181], v[182:183] op_sel:[0,0,1] op_sel_hi:[1,1,0]
	v_pk_fma_f32 v[154:155], v[186:187], v[154:155], s[0:1] op_sel_hi:[1,1,0]
	v_mul_f32_e32 v152, v168, v168
	v_pk_fma_f32 v[154:155], v[186:187], v[154:155], s[2:3] op_sel_hi:[1,1,0]
	v_pk_mul_f32 v[190:191], v[182:183], v[182:183]
	v_pk_fma_f32 v[154:155], v[186:187], v[154:155], s[28:29] op_sel_hi:[1,1,0]
	v_mov_b32_e32 v181, v166
	v_pk_fma_f32 v[154:155], v[186:187], v[154:155], s[30:31] op_sel_hi:[1,1,0]
	v_mov_b32_e32 v159, v190
	v_pk_fma_f32 v[154:155], v[186:187], v[154:155], s[48:49] op_sel_hi:[1,1,0]
	v_mov_b32_e32 v157, v191
	v_pk_fma_f32 v[154:155], v[186:187], v[154:155], s[50:51] op_sel_hi:[1,1,0]
	s_nop 0
	v_pk_fma_f32 v[154:155], v[186:187], v[154:155], s[52:53] op_sel_hi:[1,1,0]
	v_pk_fma_f32 v[186:187], v[168:169], v[168:169], v[152:153] op_sel_hi:[1,1,0]
	v_pk_fma_f32 v[154:155], v[184:185], v[154:155], 0.5 op_sel_hi:[1,1,0]
	v_mov_b32_e32 v184, v169
	v_pk_mul_f32 v[172:173], v[172:173], v[154:155]
	v_mov_b32_e32 v154, v168
	v_mov_b32_e32 v155, v170
	v_mov_b32_e32 v185, v171
	v_pk_add_f32 v[154:155], v[154:155], v[184:185]
	v_mul_f32_e32 v152, v170, v170
	v_pk_add_f32 v[184:185], v[154:155], v[154:155] op_sel:[0,1] op_sel_hi:[1,0]
	v_pk_fma_f32 v[188:189], v[170:171], v[170:171], v[152:153] op_sel_hi:[1,1,0]
	v_mul_f32_e32 v152, v172, v172
	v_pk_fma_f32 v[192:193], v[172:173], v[172:173], v[152:153] op_sel_hi:[1,1,0]
	v_cvt_pk_bf16_f32 v152, v168, v169
	v_cvt_pk_bf16_f32 v153, v170, v171
	v_cvt_pk_bf16_f32 v154, v182, v183
	v_cvt_pk_bf16_f32 v155, v172, v173
	v_mov_b32_e32 v185, v167
	v_mov_b32_e32 v164, v172
	v_mov_b32_e32 v162, v173
	global_store_dwordx4 v[150:151], v[152:155], off offset:256
	v_pk_add_f32 v[150:151], v[180:181], v[184:185]
	v_mov_b32_e32 v186, v160
	v_pk_add_f32 v[152:153], v[164:165], v[162:163]
	v_mov_b32_e32 v188, v161
	v_pk_add_f32 v[150:151], v[150:151], v[152:153]
	v_pk_add_f32 v[152:153], v[186:187], v[188:189]
	v_pk_add_f32 v[154:155], v[158:159], v[156:157]
	v_mov_b32_e32 v3, v193
	v_pk_add_f32 v[152:153], v[154:155], v[152:153]
	s_nop 0
	v_pk_add_f32 v[152:153], v[152:153], v[2:3]
	s_nop 0
	v_pk_add_f32 v[150:151], v[150:151], v[152:153]
	ds_bpermute_b32 v152, v179, v150
	ds_bpermute_b32 v153, v179, v151
	s_waitcnt lgkmcnt(0)
	v_pk_add_f32 v[150:151], v[150:151], v[152:153]
	ds_bpermute_b32 v152, v178, v150
	ds_bpermute_b32 v153, v178, v151
	s_and_saveexec_b64 s[0:1], s[4:5]
	s_cbranch_execz .LBB0_458
	v_lshlrev_b64 v[148:149], 8, v[148:149]
	v_lshl_add_u64 v[148:149], s[14:15], 0, v[148:149]
	s_waitcnt lgkmcnt(0)
	v_pk_add_f32 v[150:151], v[150:151], v[152:153]
	v_lshl_add_u64 v[148:149], s[94:95], 3, v[148:149]
	global_store_dwordx2 v[148:149], v[150:151], off
.LBB0_458:
	s_or_b64 exec, exec, s[0:1]
	v_or_b32_e32 v148, 48, v142
	v_ashrrev_i32_e32 v149, 31, v148
	v_lshl_add_u64 v[150:151], v[148:149], 2, s[16:17]
	s_waitcnt lgkmcnt(1)
	s_nop 1
	v_mov_b32_e32 v152, v242
	s_mov_b32 s0, 0xbb7be14b
	v_lshlrev_b64 v[150:151], 12, v[148:149]
	v_lshl_add_u64 v[150:151], s[12:13], 0, v[150:151]
	v_lshl_add_u64 v[150:151], v[150:151], 0, v[146:147]
	s_waitcnt lgkmcnt(0)
	v_pk_mul_f32 v[158:159], v[80:81], v[152:153] op_sel_hi:[1,0]
	s_nop 0
	v_med3_f32 v160, v158, -4.0, 4.0
	v_med3_f32 v161, v159, -4.0, 4.0
	v_pk_mul_f32 v[154:155], v[160:161], v[160:161]
	v_pk_mul_f32 v[156:157], v[82:83], v[152:153] op_sel_hi:[1,0]
	v_pk_fma_f32 v[162:163], v[154:155], s[72:73], -1.0 op_sel_hi:[1,0,0]
	v_mov_b64_e32 v[154:155], s[0:1]
	v_pk_fma_f32 v[164:165], v[162:163], s[74:75], v[154:155] op_sel_hi:[1,0,0]
	s_mov_b32 s0, 0x3bcff2a2
	v_pk_fma_f32 v[164:165], v[162:163], v[164:165], s[0:1] op_sel_hi:[1,1,0]
	s_nop 0
	v_pk_fma_f32 v[164:165], v[162:163], v[164:165], s[2:3] op_sel_hi:[1,1,0]
	s_nop 0
	v_pk_fma_f32 v[164:165], v[162:163], v[164:165], s[28:29] op_sel_hi:[1,1,0]
	s_nop 0
	v_pk_fma_f32 v[164:165], v[162:163], v[164:165], s[30:31] op_sel_hi:[1,1,0]
	s_nop 0
	v_pk_fma_f32 v[164:165], v[162:163], v[164:165], s[48:49] op_sel_hi:[1,1,0]
	s_nop 0
	v_pk_fma_f32 v[164:165], v[162:163], v[164:165], s[50:51] op_sel_hi:[1,1,0]
	s_nop 0
	v_pk_fma_f32 v[162:163], v[162:163], v[164:165], s[52:53] op_sel_hi:[1,1,0]
	s_nop 0
	v_pk_fma_f32 v[160:161], v[160:161], v[162:163], 0.5 op_sel_hi:[1,1,0]
	s_nop 0
	v_pk_mul_f32 v[168:169], v[158:159], v[160:161]
	v_med3_f32 v158, v156, -4.0, 4.0
	v_med3_f32 v159, v157, -4.0, 4.0
	v_pk_mul_f32 v[160:161], v[158:159], v[158:159]
	s_nop 0
	v_pk_fma_f32 v[160:161], v[160:161], s[72:73], -1.0 op_sel_hi:[1,0,0]
	s_nop 0
	v_pk_fma_f32 v[162:163], v[160:161], s[74:75], v[154:155] op_sel_hi:[1,0,0]
	s_nop 0
	v_pk_fma_f32 v[162:163], v[160:161], v[162:163], s[0:1] op_sel_hi:[1,1,0]
	s_nop 0
	v_pk_fma_f32 v[162:163], v[160:161], v[162:163], s[2:3] op_sel_hi:[1,1,0]
	s_nop 0
	v_pk_fma_f32 v[162:163], v[160:161], v[162:163], s[28:29] op_sel_hi:[1,1,0]
	s_nop 0
	v_pk_fma_f32 v[162:163], v[160:161], v[162:163], s[30:31] op_sel_hi:[1,1,0]
	s_nop 0
	v_pk_fma_f32 v[162:163], v[160:161], v[162:163], s[48:49] op_sel_hi:[1,1,0]
	s_nop 0
	v_pk_fma_f32 v[162:163], v[160:161], v[162:163], s[50:51] op_sel_hi:[1,1,0]
	s_nop 0
	v_pk_fma_f32 v[160:161], v[160:161], v[162:163], s[52:53] op_sel_hi:[1,1,0]
	s_nop 0
	v_pk_fma_f32 v[158:159], v[158:159], v[160:161], 0.5 op_sel_hi:[1,1,0]
	s_nop 0
	v_pk_mul_f32 v[170:171], v[156:157], v[158:159]
	v_pk_mul_f32 v[158:159], v[72:73], v[152:153] op_sel_hi:[1,0]
	v_pk_mul_f32 v[156:157], v[74:75], v[152:153] op_sel_hi:[1,0]
	v_med3_f32 v160, v158, -4.0, 4.0
	v_med3_f32 v161, v159, -4.0, 4.0
	v_pk_mul_f32 v[162:163], v[160:161], v[160:161]
	s_nop 0
	v_pk_fma_f32 v[162:163], v[162:163], s[72:73], -1.0 op_sel_hi:[1,0,0]
	s_nop 0
	v_pk_fma_f32 v[164:165], v[162:163], s[74:75], v[154:155] op_sel_hi:[1,0,0]
	s_nop 0
	v_pk_fma_f32 v[164:165], v[162:163], v[164:165], s[0:1] op_sel_hi:[1,1,0]
	s_nop 0
	v_pk_fma_f32 v[164:165], v[162:163], v[164:165], s[2:3] op_sel_hi:[1,1,0]
	s_nop 0
	v_pk_fma_f32 v[164:165], v[162:163], v[164:165], s[28:29] op_sel_hi:[1,1,0]
	s_nop 0
	v_pk_fma_f32 v[164:165], v[162:163], v[164:165], s[30:31] op_sel_hi:[1,1,0]
	s_nop 0
	v_pk_fma_f32 v[164:165], v[162:163], v[164:165], s[48:49] op_sel_hi:[1,1,0]
	s_nop 0
	v_pk_fma_f32 v[164:165], v[162:163], v[164:165], s[50:51] op_sel_hi:[1,1,0]
	s_nop 0
	v_pk_fma_f32 v[162:163], v[162:163], v[164:165], s[52:53] op_sel_hi:[1,1,0]
	s_nop 0
	v_pk_fma_f32 v[162:163], v[160:161], v[162:163], 0.5 op_sel_hi:[1,1,0]
	v_med3_f32 v160, v156, -4.0, 4.0
	v_med3_f32 v161, v157, -4.0, 4.0
	v_pk_mul_f32 v[164:165], v[160:161], v[160:161]
	v_pk_mul_f32 v[172:173], v[158:159], v[162:163]
	v_pk_fma_f32 v[164:165], v[164:165], s[72:73], -1.0 op_sel_hi:[1,0,0]
	v_pk_fma_f32 v[158:159], v[158:159], v[162:163], v[172:173] op_sel:[0,0,1] op_sel_hi:[1,1,0]
	v_pk_fma_f32 v[166:167], v[164:165], s[74:75], v[154:155] op_sel_hi:[1,0,0]
	s_nop 0
	v_pk_fma_f32 v[166:167], v[164:165], v[166:167], s[0:1] op_sel_hi:[1,1,0]
	s_nop 0
	v_pk_fma_f32 v[166:167], v[164:165], v[166:167], s[2:3] op_sel_hi:[1,1,0]
	s_nop 0
	v_pk_fma_f32 v[166:167], v[164:165], v[166:167], s[28:29] op_sel_hi:[1,1,0]
	s_nop 0
	v_pk_fma_f32 v[166:167], v[164:165], v[166:167], s[30:31] op_sel_hi:[1,1,0]
	s_nop 0
	v_pk_fma_f32 v[166:167], v[164:165], v[166:167], s[48:49] op_sel_hi:[1,1,0]
	s_nop 0
	v_pk_fma_f32 v[166:167], v[164:165], v[166:167], s[50:51] op_sel_hi:[1,1,0]
	s_nop 0
	v_pk_fma_f32 v[164:165], v[164:165], v[166:167], s[52:53] op_sel_hi:[1,1,0]
	v_mov_b32_e32 v166, v169
	v_mov_b32_e32 v167, v171
	v_pk_fma_f32 v[160:161], v[160:161], v[164:165], 0.5 op_sel_hi:[1,1,0]
	v_mov_b32_e32 v164, v168
	v_mov_b32_e32 v165, v170
	v_pk_mul_f32 v[162:163], v[166:167], v[166:167]
	v_pk_mul_f32 v[160:161], v[156:157], v[160:161]
	v_pk_fma_f32 v[162:163], v[164:165], v[164:165], v[162:163]
	v_cvt_pk_bf16_f32 v168, v168, v169
	v_pk_add_f32 v[162:163], v[162:163], v[162:163] op_sel_hi:[0,1]
	v_cvt_pk_bf16_f32 v169, v170, v171
	v_cvt_pk_bf16_f32 v170, v172, v173
	v_cvt_pk_bf16_f32 v171, v160, v161
	v_mul_f32_e32 v162, v172, v172
	global_store_dwordx4 v[150:151], v[168:171], off
	v_pk_add_f32 v[156:157], v[164:165], v[166:167]
	v_pk_fma_f32 v[164:165], v[172:173], v[172:173], v[162:163] op_sel_hi:[1,1,0]
	v_pk_mul_f32 v[168:169], v[76:77], v[152:153] op_sel_hi:[1,0]
	v_pk_mul_f32 v[170:171], v[78:79], v[152:153] op_sel_hi:[1,0]
	v_med3_f32 v172, v168, -4.0, 4.0
	v_med3_f32 v173, v169, -4.0, 4.0
	v_pk_mul_f32 v[180:181], v[172:173], v[172:173]
	v_pk_mul_f32 v[166:167], v[160:161], v[160:161]
	v_pk_fma_f32 v[180:181], v[180:181], s[72:73], -1.0 op_sel_hi:[1,0,0]
	v_pk_add_f32 v[156:157], v[156:157], v[156:157] op_sel:[0,1] op_sel_hi:[1,0]
	v_pk_fma_f32 v[182:183], v[180:181], s[74:75], v[154:155] op_sel_hi:[1,0,0]
	s_nop 0
	v_pk_fma_f32 v[182:183], v[180:181], v[182:183], s[0:1] op_sel_hi:[1,1,0]
	s_nop 0
	v_pk_fma_f32 v[182:183], v[180:181], v[182:183], s[2:3] op_sel_hi:[1,1,0]
	s_nop 0
	v_pk_fma_f32 v[182:183], v[180:181], v[182:183], s[28:29] op_sel_hi:[1,1,0]
	s_nop 0
	v_pk_fma_f32 v[182:183], v[180:181], v[182:183], s[30:31] op_sel_hi:[1,1,0]
	s_nop 0
	v_pk_fma_f32 v[182:183], v[180:181], v[182:183], s[48:49] op_sel_hi:[1,1,0]
	s_nop 0
	v_pk_fma_f32 v[182:183], v[180:181], v[182:183], s[50:51] op_sel_hi:[1,1,0]
	s_nop 0
	v_pk_fma_f32 v[180:181], v[180:181], v[182:183], s[52:53] op_sel_hi:[1,1,0]
	s_nop 0
	v_pk_fma_f32 v[172:173], v[172:173], v[180:181], 0.5 op_sel_hi:[1,1,0]
	s_nop 0
	v_pk_mul_f32 v[168:169], v[168:169], v[172:173]
	v_med3_f32 v172, v170, -4.0, 4.0
	v_med3_f32 v173, v171, -4.0, 4.0
	v_pk_mul_f32 v[180:181], v[172:173], v[172:173]
	s_nop 0
	v_pk_fma_f32 v[180:181], v[180:181], s[72:73], -1.0 op_sel_hi:[1,0,0]
	s_nop 0
	v_pk_fma_f32 v[182:183], v[180:181], s[74:75], v[154:155] op_sel_hi:[1,0,0]
	s_nop 0
	v_pk_fma_f32 v[182:183], v[180:181], v[182:183], s[0:1] op_sel_hi:[1,1,0]
	s_nop 0
	v_pk_fma_f32 v[182:183], v[180:181], v[182:183], s[2:3] op_sel_hi:[1,1,0]
	s_nop 0
	v_pk_fma_f32 v[182:183], v[180:181], v[182:183], s[28:29] op_sel_hi:[1,1,0]
	s_nop 0
	v_pk_fma_f32 v[182:183], v[180:181], v[182:183], s[30:31] op_sel_hi:[1,1,0]
	s_nop 0
	v_pk_fma_f32 v[182:183], v[180:181], v[182:183], s[48:49] op_sel_hi:[1,1,0]
	s_nop 0
	v_pk_fma_f32 v[182:183], v[180:181], v[182:183], s[50:51] op_sel_hi:[1,1,0]
	s_nop 0
	v_pk_fma_f32 v[180:181], v[180:181], v[182:183], s[52:53] op_sel_hi:[1,1,0]
	s_nop 0
	v_pk_fma_f32 v[172:173], v[172:173], v[180:181], 0.5 op_sel_hi:[1,1,0]
	s_nop 0
	v_pk_mul_f32 v[170:171], v[170:171], v[172:173]
	v_pk_mul_f32 v[172:173], v[70:71], v[152:153] op_sel_hi:[1,0]
	v_pk_mul_f32 v[152:153], v[68:69], v[152:153] op_sel_hi:[1,0]
	s_nop 0
	v_med3_f32 v180, v152, -4.0, 4.0
	v_med3_f32 v181, v153, -4.0, 4.0
	v_pk_mul_f32 v[182:183], v[180:181], v[180:181]
	s_nop 0
	v_pk_fma_f32 v[182:183], v[182:183], s[72:73], -1.0 op_sel_hi:[1,0,0]
	s_nop 0
	v_pk_fma_f32 v[184:185], v[182:183], s[74:75], v[154:155] op_sel_hi:[1,0,0]
	s_nop 0
	v_pk_fma_f32 v[184:185], v[182:183], v[184:185], s[0:1] op_sel_hi:[1,1,0]
	s_nop 0
	v_pk_fma_f32 v[184:185], v[182:183], v[184:185], s[2:3] op_sel_hi:[1,1,0]
	s_nop 0
	v_pk_fma_f32 v[184:185], v[182:183], v[184:185], s[28:29] op_sel_hi:[1,1,0]
	s_nop 0
	v_pk_fma_f32 v[184:185], v[182:183], v[184:185], s[30:31] op_sel_hi:[1,1,0]
	s_nop 0
	v_pk_fma_f32 v[184:185], v[182:183], v[184:185], s[48:49] op_sel_hi:[1,1,0]
	s_nop 0
	v_pk_fma_f32 v[184:185], v[182:183], v[184:185], s[50:51] op_sel_hi:[1,1,0]
	s_nop 0
	v_pk_fma_f32 v[182:183], v[182:183], v[184:185], s[52:53] op_sel_hi:[1,1,0]
	v_med3_f32 v184, v172, -4.0, 4.0
	v_med3_f32 v185, v173, -4.0, 4.0
	v_pk_mul_f32 v[186:187], v[184:185], v[184:185]
	v_pk_fma_f32 v[180:181], v[180:181], v[182:183], 0.5 op_sel_hi:[1,1,0]
	v_pk_fma_f32 v[186:187], v[186:187], s[72:73], -1.0 op_sel_hi:[1,0,0]
	v_pk_mul_f32 v[182:183], v[152:153], v[180:181]
	v_pk_fma_f32 v[154:155], v[186:187], s[74:75], v[154:155] op_sel_hi:[1,0,0]
	v_pk_fma_f32 v[180:181], v[152:153], v[180:181], v[182:183] op_sel:[0,0,1] op_sel_hi:[1,1,0]
	v_pk_fma_f32 v[154:155], v[186:187], v[154:155], s[0:1] op_sel_hi:[1,1,0]
	v_mul_f32_e32 v152, v168, v168
	v_pk_fma_f32 v[154:155], v[186:187], v[154:155], s[2:3] op_sel_hi:[1,1,0]
	v_pk_mul_f32 v[190:191], v[182:183], v[182:183]
	v_pk_fma_f32 v[154:155], v[186:187], v[154:155], s[28:29] op_sel_hi:[1,1,0]
	v_mov_b32_e32 v181, v166
	v_pk_fma_f32 v[154:155], v[186:187], v[154:155], s[30:31] op_sel_hi:[1,1,0]
	v_mov_b32_e32 v159, v190
	v_pk_fma_f32 v[154:155], v[186:187], v[154:155], s[48:49] op_sel_hi:[1,1,0]
	v_mov_b32_e32 v157, v191
	v_pk_fma_f32 v[154:155], v[186:187], v[154:155], s[50:51] op_sel_hi:[1,1,0]
	s_nop 0
	v_pk_fma_f32 v[154:155], v[186:187], v[154:155], s[52:53] op_sel_hi:[1,1,0]
	v_pk_fma_f32 v[186:187], v[168:169], v[168:169], v[152:153] op_sel_hi:[1,1,0]
	v_pk_fma_f32 v[154:155], v[184:185], v[154:155], 0.5 op_sel_hi:[1,1,0]
	v_mov_b32_e32 v184, v169
	v_pk_mul_f32 v[172:173], v[172:173], v[154:155]
	v_mov_b32_e32 v154, v168
	v_mov_b32_e32 v155, v170
	v_mov_b32_e32 v185, v171
	v_pk_add_f32 v[154:155], v[154:155], v[184:185]
	v_mul_f32_e32 v152, v170, v170
	v_pk_add_f32 v[184:185], v[154:155], v[154:155] op_sel:[0,1] op_sel_hi:[1,0]
	v_pk_fma_f32 v[188:189], v[170:171], v[170:171], v[152:153] op_sel_hi:[1,1,0]
	v_mul_f32_e32 v152, v172, v172
	v_pk_fma_f32 v[192:193], v[172:173], v[172:173], v[152:153] op_sel_hi:[1,1,0]
	v_cvt_pk_bf16_f32 v152, v168, v169
	v_cvt_pk_bf16_f32 v153, v170, v171
	v_cvt_pk_bf16_f32 v154, v182, v183
	v_cvt_pk_bf16_f32 v155, v172, v173
	v_mov_b32_e32 v185, v167
	v_mov_b32_e32 v164, v172
	v_mov_b32_e32 v162, v173
	global_store_dwordx4 v[150:151], v[152:155], off offset:256
	v_pk_add_f32 v[150:151], v[180:181], v[184:185]
	v_mov_b32_e32 v186, v160
	v_pk_add_f32 v[152:153], v[164:165], v[162:163]
	v_mov_b32_e32 v188, v161
	v_pk_add_f32 v[150:151], v[150:151], v[152:153]
	v_pk_add_f32 v[152:153], v[186:187], v[188:189]
	v_pk_add_f32 v[154:155], v[158:159], v[156:157]
	v_mov_b32_e32 v3, v193
	v_pk_add_f32 v[152:153], v[154:155], v[152:153]
	s_nop 0
	v_pk_add_f32 v[152:153], v[152:153], v[2:3]
	s_nop 0
	v_pk_add_f32 v[150:151], v[150:151], v[152:153]
	ds_bpermute_b32 v152, v179, v150
	ds_bpermute_b32 v153, v179, v151
	s_waitcnt lgkmcnt(0)
	v_pk_add_f32 v[150:151], v[150:151], v[152:153]
	ds_bpermute_b32 v152, v178, v150
	ds_bpermute_b32 v153, v178, v151
	s_and_saveexec_b64 s[0:1], s[4:5]
	s_cbranch_execz .LBB0_460
	v_lshlrev_b64 v[148:149], 8, v[148:149]
	v_lshl_add_u64 v[148:149], s[14:15], 0, v[148:149]
	s_waitcnt lgkmcnt(0)
	v_pk_add_f32 v[150:151], v[150:151], v[152:153]
	v_lshl_add_u64 v[148:149], s[94:95], 3, v[148:149]
	global_store_dwordx2 v[148:149], v[150:151], off
.LBB0_460:
	s_or_b64 exec, exec, s[0:1]
	s_waitcnt lgkmcnt(1)
	s_nop 1
	v_mov_b32_e32 v152, v244
	s_mov_b32 s0, 0xbb7be14b
	v_add_u32_e32 v148, 0x80, v142
	v_ashrrev_i32_e32 v149, 31, v148
	v_lshlrev_b64 v[150:151], 12, v[148:149]
	v_lshl_add_u64 v[150:151], s[12:13], 0, v[150:151]
	v_mov_b32_e32 v147, v2
	v_lshl_add_u64 v[150:151], v[150:151], 0, v[146:147]
	s_waitcnt lgkmcnt(0)
	v_pk_mul_f32 v[158:159], v[64:65], v[152:153] op_sel_hi:[1,0]
	s_nop 0
	v_med3_f32 v160, v158, -4.0, 4.0
	v_med3_f32 v161, v159, -4.0, 4.0
	v_pk_mul_f32 v[154:155], v[160:161], v[160:161]
	v_pk_mul_f32 v[156:157], v[66:67], v[152:153] op_sel_hi:[1,0]
	v_pk_fma_f32 v[162:163], v[154:155], s[72:73], -1.0 op_sel_hi:[1,0,0]
	v_mov_b64_e32 v[154:155], s[0:1]
	v_pk_fma_f32 v[164:165], v[162:163], s[74:75], v[154:155] op_sel_hi:[1,0,0]
	s_mov_b32 s0, 0x3bcff2a2
	v_pk_fma_f32 v[164:165], v[162:163], v[164:165], s[0:1] op_sel_hi:[1,1,0]
	s_nop 0
	v_pk_fma_f32 v[164:165], v[162:163], v[164:165], s[2:3] op_sel_hi:[1,1,0]
	s_nop 0
	v_pk_fma_f32 v[164:165], v[162:163], v[164:165], s[28:29] op_sel_hi:[1,1,0]
	s_nop 0
	v_pk_fma_f32 v[164:165], v[162:163], v[164:165], s[30:31] op_sel_hi:[1,1,0]
	s_nop 0
	v_pk_fma_f32 v[164:165], v[162:163], v[164:165], s[48:49] op_sel_hi:[1,1,0]
	s_nop 0
	v_pk_fma_f32 v[164:165], v[162:163], v[164:165], s[50:51] op_sel_hi:[1,1,0]
	s_nop 0
	v_pk_fma_f32 v[162:163], v[162:163], v[164:165], s[52:53] op_sel_hi:[1,1,0]
	s_nop 0
	v_pk_fma_f32 v[160:161], v[160:161], v[162:163], 0.5 op_sel_hi:[1,1,0]
	s_nop 0
	v_pk_mul_f32 v[168:169], v[158:159], v[160:161]
	v_med3_f32 v158, v156, -4.0, 4.0
	v_med3_f32 v159, v157, -4.0, 4.0
	v_pk_mul_f32 v[160:161], v[158:159], v[158:159]
	s_nop 0
	v_pk_fma_f32 v[160:161], v[160:161], s[72:73], -1.0 op_sel_hi:[1,0,0]
	s_nop 0
	v_pk_fma_f32 v[162:163], v[160:161], s[74:75], v[154:155] op_sel_hi:[1,0,0]
	s_nop 0
	v_pk_fma_f32 v[162:163], v[160:161], v[162:163], s[0:1] op_sel_hi:[1,1,0]
	s_nop 0
	v_pk_fma_f32 v[162:163], v[160:161], v[162:163], s[2:3] op_sel_hi:[1,1,0]
	s_nop 0
	v_pk_fma_f32 v[162:163], v[160:161], v[162:163], s[28:29] op_sel_hi:[1,1,0]
	s_nop 0
	v_pk_fma_f32 v[162:163], v[160:161], v[162:163], s[30:31] op_sel_hi:[1,1,0]
	s_nop 0
	v_pk_fma_f32 v[162:163], v[160:161], v[162:163], s[48:49] op_sel_hi:[1,1,0]
	s_nop 0
	v_pk_fma_f32 v[162:163], v[160:161], v[162:163], s[50:51] op_sel_hi:[1,1,0]
	s_nop 0
	v_pk_fma_f32 v[160:161], v[160:161], v[162:163], s[52:53] op_sel_hi:[1,1,0]
	s_nop 0
	v_pk_fma_f32 v[158:159], v[158:159], v[160:161], 0.5 op_sel_hi:[1,1,0]
	s_nop 0
	v_pk_mul_f32 v[170:171], v[156:157], v[158:159]
	v_pk_mul_f32 v[158:159], v[56:57], v[152:153] op_sel_hi:[1,0]
	v_pk_mul_f32 v[156:157], v[58:59], v[152:153] op_sel_hi:[1,0]
	v_med3_f32 v160, v158, -4.0, 4.0
	v_med3_f32 v161, v159, -4.0, 4.0
	v_pk_mul_f32 v[162:163], v[160:161], v[160:161]
	s_nop 0
	v_pk_fma_f32 v[162:163], v[162:163], s[72:73], -1.0 op_sel_hi:[1,0,0]
	s_nop 0
	v_pk_fma_f32 v[164:165], v[162:163], s[74:75], v[154:155] op_sel_hi:[1,0,0]
	s_nop 0
	v_pk_fma_f32 v[164:165], v[162:163], v[164:165], s[0:1] op_sel_hi:[1,1,0]
	s_nop 0
	v_pk_fma_f32 v[164:165], v[162:163], v[164:165], s[2:3] op_sel_hi:[1,1,0]
	s_nop 0
	v_pk_fma_f32 v[164:165], v[162:163], v[164:165], s[28:29] op_sel_hi:[1,1,0]
	s_nop 0
	v_pk_fma_f32 v[164:165], v[162:163], v[164:165], s[30:31] op_sel_hi:[1,1,0]
	s_nop 0
	v_pk_fma_f32 v[164:165], v[162:163], v[164:165], s[48:49] op_sel_hi:[1,1,0]
	s_nop 0
	v_pk_fma_f32 v[164:165], v[162:163], v[164:165], s[50:51] op_sel_hi:[1,1,0]
	s_nop 0
	v_pk_fma_f32 v[162:163], v[162:163], v[164:165], s[52:53] op_sel_hi:[1,1,0]
	s_nop 0
	v_pk_fma_f32 v[162:163], v[160:161], v[162:163], 0.5 op_sel_hi:[1,1,0]
	v_med3_f32 v160, v156, -4.0, 4.0
	v_med3_f32 v161, v157, -4.0, 4.0
	v_pk_mul_f32 v[164:165], v[160:161], v[160:161]
	v_pk_mul_f32 v[172:173], v[158:159], v[162:163]
	v_pk_fma_f32 v[164:165], v[164:165], s[72:73], -1.0 op_sel_hi:[1,0,0]
	v_pk_fma_f32 v[158:159], v[158:159], v[162:163], v[172:173] op_sel:[0,0,1] op_sel_hi:[1,1,0]
	v_pk_fma_f32 v[166:167], v[164:165], s[74:75], v[154:155] op_sel_hi:[1,0,0]
	s_nop 0
	v_pk_fma_f32 v[166:167], v[164:165], v[166:167], s[0:1] op_sel_hi:[1,1,0]
	s_nop 0
	v_pk_fma_f32 v[166:167], v[164:165], v[166:167], s[2:3] op_sel_hi:[1,1,0]
	s_nop 0
	v_pk_fma_f32 v[166:167], v[164:165], v[166:167], s[28:29] op_sel_hi:[1,1,0]
	s_nop 0
	v_pk_fma_f32 v[166:167], v[164:165], v[166:167], s[30:31] op_sel_hi:[1,1,0]
	s_nop 0
	v_pk_fma_f32 v[166:167], v[164:165], v[166:167], s[48:49] op_sel_hi:[1,1,0]
	s_nop 0
	v_pk_fma_f32 v[166:167], v[164:165], v[166:167], s[50:51] op_sel_hi:[1,1,0]
	s_nop 0
	v_pk_fma_f32 v[164:165], v[164:165], v[166:167], s[52:53] op_sel_hi:[1,1,0]
	v_mov_b32_e32 v166, v169
	v_mov_b32_e32 v167, v171
	v_pk_fma_f32 v[160:161], v[160:161], v[164:165], 0.5 op_sel_hi:[1,1,0]
	v_mov_b32_e32 v164, v168
	v_mov_b32_e32 v165, v170
	v_pk_mul_f32 v[162:163], v[166:167], v[166:167]
	v_pk_mul_f32 v[160:161], v[156:157], v[160:161]
	v_pk_fma_f32 v[162:163], v[164:165], v[164:165], v[162:163]
	v_cvt_pk_bf16_f32 v168, v168, v169
	v_pk_add_f32 v[162:163], v[162:163], v[162:163] op_sel_hi:[0,1]
	v_cvt_pk_bf16_f32 v169, v170, v171
	v_cvt_pk_bf16_f32 v170, v172, v173
	v_cvt_pk_bf16_f32 v171, v160, v161
	v_mul_f32_e32 v162, v172, v172
	global_store_dwordx4 v[150:151], v[168:171], off
	v_pk_add_f32 v[156:157], v[164:165], v[166:167]
	v_pk_fma_f32 v[164:165], v[172:173], v[172:173], v[162:163] op_sel_hi:[1,1,0]
	v_pk_mul_f32 v[170:171], v[60:61], v[152:153] op_sel_hi:[1,0]
	v_pk_mul_f32 v[168:169], v[62:63], v[152:153] op_sel_hi:[1,0]
	v_med3_f32 v172, v170, -4.0, 4.0
	v_med3_f32 v173, v171, -4.0, 4.0
	v_pk_mul_f32 v[180:181], v[172:173], v[172:173]
	v_pk_mul_f32 v[166:167], v[160:161], v[160:161]
	v_pk_fma_f32 v[180:181], v[180:181], s[72:73], -1.0 op_sel_hi:[1,0,0]
	v_pk_add_f32 v[156:157], v[156:157], v[156:157] op_sel:[0,1] op_sel_hi:[1,0]
	v_pk_fma_f32 v[182:183], v[180:181], s[74:75], v[154:155] op_sel_hi:[1,0,0]
	s_nop 0
	v_pk_fma_f32 v[182:183], v[180:181], v[182:183], s[0:1] op_sel_hi:[1,1,0]
	s_nop 0
	v_pk_fma_f32 v[182:183], v[180:181], v[182:183], s[2:3] op_sel_hi:[1,1,0]
	s_nop 0
	v_pk_fma_f32 v[182:183], v[180:181], v[182:183], s[28:29] op_sel_hi:[1,1,0]
	s_nop 0
	v_pk_fma_f32 v[182:183], v[180:181], v[182:183], s[30:31] op_sel_hi:[1,1,0]
	s_nop 0
	v_pk_fma_f32 v[182:183], v[180:181], v[182:183], s[48:49] op_sel_hi:[1,1,0]
	s_nop 0
	v_pk_fma_f32 v[182:183], v[180:181], v[182:183], s[50:51] op_sel_hi:[1,1,0]
	s_nop 0
	v_pk_fma_f32 v[180:181], v[180:181], v[182:183], s[52:53] op_sel_hi:[1,1,0]
	s_nop 0
	v_pk_fma_f32 v[172:173], v[172:173], v[180:181], 0.5 op_sel_hi:[1,1,0]
	s_nop 0
	v_pk_mul_f32 v[170:171], v[170:171], v[172:173]
	v_med3_f32 v172, v168, -4.0, 4.0
	v_med3_f32 v173, v169, -4.0, 4.0
	v_pk_mul_f32 v[180:181], v[172:173], v[172:173]
	s_nop 0
	v_pk_fma_f32 v[180:181], v[180:181], s[72:73], -1.0 op_sel_hi:[1,0,0]
	s_nop 0
	v_pk_fma_f32 v[182:183], v[180:181], s[74:75], v[154:155] op_sel_hi:[1,0,0]
	s_nop 0
	v_pk_fma_f32 v[182:183], v[180:181], v[182:183], s[0:1] op_sel_hi:[1,1,0]
	s_nop 0
	v_pk_fma_f32 v[182:183], v[180:181], v[182:183], s[2:3] op_sel_hi:[1,1,0]
	s_nop 0
	v_pk_fma_f32 v[182:183], v[180:181], v[182:183], s[28:29] op_sel_hi:[1,1,0]
	s_nop 0
	v_pk_fma_f32 v[182:183], v[180:181], v[182:183], s[30:31] op_sel_hi:[1,1,0]
	s_nop 0
	v_pk_fma_f32 v[182:183], v[180:181], v[182:183], s[48:49] op_sel_hi:[1,1,0]
	s_nop 0
	v_pk_fma_f32 v[182:183], v[180:181], v[182:183], s[50:51] op_sel_hi:[1,1,0]
	s_nop 0
	v_pk_fma_f32 v[180:181], v[180:181], v[182:183], s[52:53] op_sel_hi:[1,1,0]
	s_nop 0
	v_pk_fma_f32 v[172:173], v[172:173], v[180:181], 0.5 op_sel_hi:[1,1,0]
	s_nop 0
	v_pk_mul_f32 v[168:169], v[168:169], v[172:173]
	v_pk_mul_f32 v[172:173], v[54:55], v[152:153] op_sel_hi:[1,0]
	v_pk_mul_f32 v[152:153], v[52:53], v[152:153] op_sel_hi:[1,0]
	s_nop 0
	v_med3_f32 v180, v152, -4.0, 4.0
	v_med3_f32 v181, v153, -4.0, 4.0
	v_pk_mul_f32 v[182:183], v[180:181], v[180:181]
	s_nop 0
	v_pk_fma_f32 v[182:183], v[182:183], s[72:73], -1.0 op_sel_hi:[1,0,0]
	s_nop 0
	v_pk_fma_f32 v[184:185], v[182:183], s[74:75], v[154:155] op_sel_hi:[1,0,0]
	s_nop 0
	v_pk_fma_f32 v[184:185], v[182:183], v[184:185], s[0:1] op_sel_hi:[1,1,0]
	s_nop 0
	v_pk_fma_f32 v[184:185], v[182:183], v[184:185], s[2:3] op_sel_hi:[1,1,0]
	s_nop 0
	v_pk_fma_f32 v[184:185], v[182:183], v[184:185], s[28:29] op_sel_hi:[1,1,0]
	s_nop 0
	v_pk_fma_f32 v[184:185], v[182:183], v[184:185], s[30:31] op_sel_hi:[1,1,0]
	s_nop 0
	v_pk_fma_f32 v[184:185], v[182:183], v[184:185], s[48:49] op_sel_hi:[1,1,0]
	s_nop 0
	v_pk_fma_f32 v[184:185], v[182:183], v[184:185], s[50:51] op_sel_hi:[1,1,0]
	s_nop 0
	v_pk_fma_f32 v[182:183], v[182:183], v[184:185], s[52:53] op_sel_hi:[1,1,0]
	v_med3_f32 v184, v172, -4.0, 4.0
	v_med3_f32 v185, v173, -4.0, 4.0
	v_pk_mul_f32 v[186:187], v[184:185], v[184:185]
	v_pk_fma_f32 v[180:181], v[180:181], v[182:183], 0.5 op_sel_hi:[1,1,0]
	v_pk_fma_f32 v[186:187], v[186:187], s[72:73], -1.0 op_sel_hi:[1,0,0]
	v_pk_mul_f32 v[182:183], v[152:153], v[180:181]
	v_pk_fma_f32 v[154:155], v[186:187], s[74:75], v[154:155] op_sel_hi:[1,0,0]
	v_pk_fma_f32 v[180:181], v[152:153], v[180:181], v[182:183] op_sel:[0,0,1] op_sel_hi:[1,1,0]
	v_pk_fma_f32 v[154:155], v[186:187], v[154:155], s[0:1] op_sel_hi:[1,1,0]
	v_mul_f32_e32 v152, v170, v170
	v_pk_fma_f32 v[154:155], v[186:187], v[154:155], s[2:3] op_sel_hi:[1,1,0]
	v_pk_mul_f32 v[190:191], v[182:183], v[182:183]
	v_pk_fma_f32 v[154:155], v[186:187], v[154:155], s[28:29] op_sel_hi:[1,1,0]
	v_mov_b32_e32 v181, v166
	v_pk_fma_f32 v[154:155], v[186:187], v[154:155], s[30:31] op_sel_hi:[1,1,0]
	v_mov_b32_e32 v159, v190
	v_pk_fma_f32 v[154:155], v[186:187], v[154:155], s[48:49] op_sel_hi:[1,1,0]
	v_mov_b32_e32 v157, v191
	v_pk_fma_f32 v[154:155], v[186:187], v[154:155], s[50:51] op_sel_hi:[1,1,0]
	s_nop 0
	v_pk_fma_f32 v[154:155], v[186:187], v[154:155], s[52:53] op_sel_hi:[1,1,0]
	v_pk_fma_f32 v[186:187], v[170:171], v[170:171], v[152:153] op_sel_hi:[1,1,0]
	v_pk_fma_f32 v[154:155], v[184:185], v[154:155], 0.5 op_sel_hi:[1,1,0]
	v_mov_b32_e32 v184, v171
	v_pk_mul_f32 v[172:173], v[172:173], v[154:155]
	v_mov_b32_e32 v154, v170
	v_mov_b32_e32 v155, v168
	v_mov_b32_e32 v185, v169
	v_pk_add_f32 v[154:155], v[154:155], v[184:185]
	v_mul_f32_e32 v152, v168, v168
	v_pk_add_f32 v[184:185], v[154:155], v[154:155] op_sel:[0,1] op_sel_hi:[1,0]
	v_pk_fma_f32 v[188:189], v[168:169], v[168:169], v[152:153] op_sel_hi:[1,1,0]
	v_mul_f32_e32 v152, v172, v172
	v_pk_fma_f32 v[192:193], v[172:173], v[172:173], v[152:153] op_sel_hi:[1,1,0]
	v_cvt_pk_bf16_f32 v152, v170, v171
	v_cvt_pk_bf16_f32 v153, v168, v169
	v_cvt_pk_bf16_f32 v154, v182, v183
	v_cvt_pk_bf16_f32 v155, v172, v173
	v_mov_b32_e32 v185, v167
	v_mov_b32_e32 v164, v172
	v_mov_b32_e32 v162, v173
	global_store_dwordx4 v[150:151], v[152:155], off offset:256
	v_pk_add_f32 v[150:151], v[180:181], v[184:185]
	v_mov_b32_e32 v186, v160
	v_pk_add_f32 v[152:153], v[164:165], v[162:163]
	v_mov_b32_e32 v188, v161
	v_pk_add_f32 v[150:151], v[150:151], v[152:153]
	v_pk_add_f32 v[152:153], v[186:187], v[188:189]
	v_pk_add_f32 v[154:155], v[158:159], v[156:157]
	v_mov_b32_e32 v3, v193
	v_pk_add_f32 v[152:153], v[154:155], v[152:153]
	s_nop 0
	v_pk_add_f32 v[152:153], v[152:153], v[2:3]
	s_nop 0
	v_pk_add_f32 v[150:151], v[150:151], v[152:153]
	ds_bpermute_b32 v152, v179, v150
	ds_bpermute_b32 v153, v179, v151
	s_waitcnt lgkmcnt(0)
	v_pk_add_f32 v[150:151], v[150:151], v[152:153]
	ds_bpermute_b32 v152, v178, v150
	ds_bpermute_b32 v153, v178, v151
	s_and_saveexec_b64 s[0:1], s[4:5]
	s_cbranch_execz .LBB0_462
	v_lshlrev_b64 v[148:149], 8, v[148:149]
	v_lshl_add_u64 v[148:149], s[14:15], 0, v[148:149]
	s_waitcnt lgkmcnt(0)
	v_pk_add_f32 v[150:151], v[150:151], v[152:153]
	v_lshl_add_u64 v[148:149], s[94:95], 3, v[148:149]
	global_store_dwordx2 v[148:149], v[150:151], off
.LBB0_462:
	s_or_b64 exec, exec, s[0:1]
	s_waitcnt lgkmcnt(1)
	s_nop 1
	v_mov_b32_e32 v152, v246
	s_mov_b32 s0, 0xbb7be14b
	v_add_u32_e32 v148, 0x90, v142
	v_ashrrev_i32_e32 v149, 31, v148
	v_lshlrev_b64 v[150:151], 12, v[148:149]
	v_lshl_add_u64 v[150:151], s[12:13], 0, v[150:151]
	v_lshl_add_u64 v[150:151], v[150:151], 0, v[146:147]
	s_waitcnt lgkmcnt(0)
	v_pk_mul_f32 v[158:159], v[48:49], v[152:153] op_sel_hi:[1,0]
	s_nop 0
	v_med3_f32 v160, v158, -4.0, 4.0
	v_med3_f32 v161, v159, -4.0, 4.0
	v_pk_mul_f32 v[154:155], v[160:161], v[160:161]
	v_pk_mul_f32 v[156:157], v[50:51], v[152:153] op_sel_hi:[1,0]
	v_pk_fma_f32 v[162:163], v[154:155], s[72:73], -1.0 op_sel_hi:[1,0,0]
	v_mov_b64_e32 v[154:155], s[0:1]
	v_pk_fma_f32 v[164:165], v[162:163], s[74:75], v[154:155] op_sel_hi:[1,0,0]
	s_mov_b32 s0, 0x3bcff2a2
	v_pk_fma_f32 v[164:165], v[162:163], v[164:165], s[0:1] op_sel_hi:[1,1,0]
	s_nop 0
	v_pk_fma_f32 v[164:165], v[162:163], v[164:165], s[2:3] op_sel_hi:[1,1,0]
	s_nop 0
	v_pk_fma_f32 v[164:165], v[162:163], v[164:165], s[28:29] op_sel_hi:[1,1,0]
	s_nop 0
	v_pk_fma_f32 v[164:165], v[162:163], v[164:165], s[30:31] op_sel_hi:[1,1,0]
	s_nop 0
	v_pk_fma_f32 v[164:165], v[162:163], v[164:165], s[48:49] op_sel_hi:[1,1,0]
	s_nop 0
	v_pk_fma_f32 v[164:165], v[162:163], v[164:165], s[50:51] op_sel_hi:[1,1,0]
	s_nop 0
	v_pk_fma_f32 v[162:163], v[162:163], v[164:165], s[52:53] op_sel_hi:[1,1,0]
	s_nop 0
	v_pk_fma_f32 v[160:161], v[160:161], v[162:163], 0.5 op_sel_hi:[1,1,0]
	s_nop 0
	v_pk_mul_f32 v[168:169], v[158:159], v[160:161]
	v_med3_f32 v158, v156, -4.0, 4.0
	v_med3_f32 v159, v157, -4.0, 4.0
	v_pk_mul_f32 v[160:161], v[158:159], v[158:159]
	s_nop 0
	v_pk_fma_f32 v[160:161], v[160:161], s[72:73], -1.0 op_sel_hi:[1,0,0]
	s_nop 0
	v_pk_fma_f32 v[162:163], v[160:161], s[74:75], v[154:155] op_sel_hi:[1,0,0]
	s_nop 0
	v_pk_fma_f32 v[162:163], v[160:161], v[162:163], s[0:1] op_sel_hi:[1,1,0]
	s_nop 0
	v_pk_fma_f32 v[162:163], v[160:161], v[162:163], s[2:3] op_sel_hi:[1,1,0]
	s_nop 0
	v_pk_fma_f32 v[162:163], v[160:161], v[162:163], s[28:29] op_sel_hi:[1,1,0]
	s_nop 0
	v_pk_fma_f32 v[162:163], v[160:161], v[162:163], s[30:31] op_sel_hi:[1,1,0]
	s_nop 0
	v_pk_fma_f32 v[162:163], v[160:161], v[162:163], s[48:49] op_sel_hi:[1,1,0]
	s_nop 0
	v_pk_fma_f32 v[162:163], v[160:161], v[162:163], s[50:51] op_sel_hi:[1,1,0]
	s_nop 0
	v_pk_fma_f32 v[160:161], v[160:161], v[162:163], s[52:53] op_sel_hi:[1,1,0]
	s_nop 0
	v_pk_fma_f32 v[158:159], v[158:159], v[160:161], 0.5 op_sel_hi:[1,1,0]
	s_nop 0
	v_pk_mul_f32 v[170:171], v[156:157], v[158:159]
	v_pk_mul_f32 v[158:159], v[40:41], v[152:153] op_sel_hi:[1,0]
	v_pk_mul_f32 v[156:157], v[42:43], v[152:153] op_sel_hi:[1,0]
	v_med3_f32 v160, v158, -4.0, 4.0
	v_med3_f32 v161, v159, -4.0, 4.0
	v_pk_mul_f32 v[162:163], v[160:161], v[160:161]
	s_nop 0
	v_pk_fma_f32 v[162:163], v[162:163], s[72:73], -1.0 op_sel_hi:[1,0,0]
	s_nop 0
	v_pk_fma_f32 v[164:165], v[162:163], s[74:75], v[154:155] op_sel_hi:[1,0,0]
	s_nop 0
	v_pk_fma_f32 v[164:165], v[162:163], v[164:165], s[0:1] op_sel_hi:[1,1,0]
	s_nop 0
	v_pk_fma_f32 v[164:165], v[162:163], v[164:165], s[2:3] op_sel_hi:[1,1,0]
	s_nop 0
	v_pk_fma_f32 v[164:165], v[162:163], v[164:165], s[28:29] op_sel_hi:[1,1,0]
	s_nop 0
	v_pk_fma_f32 v[164:165], v[162:163], v[164:165], s[30:31] op_sel_hi:[1,1,0]
	s_nop 0
	v_pk_fma_f32 v[164:165], v[162:163], v[164:165], s[48:49] op_sel_hi:[1,1,0]
	s_nop 0
	v_pk_fma_f32 v[164:165], v[162:163], v[164:165], s[50:51] op_sel_hi:[1,1,0]
	s_nop 0
	v_pk_fma_f32 v[162:163], v[162:163], v[164:165], s[52:53] op_sel_hi:[1,1,0]
	s_nop 0
	v_pk_fma_f32 v[162:163], v[160:161], v[162:163], 0.5 op_sel_hi:[1,1,0]
	v_med3_f32 v160, v156, -4.0, 4.0
	v_med3_f32 v161, v157, -4.0, 4.0
	v_pk_mul_f32 v[164:165], v[160:161], v[160:161]
	v_pk_mul_f32 v[172:173], v[158:159], v[162:163]
	v_pk_fma_f32 v[164:165], v[164:165], s[72:73], -1.0 op_sel_hi:[1,0,0]
	v_pk_fma_f32 v[158:159], v[158:159], v[162:163], v[172:173] op_sel:[0,0,1] op_sel_hi:[1,1,0]
	v_pk_fma_f32 v[166:167], v[164:165], s[74:75], v[154:155] op_sel_hi:[1,0,0]
	s_nop 0
	v_pk_fma_f32 v[166:167], v[164:165], v[166:167], s[0:1] op_sel_hi:[1,1,0]
	s_nop 0
	v_pk_fma_f32 v[166:167], v[164:165], v[166:167], s[2:3] op_sel_hi:[1,1,0]
	s_nop 0
	v_pk_fma_f32 v[166:167], v[164:165], v[166:167], s[28:29] op_sel_hi:[1,1,0]
	s_nop 0
	v_pk_fma_f32 v[166:167], v[164:165], v[166:167], s[30:31] op_sel_hi:[1,1,0]
	s_nop 0
	v_pk_fma_f32 v[166:167], v[164:165], v[166:167], s[48:49] op_sel_hi:[1,1,0]
	s_nop 0
	v_pk_fma_f32 v[166:167], v[164:165], v[166:167], s[50:51] op_sel_hi:[1,1,0]
	s_nop 0
	v_pk_fma_f32 v[164:165], v[164:165], v[166:167], s[52:53] op_sel_hi:[1,1,0]
	v_mov_b32_e32 v166, v169
	v_mov_b32_e32 v167, v171
	v_pk_fma_f32 v[160:161], v[160:161], v[164:165], 0.5 op_sel_hi:[1,1,0]
	v_mov_b32_e32 v164, v168
	v_mov_b32_e32 v165, v170
	v_pk_mul_f32 v[162:163], v[166:167], v[166:167]
	v_pk_mul_f32 v[160:161], v[156:157], v[160:161]
	v_pk_fma_f32 v[162:163], v[164:165], v[164:165], v[162:163]
	v_cvt_pk_bf16_f32 v168, v168, v169
	v_pk_add_f32 v[162:163], v[162:163], v[162:163] op_sel_hi:[0,1]
	v_cvt_pk_bf16_f32 v169, v170, v171
	v_cvt_pk_bf16_f32 v170, v172, v173
	v_cvt_pk_bf16_f32 v171, v160, v161
	v_mul_f32_e32 v162, v172, v172
	global_store_dwordx4 v[150:151], v[168:171], off
	v_pk_add_f32 v[156:157], v[164:165], v[166:167]
	v_pk_fma_f32 v[164:165], v[172:173], v[172:173], v[162:163] op_sel_hi:[1,1,0]
	v_pk_mul_f32 v[170:171], v[44:45], v[152:153] op_sel_hi:[1,0]
	v_pk_mul_f32 v[168:169], v[46:47], v[152:153] op_sel_hi:[1,0]
	v_med3_f32 v172, v170, -4.0, 4.0
	v_med3_f32 v173, v171, -4.0, 4.0
	v_pk_mul_f32 v[180:181], v[172:173], v[172:173]
	v_pk_mul_f32 v[166:167], v[160:161], v[160:161]
	v_pk_fma_f32 v[180:181], v[180:181], s[72:73], -1.0 op_sel_hi:[1,0,0]
	v_pk_add_f32 v[156:157], v[156:157], v[156:157] op_sel:[0,1] op_sel_hi:[1,0]
	v_pk_fma_f32 v[182:183], v[180:181], s[74:75], v[154:155] op_sel_hi:[1,0,0]
	s_nop 0
	v_pk_fma_f32 v[182:183], v[180:181], v[182:183], s[0:1] op_sel_hi:[1,1,0]
	s_nop 0
	v_pk_fma_f32 v[182:183], v[180:181], v[182:183], s[2:3] op_sel_hi:[1,1,0]
	s_nop 0
	v_pk_fma_f32 v[182:183], v[180:181], v[182:183], s[28:29] op_sel_hi:[1,1,0]
	s_nop 0
	v_pk_fma_f32 v[182:183], v[180:181], v[182:183], s[30:31] op_sel_hi:[1,1,0]
	s_nop 0
	v_pk_fma_f32 v[182:183], v[180:181], v[182:183], s[48:49] op_sel_hi:[1,1,0]
	s_nop 0
	v_pk_fma_f32 v[182:183], v[180:181], v[182:183], s[50:51] op_sel_hi:[1,1,0]
	s_nop 0
	v_pk_fma_f32 v[180:181], v[180:181], v[182:183], s[52:53] op_sel_hi:[1,1,0]
	s_nop 0
	v_pk_fma_f32 v[172:173], v[172:173], v[180:181], 0.5 op_sel_hi:[1,1,0]
	s_nop 0
	v_pk_mul_f32 v[170:171], v[170:171], v[172:173]
	v_med3_f32 v172, v168, -4.0, 4.0
	v_med3_f32 v173, v169, -4.0, 4.0
	v_pk_mul_f32 v[180:181], v[172:173], v[172:173]
	s_nop 0
	v_pk_fma_f32 v[180:181], v[180:181], s[72:73], -1.0 op_sel_hi:[1,0,0]
	s_nop 0
	v_pk_fma_f32 v[182:183], v[180:181], s[74:75], v[154:155] op_sel_hi:[1,0,0]
	s_nop 0
	v_pk_fma_f32 v[182:183], v[180:181], v[182:183], s[0:1] op_sel_hi:[1,1,0]
	s_nop 0
	v_pk_fma_f32 v[182:183], v[180:181], v[182:183], s[2:3] op_sel_hi:[1,1,0]
	s_nop 0
	v_pk_fma_f32 v[182:183], v[180:181], v[182:183], s[28:29] op_sel_hi:[1,1,0]
	s_nop 0
	v_pk_fma_f32 v[182:183], v[180:181], v[182:183], s[30:31] op_sel_hi:[1,1,0]
	s_nop 0
	v_pk_fma_f32 v[182:183], v[180:181], v[182:183], s[48:49] op_sel_hi:[1,1,0]
	s_nop 0
	v_pk_fma_f32 v[182:183], v[180:181], v[182:183], s[50:51] op_sel_hi:[1,1,0]
	s_nop 0
	v_pk_fma_f32 v[180:181], v[180:181], v[182:183], s[52:53] op_sel_hi:[1,1,0]
	s_nop 0
	v_pk_fma_f32 v[172:173], v[172:173], v[180:181], 0.5 op_sel_hi:[1,1,0]
	s_nop 0
	v_pk_mul_f32 v[168:169], v[168:169], v[172:173]
	v_pk_mul_f32 v[172:173], v[38:39], v[152:153] op_sel_hi:[1,0]
	v_pk_mul_f32 v[152:153], v[36:37], v[152:153] op_sel_hi:[1,0]
	s_nop 0
	v_med3_f32 v180, v152, -4.0, 4.0
	v_med3_f32 v181, v153, -4.0, 4.0
	v_pk_mul_f32 v[182:183], v[180:181], v[180:181]
	s_nop 0
	v_pk_fma_f32 v[182:183], v[182:183], s[72:73], -1.0 op_sel_hi:[1,0,0]
	s_nop 0
	v_pk_fma_f32 v[184:185], v[182:183], s[74:75], v[154:155] op_sel_hi:[1,0,0]
	s_nop 0
	v_pk_fma_f32 v[184:185], v[182:183], v[184:185], s[0:1] op_sel_hi:[1,1,0]
	s_nop 0
	v_pk_fma_f32 v[184:185], v[182:183], v[184:185], s[2:3] op_sel_hi:[1,1,0]
	s_nop 0
	v_pk_fma_f32 v[184:185], v[182:183], v[184:185], s[28:29] op_sel_hi:[1,1,0]
	s_nop 0
	v_pk_fma_f32 v[184:185], v[182:183], v[184:185], s[30:31] op_sel_hi:[1,1,0]
	s_nop 0
	v_pk_fma_f32 v[184:185], v[182:183], v[184:185], s[48:49] op_sel_hi:[1,1,0]
	s_nop 0
	v_pk_fma_f32 v[184:185], v[182:183], v[184:185], s[50:51] op_sel_hi:[1,1,0]
	s_nop 0
	v_pk_fma_f32 v[182:183], v[182:183], v[184:185], s[52:53] op_sel_hi:[1,1,0]
	v_med3_f32 v184, v172, -4.0, 4.0
	v_med3_f32 v185, v173, -4.0, 4.0
	v_pk_mul_f32 v[186:187], v[184:185], v[184:185]
	v_pk_fma_f32 v[180:181], v[180:181], v[182:183], 0.5 op_sel_hi:[1,1,0]
	v_pk_fma_f32 v[186:187], v[186:187], s[72:73], -1.0 op_sel_hi:[1,0,0]
	v_pk_mul_f32 v[182:183], v[152:153], v[180:181]
	v_pk_fma_f32 v[154:155], v[186:187], s[74:75], v[154:155] op_sel_hi:[1,0,0]
	v_pk_fma_f32 v[180:181], v[152:153], v[180:181], v[182:183] op_sel:[0,0,1] op_sel_hi:[1,1,0]
	v_pk_fma_f32 v[154:155], v[186:187], v[154:155], s[0:1] op_sel_hi:[1,1,0]
	v_mul_f32_e32 v152, v170, v170
	v_pk_fma_f32 v[154:155], v[186:187], v[154:155], s[2:3] op_sel_hi:[1,1,0]
	v_pk_mul_f32 v[190:191], v[182:183], v[182:183]
	v_pk_fma_f32 v[154:155], v[186:187], v[154:155], s[28:29] op_sel_hi:[1,1,0]
	v_mov_b32_e32 v181, v166
	v_pk_fma_f32 v[154:155], v[186:187], v[154:155], s[30:31] op_sel_hi:[1,1,0]
	v_mov_b32_e32 v159, v190
	v_pk_fma_f32 v[154:155], v[186:187], v[154:155], s[48:49] op_sel_hi:[1,1,0]
	v_mov_b32_e32 v157, v191
	v_pk_fma_f32 v[154:155], v[186:187], v[154:155], s[50:51] op_sel_hi:[1,1,0]
	s_nop 0
	v_pk_fma_f32 v[154:155], v[186:187], v[154:155], s[52:53] op_sel_hi:[1,1,0]
	v_pk_fma_f32 v[186:187], v[170:171], v[170:171], v[152:153] op_sel_hi:[1,1,0]
	v_pk_fma_f32 v[154:155], v[184:185], v[154:155], 0.5 op_sel_hi:[1,1,0]
	v_mov_b32_e32 v184, v171
	v_pk_mul_f32 v[172:173], v[172:173], v[154:155]
	v_mov_b32_e32 v154, v170
	v_mov_b32_e32 v155, v168
	v_mov_b32_e32 v185, v169
	v_pk_add_f32 v[154:155], v[154:155], v[184:185]
	v_mul_f32_e32 v152, v168, v168
	v_pk_add_f32 v[184:185], v[154:155], v[154:155] op_sel:[0,1] op_sel_hi:[1,0]
	v_pk_fma_f32 v[188:189], v[168:169], v[168:169], v[152:153] op_sel_hi:[1,1,0]
	v_mul_f32_e32 v152, v172, v172
	v_pk_fma_f32 v[192:193], v[172:173], v[172:173], v[152:153] op_sel_hi:[1,1,0]
	v_cvt_pk_bf16_f32 v152, v170, v171
	v_cvt_pk_bf16_f32 v153, v168, v169
	v_cvt_pk_bf16_f32 v154, v182, v183
	v_cvt_pk_bf16_f32 v155, v172, v173
	v_mov_b32_e32 v185, v167
	v_mov_b32_e32 v164, v172
	v_mov_b32_e32 v162, v173
	global_store_dwordx4 v[150:151], v[152:155], off offset:256
	v_pk_add_f32 v[150:151], v[180:181], v[184:185]
	v_mov_b32_e32 v186, v160
	v_pk_add_f32 v[152:153], v[164:165], v[162:163]
	v_mov_b32_e32 v188, v161
	v_pk_add_f32 v[150:151], v[150:151], v[152:153]
	v_pk_add_f32 v[152:153], v[186:187], v[188:189]
	v_pk_add_f32 v[154:155], v[158:159], v[156:157]
	v_mov_b32_e32 v3, v193
	v_pk_add_f32 v[152:153], v[154:155], v[152:153]
	s_nop 0
	v_pk_add_f32 v[152:153], v[152:153], v[2:3]
	s_nop 0
	v_pk_add_f32 v[150:151], v[150:151], v[152:153]
	ds_bpermute_b32 v152, v179, v150
	ds_bpermute_b32 v153, v179, v151
	s_waitcnt lgkmcnt(0)
	v_pk_add_f32 v[150:151], v[150:151], v[152:153]
	ds_bpermute_b32 v152, v178, v150
	ds_bpermute_b32 v153, v178, v151
	s_and_saveexec_b64 s[0:1], s[4:5]
	s_cbranch_execz .LBB0_464
	v_lshlrev_b64 v[148:149], 8, v[148:149]
	v_lshl_add_u64 v[148:149], s[14:15], 0, v[148:149]
	s_waitcnt lgkmcnt(0)
	v_pk_add_f32 v[150:151], v[150:151], v[152:153]
	v_lshl_add_u64 v[148:149], s[94:95], 3, v[148:149]
	global_store_dwordx2 v[148:149], v[150:151], off
.LBB0_464:
	s_or_b64 exec, exec, s[0:1]
	s_waitcnt lgkmcnt(1)
	s_nop 1
	v_mov_b32_e32 v152, v248
	s_mov_b32 s0, 0xbb7be14b
	v_add_u32_e32 v148, 0xa0, v142
	v_ashrrev_i32_e32 v149, 31, v148
	v_lshlrev_b64 v[150:151], 12, v[148:149]
	v_lshl_add_u64 v[150:151], s[12:13], 0, v[150:151]
	v_mov_b32_e32 v147, v2
	v_lshl_add_u64 v[150:151], v[150:151], 0, v[146:147]
	s_waitcnt lgkmcnt(0)
	v_pk_mul_f32 v[158:159], v[32:33], v[152:153] op_sel_hi:[1,0]
	s_nop 0
	v_med3_f32 v160, v158, -4.0, 4.0
	v_med3_f32 v161, v159, -4.0, 4.0
	v_pk_mul_f32 v[154:155], v[160:161], v[160:161]
	v_pk_mul_f32 v[156:157], v[34:35], v[152:153] op_sel_hi:[1,0]
	v_pk_fma_f32 v[162:163], v[154:155], s[72:73], -1.0 op_sel_hi:[1,0,0]
	v_mov_b64_e32 v[154:155], s[0:1]
	v_pk_fma_f32 v[164:165], v[162:163], s[74:75], v[154:155] op_sel_hi:[1,0,0]
	s_mov_b32 s0, 0x3bcff2a2
	v_pk_fma_f32 v[164:165], v[162:163], v[164:165], s[0:1] op_sel_hi:[1,1,0]
	s_nop 0
	v_pk_fma_f32 v[164:165], v[162:163], v[164:165], s[2:3] op_sel_hi:[1,1,0]
	s_nop 0
	v_pk_fma_f32 v[164:165], v[162:163], v[164:165], s[28:29] op_sel_hi:[1,1,0]
	s_nop 0
	v_pk_fma_f32 v[164:165], v[162:163], v[164:165], s[30:31] op_sel_hi:[1,1,0]
	s_nop 0
	v_pk_fma_f32 v[164:165], v[162:163], v[164:165], s[48:49] op_sel_hi:[1,1,0]
	s_nop 0
	v_pk_fma_f32 v[164:165], v[162:163], v[164:165], s[50:51] op_sel_hi:[1,1,0]
	s_nop 0
	v_pk_fma_f32 v[162:163], v[162:163], v[164:165], s[52:53] op_sel_hi:[1,1,0]
	s_nop 0
	v_pk_fma_f32 v[160:161], v[160:161], v[162:163], 0.5 op_sel_hi:[1,1,0]
	s_nop 0
	v_pk_mul_f32 v[168:169], v[158:159], v[160:161]
	v_med3_f32 v158, v156, -4.0, 4.0
	v_med3_f32 v159, v157, -4.0, 4.0
	v_pk_mul_f32 v[160:161], v[158:159], v[158:159]
	s_nop 0
	v_pk_fma_f32 v[160:161], v[160:161], s[72:73], -1.0 op_sel_hi:[1,0,0]
	s_nop 0
	v_pk_fma_f32 v[162:163], v[160:161], s[74:75], v[154:155] op_sel_hi:[1,0,0]
	s_nop 0
	v_pk_fma_f32 v[162:163], v[160:161], v[162:163], s[0:1] op_sel_hi:[1,1,0]
	s_nop 0
	v_pk_fma_f32 v[162:163], v[160:161], v[162:163], s[2:3] op_sel_hi:[1,1,0]
	s_nop 0
	v_pk_fma_f32 v[162:163], v[160:161], v[162:163], s[28:29] op_sel_hi:[1,1,0]
	s_nop 0
	v_pk_fma_f32 v[162:163], v[160:161], v[162:163], s[30:31] op_sel_hi:[1,1,0]
	s_nop 0
	v_pk_fma_f32 v[162:163], v[160:161], v[162:163], s[48:49] op_sel_hi:[1,1,0]
	s_nop 0
	v_pk_fma_f32 v[162:163], v[160:161], v[162:163], s[50:51] op_sel_hi:[1,1,0]
	s_nop 0
	v_pk_fma_f32 v[160:161], v[160:161], v[162:163], s[52:53] op_sel_hi:[1,1,0]
	s_nop 0
	v_pk_fma_f32 v[158:159], v[158:159], v[160:161], 0.5 op_sel_hi:[1,1,0]
	s_nop 0
	v_pk_mul_f32 v[170:171], v[156:157], v[158:159]
	v_pk_mul_f32 v[158:159], v[24:25], v[152:153] op_sel_hi:[1,0]
	v_pk_mul_f32 v[156:157], v[26:27], v[152:153] op_sel_hi:[1,0]
	v_med3_f32 v160, v158, -4.0, 4.0
	v_med3_f32 v161, v159, -4.0, 4.0
	v_pk_mul_f32 v[162:163], v[160:161], v[160:161]
	s_nop 0
	v_pk_fma_f32 v[162:163], v[162:163], s[72:73], -1.0 op_sel_hi:[1,0,0]
	s_nop 0
	v_pk_fma_f32 v[164:165], v[162:163], s[74:75], v[154:155] op_sel_hi:[1,0,0]
	s_nop 0
	v_pk_fma_f32 v[164:165], v[162:163], v[164:165], s[0:1] op_sel_hi:[1,1,0]
	s_nop 0
	v_pk_fma_f32 v[164:165], v[162:163], v[164:165], s[2:3] op_sel_hi:[1,1,0]
	s_nop 0
	v_pk_fma_f32 v[164:165], v[162:163], v[164:165], s[28:29] op_sel_hi:[1,1,0]
	s_nop 0
	v_pk_fma_f32 v[164:165], v[162:163], v[164:165], s[30:31] op_sel_hi:[1,1,0]
	s_nop 0
	v_pk_fma_f32 v[164:165], v[162:163], v[164:165], s[48:49] op_sel_hi:[1,1,0]
	s_nop 0
	v_pk_fma_f32 v[164:165], v[162:163], v[164:165], s[50:51] op_sel_hi:[1,1,0]
	s_nop 0
	v_pk_fma_f32 v[162:163], v[162:163], v[164:165], s[52:53] op_sel_hi:[1,1,0]
	s_nop 0
	v_pk_fma_f32 v[162:163], v[160:161], v[162:163], 0.5 op_sel_hi:[1,1,0]
	v_med3_f32 v160, v156, -4.0, 4.0
	v_med3_f32 v161, v157, -4.0, 4.0
	v_pk_mul_f32 v[164:165], v[160:161], v[160:161]
	v_pk_mul_f32 v[172:173], v[158:159], v[162:163]
	v_pk_fma_f32 v[164:165], v[164:165], s[72:73], -1.0 op_sel_hi:[1,0,0]
	v_pk_fma_f32 v[158:159], v[158:159], v[162:163], v[172:173] op_sel:[0,0,1] op_sel_hi:[1,1,0]
	v_pk_fma_f32 v[166:167], v[164:165], s[74:75], v[154:155] op_sel_hi:[1,0,0]
	s_nop 0
	v_pk_fma_f32 v[166:167], v[164:165], v[166:167], s[0:1] op_sel_hi:[1,1,0]
	s_nop 0
	v_pk_fma_f32 v[166:167], v[164:165], v[166:167], s[2:3] op_sel_hi:[1,1,0]
	s_nop 0
	v_pk_fma_f32 v[166:167], v[164:165], v[166:167], s[28:29] op_sel_hi:[1,1,0]
	s_nop 0
	v_pk_fma_f32 v[166:167], v[164:165], v[166:167], s[30:31] op_sel_hi:[1,1,0]
	s_nop 0
	v_pk_fma_f32 v[166:167], v[164:165], v[166:167], s[48:49] op_sel_hi:[1,1,0]
	s_nop 0
	v_pk_fma_f32 v[166:167], v[164:165], v[166:167], s[50:51] op_sel_hi:[1,1,0]
	s_nop 0
	v_pk_fma_f32 v[164:165], v[164:165], v[166:167], s[52:53] op_sel_hi:[1,1,0]
	v_mov_b32_e32 v166, v169
	v_mov_b32_e32 v167, v171
	v_pk_fma_f32 v[160:161], v[160:161], v[164:165], 0.5 op_sel_hi:[1,1,0]
	v_mov_b32_e32 v164, v168
	v_mov_b32_e32 v165, v170
	v_pk_mul_f32 v[162:163], v[166:167], v[166:167]
	v_pk_mul_f32 v[160:161], v[156:157], v[160:161]
	v_pk_fma_f32 v[162:163], v[164:165], v[164:165], v[162:163]
	v_cvt_pk_bf16_f32 v168, v168, v169
	v_pk_add_f32 v[162:163], v[162:163], v[162:163] op_sel_hi:[0,1]
	v_cvt_pk_bf16_f32 v169, v170, v171
	v_cvt_pk_bf16_f32 v170, v172, v173
	v_cvt_pk_bf16_f32 v171, v160, v161
	v_mul_f32_e32 v162, v172, v172
	global_store_dwordx4 v[150:151], v[168:171], off
	v_pk_add_f32 v[156:157], v[164:165], v[166:167]
	v_pk_fma_f32 v[164:165], v[172:173], v[172:173], v[162:163] op_sel_hi:[1,1,0]
	v_pk_mul_f32 v[170:171], v[28:29], v[152:153] op_sel_hi:[1,0]
	v_pk_mul_f32 v[168:169], v[30:31], v[152:153] op_sel_hi:[1,0]
	v_med3_f32 v172, v170, -4.0, 4.0
	v_med3_f32 v173, v171, -4.0, 4.0
	v_pk_mul_f32 v[180:181], v[172:173], v[172:173]
	v_pk_mul_f32 v[166:167], v[160:161], v[160:161]
	v_pk_fma_f32 v[180:181], v[180:181], s[72:73], -1.0 op_sel_hi:[1,0,0]
	v_pk_add_f32 v[156:157], v[156:157], v[156:157] op_sel:[0,1] op_sel_hi:[1,0]
	v_pk_fma_f32 v[182:183], v[180:181], s[74:75], v[154:155] op_sel_hi:[1,0,0]
	s_nop 0
	v_pk_fma_f32 v[182:183], v[180:181], v[182:183], s[0:1] op_sel_hi:[1,1,0]
	s_nop 0
	v_pk_fma_f32 v[182:183], v[180:181], v[182:183], s[2:3] op_sel_hi:[1,1,0]
	s_nop 0
	v_pk_fma_f32 v[182:183], v[180:181], v[182:183], s[28:29] op_sel_hi:[1,1,0]
	s_nop 0
	v_pk_fma_f32 v[182:183], v[180:181], v[182:183], s[30:31] op_sel_hi:[1,1,0]
	s_nop 0
	v_pk_fma_f32 v[182:183], v[180:181], v[182:183], s[48:49] op_sel_hi:[1,1,0]
	s_nop 0
	v_pk_fma_f32 v[182:183], v[180:181], v[182:183], s[50:51] op_sel_hi:[1,1,0]
	s_nop 0
	v_pk_fma_f32 v[180:181], v[180:181], v[182:183], s[52:53] op_sel_hi:[1,1,0]
	s_nop 0
	v_pk_fma_f32 v[172:173], v[172:173], v[180:181], 0.5 op_sel_hi:[1,1,0]
	s_nop 0
	v_pk_mul_f32 v[170:171], v[170:171], v[172:173]
	v_med3_f32 v172, v168, -4.0, 4.0
	v_med3_f32 v173, v169, -4.0, 4.0
	v_pk_mul_f32 v[180:181], v[172:173], v[172:173]
	s_nop 0
	v_pk_fma_f32 v[180:181], v[180:181], s[72:73], -1.0 op_sel_hi:[1,0,0]
	s_nop 0
	v_pk_fma_f32 v[182:183], v[180:181], s[74:75], v[154:155] op_sel_hi:[1,0,0]
	s_nop 0
	v_pk_fma_f32 v[182:183], v[180:181], v[182:183], s[0:1] op_sel_hi:[1,1,0]
	s_nop 0
	v_pk_fma_f32 v[182:183], v[180:181], v[182:183], s[2:3] op_sel_hi:[1,1,0]
	s_nop 0
	v_pk_fma_f32 v[182:183], v[180:181], v[182:183], s[28:29] op_sel_hi:[1,1,0]
	s_nop 0
	v_pk_fma_f32 v[182:183], v[180:181], v[182:183], s[30:31] op_sel_hi:[1,1,0]
	s_nop 0
	v_pk_fma_f32 v[182:183], v[180:181], v[182:183], s[48:49] op_sel_hi:[1,1,0]
	s_nop 0
	v_pk_fma_f32 v[182:183], v[180:181], v[182:183], s[50:51] op_sel_hi:[1,1,0]
	s_nop 0
	v_pk_fma_f32 v[180:181], v[180:181], v[182:183], s[52:53] op_sel_hi:[1,1,0]
	s_nop 0
	v_pk_fma_f32 v[172:173], v[172:173], v[180:181], 0.5 op_sel_hi:[1,1,0]
	s_nop 0
	v_pk_mul_f32 v[168:169], v[168:169], v[172:173]
	v_pk_mul_f32 v[172:173], v[22:23], v[152:153] op_sel_hi:[1,0]
	v_pk_mul_f32 v[152:153], v[20:21], v[152:153] op_sel_hi:[1,0]
	s_nop 0
	v_med3_f32 v180, v152, -4.0, 4.0
	v_med3_f32 v181, v153, -4.0, 4.0
	v_pk_mul_f32 v[182:183], v[180:181], v[180:181]
	s_nop 0
	v_pk_fma_f32 v[182:183], v[182:183], s[72:73], -1.0 op_sel_hi:[1,0,0]
	s_nop 0
	v_pk_fma_f32 v[184:185], v[182:183], s[74:75], v[154:155] op_sel_hi:[1,0,0]
	s_nop 0
	v_pk_fma_f32 v[184:185], v[182:183], v[184:185], s[0:1] op_sel_hi:[1,1,0]
	s_nop 0
	v_pk_fma_f32 v[184:185], v[182:183], v[184:185], s[2:3] op_sel_hi:[1,1,0]
	s_nop 0
	v_pk_fma_f32 v[184:185], v[182:183], v[184:185], s[28:29] op_sel_hi:[1,1,0]
	s_nop 0
	v_pk_fma_f32 v[184:185], v[182:183], v[184:185], s[30:31] op_sel_hi:[1,1,0]
	s_nop 0
	v_pk_fma_f32 v[184:185], v[182:183], v[184:185], s[48:49] op_sel_hi:[1,1,0]
	s_nop 0
	v_pk_fma_f32 v[184:185], v[182:183], v[184:185], s[50:51] op_sel_hi:[1,1,0]
	s_nop 0
	v_pk_fma_f32 v[182:183], v[182:183], v[184:185], s[52:53] op_sel_hi:[1,1,0]
	v_med3_f32 v184, v172, -4.0, 4.0
	v_med3_f32 v185, v173, -4.0, 4.0
	v_pk_mul_f32 v[186:187], v[184:185], v[184:185]
	v_pk_fma_f32 v[180:181], v[180:181], v[182:183], 0.5 op_sel_hi:[1,1,0]
	v_pk_fma_f32 v[186:187], v[186:187], s[72:73], -1.0 op_sel_hi:[1,0,0]
	v_pk_mul_f32 v[182:183], v[152:153], v[180:181]
	v_pk_fma_f32 v[154:155], v[186:187], s[74:75], v[154:155] op_sel_hi:[1,0,0]
	v_pk_fma_f32 v[180:181], v[152:153], v[180:181], v[182:183] op_sel:[0,0,1] op_sel_hi:[1,1,0]
	v_pk_fma_f32 v[154:155], v[186:187], v[154:155], s[0:1] op_sel_hi:[1,1,0]
	v_mul_f32_e32 v152, v170, v170
	v_pk_fma_f32 v[154:155], v[186:187], v[154:155], s[2:3] op_sel_hi:[1,1,0]
	v_pk_mul_f32 v[190:191], v[182:183], v[182:183]
	v_pk_fma_f32 v[154:155], v[186:187], v[154:155], s[28:29] op_sel_hi:[1,1,0]
	v_mov_b32_e32 v181, v166
	v_pk_fma_f32 v[154:155], v[186:187], v[154:155], s[30:31] op_sel_hi:[1,1,0]
	v_mov_b32_e32 v159, v190
	v_pk_fma_f32 v[154:155], v[186:187], v[154:155], s[48:49] op_sel_hi:[1,1,0]
	v_mov_b32_e32 v157, v191
	v_pk_fma_f32 v[154:155], v[186:187], v[154:155], s[50:51] op_sel_hi:[1,1,0]
	s_nop 0
	v_pk_fma_f32 v[154:155], v[186:187], v[154:155], s[52:53] op_sel_hi:[1,1,0]
	v_pk_fma_f32 v[186:187], v[170:171], v[170:171], v[152:153] op_sel_hi:[1,1,0]
	v_pk_fma_f32 v[154:155], v[184:185], v[154:155], 0.5 op_sel_hi:[1,1,0]
	v_mov_b32_e32 v184, v171
	v_pk_mul_f32 v[172:173], v[172:173], v[154:155]
	v_mov_b32_e32 v154, v170
	v_mov_b32_e32 v155, v168
	v_mov_b32_e32 v185, v169
	v_pk_add_f32 v[154:155], v[154:155], v[184:185]
	v_mul_f32_e32 v152, v168, v168
	v_pk_add_f32 v[184:185], v[154:155], v[154:155] op_sel:[0,1] op_sel_hi:[1,0]
	v_pk_fma_f32 v[188:189], v[168:169], v[168:169], v[152:153] op_sel_hi:[1,1,0]
	v_mul_f32_e32 v152, v172, v172
	v_pk_fma_f32 v[192:193], v[172:173], v[172:173], v[152:153] op_sel_hi:[1,1,0]
	v_cvt_pk_bf16_f32 v152, v170, v171
	v_cvt_pk_bf16_f32 v153, v168, v169
	v_cvt_pk_bf16_f32 v154, v182, v183
	v_cvt_pk_bf16_f32 v155, v172, v173
	v_mov_b32_e32 v185, v167
	v_mov_b32_e32 v164, v172
	v_mov_b32_e32 v162, v173
	global_store_dwordx4 v[150:151], v[152:155], off offset:256
	v_pk_add_f32 v[150:151], v[180:181], v[184:185]
	v_mov_b32_e32 v186, v160
	v_pk_add_f32 v[152:153], v[164:165], v[162:163]
	v_mov_b32_e32 v188, v161
	v_pk_add_f32 v[150:151], v[150:151], v[152:153]
	v_pk_add_f32 v[152:153], v[186:187], v[188:189]
	v_pk_add_f32 v[154:155], v[158:159], v[156:157]
	v_mov_b32_e32 v3, v193
	v_pk_add_f32 v[152:153], v[154:155], v[152:153]
	s_nop 0
	v_pk_add_f32 v[152:153], v[152:153], v[2:3]
	s_nop 0
	v_pk_add_f32 v[150:151], v[150:151], v[152:153]
	ds_bpermute_b32 v152, v179, v150
	ds_bpermute_b32 v153, v179, v151
	s_waitcnt lgkmcnt(0)
	v_pk_add_f32 v[150:151], v[150:151], v[152:153]
	ds_bpermute_b32 v152, v178, v150
	ds_bpermute_b32 v153, v178, v151
	s_and_saveexec_b64 s[0:1], s[4:5]
	s_cbranch_execz .LBB0_466
	v_lshlrev_b64 v[148:149], 8, v[148:149]
	v_lshl_add_u64 v[148:149], s[14:15], 0, v[148:149]
	s_waitcnt lgkmcnt(0)
	v_pk_add_f32 v[150:151], v[150:151], v[152:153]
	v_lshl_add_u64 v[148:149], s[94:95], 3, v[148:149]
	global_store_dwordx2 v[148:149], v[150:151], off
.LBB0_466:
	s_or_b64 exec, exec, s[0:1]
	s_nop 1
	v_mov_b32_e32 v150, v250
	v_add_u32_e32 v148, 0xb0, v142
	v_ashrrev_i32_e32 v149, 31, v148
	v_lshlrev_b64 v[144:145], 12, v[148:149]
	v_lshl_add_u64 v[144:145], s[12:13], 0, v[144:145]
	v_lshl_add_u64 v[144:145], v[144:145], 0, v[146:147]
	s_mov_b32 s0, 0xbb7be14b
	v_pk_mul_f32 v[154:155], v[16:17], v[150:151] op_sel_hi:[1,0]
	s_nop 0
	v_med3_f32 v156, v154, -4.0, 4.0
	v_med3_f32 v157, v155, -4.0, 4.0
	v_pk_mul_f32 v[146:147], v[156:157], v[156:157]
	s_waitcnt lgkmcnt(0)
	v_pk_mul_f32 v[152:153], v[18:19], v[150:151] op_sel_hi:[1,0]
	v_pk_fma_f32 v[158:159], v[146:147], s[72:73], -1.0 op_sel_hi:[1,0,0]
	v_mov_b64_e32 v[146:147], s[0:1]
	v_pk_fma_f32 v[160:161], v[158:159], s[74:75], v[146:147] op_sel_hi:[1,0,0]
	s_mov_b32 s0, 0x3bcff2a2
	v_pk_fma_f32 v[160:161], v[158:159], v[160:161], s[0:1] op_sel_hi:[1,1,0]
	s_nop 0
	v_pk_fma_f32 v[160:161], v[158:159], v[160:161], s[2:3] op_sel_hi:[1,1,0]
	s_nop 0
	v_pk_fma_f32 v[160:161], v[158:159], v[160:161], s[28:29] op_sel_hi:[1,1,0]
	s_nop 0
	v_pk_fma_f32 v[160:161], v[158:159], v[160:161], s[30:31] op_sel_hi:[1,1,0]
	s_nop 0
	v_pk_fma_f32 v[160:161], v[158:159], v[160:161], s[48:49] op_sel_hi:[1,1,0]
	s_nop 0
	v_pk_fma_f32 v[160:161], v[158:159], v[160:161], s[50:51] op_sel_hi:[1,1,0]
	s_nop 0
	v_pk_fma_f32 v[158:159], v[158:159], v[160:161], s[52:53] op_sel_hi:[1,1,0]
	s_nop 0
	v_pk_fma_f32 v[156:157], v[156:157], v[158:159], 0.5 op_sel_hi:[1,1,0]
	s_nop 0
	v_pk_mul_f32 v[164:165], v[154:155], v[156:157]
	v_med3_f32 v154, v152, -4.0, 4.0
	v_med3_f32 v155, v153, -4.0, 4.0
	v_pk_mul_f32 v[156:157], v[154:155], v[154:155]
	s_nop 0
	v_pk_fma_f32 v[156:157], v[156:157], s[72:73], -1.0 op_sel_hi:[1,0,0]
	s_nop 0
	v_pk_fma_f32 v[158:159], v[156:157], s[74:75], v[146:147] op_sel_hi:[1,0,0]
	s_nop 0
	v_pk_fma_f32 v[158:159], v[156:157], v[158:159], s[0:1] op_sel_hi:[1,1,0]
	s_nop 0
	v_pk_fma_f32 v[158:159], v[156:157], v[158:159], s[2:3] op_sel_hi:[1,1,0]
	s_nop 0
	v_pk_fma_f32 v[158:159], v[156:157], v[158:159], s[28:29] op_sel_hi:[1,1,0]
	s_nop 0
	v_pk_fma_f32 v[158:159], v[156:157], v[158:159], s[30:31] op_sel_hi:[1,1,0]
	s_nop 0
	v_pk_fma_f32 v[158:159], v[156:157], v[158:159], s[48:49] op_sel_hi:[1,1,0]
	s_nop 0
	v_pk_fma_f32 v[158:159], v[156:157], v[158:159], s[50:51] op_sel_hi:[1,1,0]
	s_nop 0
	v_pk_fma_f32 v[156:157], v[156:157], v[158:159], s[52:53] op_sel_hi:[1,1,0]
	s_nop 0
	v_pk_fma_f32 v[154:155], v[154:155], v[156:157], 0.5 op_sel_hi:[1,1,0]
	s_nop 0
	v_pk_mul_f32 v[166:167], v[152:153], v[154:155]
	v_pk_mul_f32 v[154:155], v[8:9], v[150:151] op_sel_hi:[1,0]
	v_pk_mul_f32 v[152:153], v[10:11], v[150:151] op_sel_hi:[1,0]
	v_med3_f32 v156, v154, -4.0, 4.0
	v_med3_f32 v157, v155, -4.0, 4.0
	v_pk_mul_f32 v[158:159], v[156:157], v[156:157]
	s_nop 0
	v_pk_fma_f32 v[158:159], v[158:159], s[72:73], -1.0 op_sel_hi:[1,0,0]
	s_nop 0
	v_pk_fma_f32 v[160:161], v[158:159], s[74:75], v[146:147] op_sel_hi:[1,0,0]
	s_nop 0
	v_pk_fma_f32 v[160:161], v[158:159], v[160:161], s[0:1] op_sel_hi:[1,1,0]
	s_nop 0
	v_pk_fma_f32 v[160:161], v[158:159], v[160:161], s[2:3] op_sel_hi:[1,1,0]
	s_nop 0
	v_pk_fma_f32 v[160:161], v[158:159], v[160:161], s[28:29] op_sel_hi:[1,1,0]
	s_nop 0
	v_pk_fma_f32 v[160:161], v[158:159], v[160:161], s[30:31] op_sel_hi:[1,1,0]
	s_nop 0
	v_pk_fma_f32 v[160:161], v[158:159], v[160:161], s[48:49] op_sel_hi:[1,1,0]
	s_nop 0
	v_pk_fma_f32 v[160:161], v[158:159], v[160:161], s[50:51] op_sel_hi:[1,1,0]
	s_nop 0
	v_pk_fma_f32 v[158:159], v[158:159], v[160:161], s[52:53] op_sel_hi:[1,1,0]
	s_nop 0
	v_pk_fma_f32 v[158:159], v[156:157], v[158:159], 0.5 op_sel_hi:[1,1,0]
	v_med3_f32 v156, v152, -4.0, 4.0
	v_med3_f32 v157, v153, -4.0, 4.0
	v_pk_mul_f32 v[160:161], v[156:157], v[156:157]
	v_pk_mul_f32 v[168:169], v[154:155], v[158:159]
	v_pk_fma_f32 v[160:161], v[160:161], s[72:73], -1.0 op_sel_hi:[1,0,0]
	v_pk_fma_f32 v[154:155], v[154:155], v[158:159], v[168:169] op_sel:[0,0,1] op_sel_hi:[1,1,0]
	v_pk_fma_f32 v[162:163], v[160:161], s[74:75], v[146:147] op_sel_hi:[1,0,0]
	s_nop 0
	v_pk_fma_f32 v[162:163], v[160:161], v[162:163], s[0:1] op_sel_hi:[1,1,0]
	s_nop 0
	v_pk_fma_f32 v[162:163], v[160:161], v[162:163], s[2:3] op_sel_hi:[1,1,0]
	s_nop 0
	v_pk_fma_f32 v[162:163], v[160:161], v[162:163], s[28:29] op_sel_hi:[1,1,0]
	s_nop 0
	v_pk_fma_f32 v[162:163], v[160:161], v[162:163], s[30:31] op_sel_hi:[1,1,0]
	s_nop 0
	v_pk_fma_f32 v[162:163], v[160:161], v[162:163], s[48:49] op_sel_hi:[1,1,0]
	s_nop 0
	v_pk_fma_f32 v[162:163], v[160:161], v[162:163], s[50:51] op_sel_hi:[1,1,0]
	s_nop 0
	v_pk_fma_f32 v[160:161], v[160:161], v[162:163], s[52:53] op_sel_hi:[1,1,0]
	v_mov_b32_e32 v162, v165
	v_mov_b32_e32 v163, v167
	v_pk_fma_f32 v[156:157], v[156:157], v[160:161], 0.5 op_sel_hi:[1,1,0]
	v_mov_b32_e32 v160, v164
	v_mov_b32_e32 v161, v166
	v_pk_mul_f32 v[158:159], v[162:163], v[162:163]
	v_pk_mul_f32 v[156:157], v[152:153], v[156:157]
	v_pk_fma_f32 v[158:159], v[160:161], v[160:161], v[158:159]
	v_cvt_pk_bf16_f32 v164, v164, v165
	v_pk_add_f32 v[158:159], v[158:159], v[158:159] op_sel_hi:[0,1]
	v_cvt_pk_bf16_f32 v165, v166, v167
	v_cvt_pk_bf16_f32 v166, v168, v169
	v_cvt_pk_bf16_f32 v167, v156, v157
	v_mul_f32_e32 v158, v168, v168
	global_store_dwordx4 v[144:145], v[164:167], off
	v_pk_add_f32 v[152:153], v[160:161], v[162:163]
	v_pk_fma_f32 v[160:161], v[168:169], v[168:169], v[158:159] op_sel_hi:[1,1,0]
	v_pk_mul_f32 v[166:167], v[12:13], v[150:151] op_sel_hi:[1,0]
	v_pk_mul_f32 v[164:165], v[14:15], v[150:151] op_sel_hi:[1,0]
	v_med3_f32 v168, v166, -4.0, 4.0
	v_med3_f32 v169, v167, -4.0, 4.0
	v_pk_mul_f32 v[170:171], v[168:169], v[168:169]
	v_pk_mul_f32 v[162:163], v[156:157], v[156:157]
	v_pk_fma_f32 v[170:171], v[170:171], s[72:73], -1.0 op_sel_hi:[1,0,0]
	v_pk_add_f32 v[152:153], v[152:153], v[152:153] op_sel:[0,1] op_sel_hi:[1,0]
	v_pk_fma_f32 v[172:173], v[170:171], s[74:75], v[146:147] op_sel_hi:[1,0,0]
	s_nop 0
	v_pk_fma_f32 v[172:173], v[170:171], v[172:173], s[0:1] op_sel_hi:[1,1,0]
	s_nop 0
	v_pk_fma_f32 v[172:173], v[170:171], v[172:173], s[2:3] op_sel_hi:[1,1,0]
	s_nop 0
	v_pk_fma_f32 v[172:173], v[170:171], v[172:173], s[28:29] op_sel_hi:[1,1,0]
	s_nop 0
	v_pk_fma_f32 v[172:173], v[170:171], v[172:173], s[30:31] op_sel_hi:[1,1,0]
	s_nop 0
	v_pk_fma_f32 v[172:173], v[170:171], v[172:173], s[48:49] op_sel_hi:[1,1,0]
	s_nop 0
	v_pk_fma_f32 v[172:173], v[170:171], v[172:173], s[50:51] op_sel_hi:[1,1,0]
	s_nop 0
	v_pk_fma_f32 v[170:171], v[170:171], v[172:173], s[52:53] op_sel_hi:[1,1,0]
	s_nop 0
	v_pk_fma_f32 v[168:169], v[168:169], v[170:171], 0.5 op_sel_hi:[1,1,0]
	s_nop 0
	v_pk_mul_f32 v[166:167], v[166:167], v[168:169]
	v_med3_f32 v168, v164, -4.0, 4.0
	v_med3_f32 v169, v165, -4.0, 4.0
	v_pk_mul_f32 v[170:171], v[168:169], v[168:169]
	v_mul_f32_e32 v158, v166, v166
	v_pk_fma_f32 v[170:171], v[170:171], s[72:73], -1.0 op_sel_hi:[1,0,0]
	s_nop 0
	v_pk_fma_f32 v[172:173], v[170:171], s[74:75], v[146:147] op_sel_hi:[1,0,0]
	s_nop 0
	v_pk_fma_f32 v[172:173], v[170:171], v[172:173], s[0:1] op_sel_hi:[1,1,0]
	s_nop 0
	v_pk_fma_f32 v[172:173], v[170:171], v[172:173], s[2:3] op_sel_hi:[1,1,0]
	s_nop 0
	v_pk_fma_f32 v[172:173], v[170:171], v[172:173], s[28:29] op_sel_hi:[1,1,0]
	s_nop 0
	v_pk_fma_f32 v[172:173], v[170:171], v[172:173], s[30:31] op_sel_hi:[1,1,0]
	s_nop 0
	v_pk_fma_f32 v[172:173], v[170:171], v[172:173], s[48:49] op_sel_hi:[1,1,0]
	s_nop 0
	v_pk_fma_f32 v[172:173], v[170:171], v[172:173], s[50:51] op_sel_hi:[1,1,0]
	s_nop 0
	v_pk_fma_f32 v[170:171], v[170:171], v[172:173], s[52:53] op_sel_hi:[1,1,0]
	s_nop 0
	v_pk_fma_f32 v[168:169], v[168:169], v[170:171], 0.5 op_sel_hi:[1,1,0]
	s_nop 0
	v_pk_mul_f32 v[168:169], v[164:165], v[168:169]
	v_pk_mul_f32 v[164:165], v[6:7], v[150:151] op_sel_hi:[1,0]
	v_pk_mul_f32 v[150:151], v[4:5], v[150:151] op_sel_hi:[1,0]
	s_nop 0
	v_med3_f32 v170, v150, -4.0, 4.0
	v_med3_f32 v171, v151, -4.0, 4.0
	v_pk_mul_f32 v[172:173], v[170:171], v[170:171]
	s_nop 0
	v_pk_fma_f32 v[172:173], v[172:173], s[72:73], -1.0 op_sel_hi:[1,0,0]
	s_nop 0
	v_pk_fma_f32 v[180:181], v[172:173], s[74:75], v[146:147] op_sel_hi:[1,0,0]
	s_nop 0
	v_pk_fma_f32 v[180:181], v[172:173], v[180:181], s[0:1] op_sel_hi:[1,1,0]
	s_nop 0
	v_pk_fma_f32 v[180:181], v[172:173], v[180:181], s[2:3] op_sel_hi:[1,1,0]
	s_nop 0
	v_pk_fma_f32 v[180:181], v[172:173], v[180:181], s[28:29] op_sel_hi:[1,1,0]
	s_nop 0
	v_pk_fma_f32 v[180:181], v[172:173], v[180:181], s[30:31] op_sel_hi:[1,1,0]
	s_nop 0
	v_pk_fma_f32 v[180:181], v[172:173], v[180:181], s[48:49] op_sel_hi:[1,1,0]
	s_nop 0
	v_pk_fma_f32 v[180:181], v[172:173], v[180:181], s[50:51] op_sel_hi:[1,1,0]
	s_nop 0
	v_pk_fma_f32 v[172:173], v[172:173], v[180:181], s[52:53] op_sel_hi:[1,1,0]
	v_med3_f32 v180, v164, -4.0, 4.0
	v_med3_f32 v181, v165, -4.0, 4.0
	v_pk_mul_f32 v[182:183], v[180:181], v[180:181]
	v_pk_fma_f32 v[170:171], v[170:171], v[172:173], 0.5 op_sel_hi:[1,1,0]
	v_pk_fma_f32 v[182:183], v[182:183], s[72:73], -1.0 op_sel_hi:[1,0,0]
	v_pk_mul_f32 v[172:173], v[150:151], v[170:171]
	v_pk_fma_f32 v[146:147], v[182:183], s[74:75], v[146:147] op_sel_hi:[1,0,0]
	v_pk_fma_f32 v[150:151], v[150:151], v[170:171], v[172:173] op_sel:[0,0,1] op_sel_hi:[1,1,0]
	v_pk_fma_f32 v[146:147], v[182:183], v[146:147], s[0:1] op_sel_hi:[1,1,0]
	v_pk_fma_f32 v[170:171], v[166:167], v[166:167], v[158:159] op_sel_hi:[1,1,0]
	v_pk_fma_f32 v[146:147], v[182:183], v[146:147], s[2:3] op_sel_hi:[1,1,0]
	v_mul_f32_e32 v158, v168, v168
	v_pk_fma_f32 v[146:147], v[182:183], v[146:147], s[28:29] op_sel_hi:[1,1,0]
	v_pk_mul_f32 v[184:185], v[172:173], v[172:173]
	v_pk_fma_f32 v[146:147], v[182:183], v[146:147], s[30:31] op_sel_hi:[1,1,0]
	v_mov_b32_e32 v151, v162
	v_pk_fma_f32 v[146:147], v[182:183], v[146:147], s[48:49] op_sel_hi:[1,1,0]
	v_mov_b32_e32 v170, v156
	v_pk_fma_f32 v[146:147], v[182:183], v[146:147], s[50:51] op_sel_hi:[1,1,0]
	v_mov_b32_e32 v155, v184
	v_pk_fma_f32 v[146:147], v[182:183], v[146:147], s[52:53] op_sel_hi:[1,1,0]
	v_pk_fma_f32 v[182:183], v[168:169], v[168:169], v[158:159] op_sel_hi:[1,1,0]
	v_pk_fma_f32 v[146:147], v[180:181], v[146:147], 0.5 op_sel_hi:[1,1,0]
	v_mov_b32_e32 v180, v167
	v_pk_mul_f32 v[146:147], v[164:165], v[146:147]
	v_mov_b32_e32 v164, v166
	v_mov_b32_e32 v165, v168
	v_mov_b32_e32 v181, v169
	v_pk_add_f32 v[164:165], v[164:165], v[180:181]
	v_mul_f32_e32 v158, v146, v146
	v_pk_add_f32 v[180:181], v[164:165], v[164:165] op_sel:[0,1] op_sel_hi:[1,0]
	v_pk_fma_f32 v[186:187], v[146:147], v[146:147], v[158:159] op_sel_hi:[1,1,0]
	v_cvt_pk_bf16_f32 v164, v166, v167
	v_cvt_pk_bf16_f32 v165, v168, v169
	v_cvt_pk_bf16_f32 v166, v172, v173
	v_cvt_pk_bf16_f32 v167, v146, v147
	v_mov_b32_e32 v181, v163
	v_mov_b32_e32 v160, v146
	v_mov_b32_e32 v158, v147
	global_store_dwordx4 v[144:145], v[164:167], off offset:256
	v_pk_add_f32 v[144:145], v[150:151], v[180:181]
	v_pk_add_f32 v[146:147], v[160:161], v[158:159]
	v_mov_b32_e32 v182, v157
	v_mov_b32_e32 v153, v185
	v_pk_add_f32 v[144:145], v[144:145], v[146:147]
	v_pk_add_f32 v[146:147], v[170:171], v[182:183]
	v_pk_add_f32 v[150:151], v[154:155], v[152:153]
	v_mov_b32_e32 v3, v187
	v_pk_add_f32 v[146:147], v[150:151], v[146:147]
	s_nop 0
	v_pk_add_f32 v[146:147], v[146:147], v[2:3]
	s_nop 0
	v_pk_add_f32 v[144:145], v[144:145], v[146:147]
	ds_bpermute_b32 v146, v179, v144
	ds_bpermute_b32 v147, v179, v145
	s_waitcnt lgkmcnt(0)
	v_pk_add_f32 v[144:145], v[144:145], v[146:147]
	ds_bpermute_b32 v146, v178, v144
	ds_bpermute_b32 v147, v178, v145
	s_and_saveexec_b64 s[0:1], s[4:5]
	s_cbranch_execz .LBB0_468
	v_lshlrev_b64 v[148:149], 8, v[148:149]
	s_waitcnt lgkmcnt(0)
	v_pk_add_f32 v[144:145], v[144:145], v[146:147]
	v_lshl_add_u64 v[146:147], s[14:15], 0, v[148:149]
	v_lshl_add_u64 v[146:147], s[94:95], 3, v[146:147]
	global_store_dwordx2 v[146:147], v[144:145], off

.LBB0_469:
	s_mov_b32 s0, 0xbb7be14b
	s_mov_b32 s2, 0x3bcff2a2
	s_mov_b32 s28, 0xbc40d0ac
	s_mov_b32 s30, 0x3cb76c34
	s_mov_b32 s48, 0xbd17b858
	s_mov_b32 s50, 0x3d6537d1
	s_mov_b32 s52, 0xbdacab04
	s_mov_b32 s54, 0x3e342bfa
	v_mov_b32_e32 v198, s0
	v_lshl_or_b32 v146, s47, 7, v176
	v_lshlrev_b32_e32 v145, 12, v142
	v_lshl_add_u32 v182, v146, 1, v145
	v_add_u32_e32 v183, 0x10000, v182
	v_add_u32_e32 v184, 0x20000, v182
	v_add_u32_e32 v185, 0x30000, v182
	v_add_u32_e32 v186, 0x80000, v182
	v_add_u32_e32 v187, 0x90000, v182
	v_add_u32_e32 v188, 0xa0000, v182
	v_add_u32_e32 v189, 0xb0000, v182
	s_waitcnt vmcnt(0)
	v_pk_mul_f32 v[128:129], v[128:129], v[236:237] op_sel_hi:[1,0]
	v_pk_mul_f32 v[130:131], v[130:131], v[236:237] op_sel_hi:[1,0]
	v_pk_mul_f32 v[120:121], v[120:121], v[236:237] op_sel_hi:[1,0]
	v_pk_mul_f32 v[122:123], v[122:123], v[236:237] op_sel_hi:[1,0]
	v_pk_mul_f32 v[124:125], v[124:125], v[236:237] op_sel_hi:[1,0]
	v_pk_mul_f32 v[126:127], v[126:127], v[236:237] op_sel_hi:[1,0]
	v_pk_mul_f32 v[116:117], v[116:117], v[236:237] op_sel_hi:[1,0]
	v_pk_mul_f32 v[118:119], v[118:119], v[236:237] op_sel_hi:[1,0]
	v_med3_f32 v158, v128, -4.0, 4.0
	v_med3_f32 v164, v130, -4.0, 4.0
	v_mul_f32_e32 v170, 0xbfb8aa3b, v124
	v_med3_f32 v159, v129, -4.0, 4.0
	v_med3_f32 v165, v131, -4.0, 4.0
	v_mul_f32_e32 v171, 0xbfb8aa3b, v125
	v_pk_mul_f32 v[160:161], v[158:159], v[158:159]
	v_pk_mul_f32 v[166:167], v[164:165], v[164:165]
	v_mul_f32_e32 v172, 0xbfb8aa3b, v126
	v_pk_fma_f32 v[160:161], v[160:161], s[72:73], -1.0 op_sel_hi:[1,0,0]
	v_pk_fma_f32 v[166:167], v[166:167], s[72:73], -1.0 op_sel_hi:[1,0,0]
	v_mul_f32_e32 v173, 0xbfb8aa3b, v127
	v_pk_fma_f32 v[162:163], v[160:161], s[74:75], v[198:199] op_sel_hi:[1,0,0]
	v_pk_fma_f32 v[168:169], v[166:167], s[74:75], v[198:199] op_sel_hi:[1,0,0]
	v_exp_f32_e32 v170, v170
	v_pk_fma_f32 v[162:163], v[160:161], v[162:163], s[2:3] op_sel_hi:[1,1,0]
	v_pk_fma_f32 v[168:169], v[166:167], v[168:169], s[2:3] op_sel_hi:[1,1,0]
	v_exp_f32_e32 v171, v171
	v_pk_fma_f32 v[162:163], v[160:161], v[162:163], s[28:29] op_sel_hi:[1,1,0]
	v_pk_fma_f32 v[168:169], v[166:167], v[168:169], s[28:29] op_sel_hi:[1,1,0]
	v_exp_f32_e32 v172, v172
	v_pk_fma_f32 v[162:163], v[160:161], v[162:163], s[30:31] op_sel_hi:[1,1,0]
	v_pk_fma_f32 v[168:169], v[166:167], v[168:169], s[30:31] op_sel_hi:[1,1,0]
	v_exp_f32_e32 v173, v173
	v_pk_fma_f32 v[162:163], v[160:161], v[162:163], s[48:49] op_sel_hi:[1,1,0]
	v_pk_fma_f32 v[168:169], v[166:167], v[168:169], s[48:49] op_sel_hi:[1,1,0]
	v_add_f32_e32 v170, 1.0, v170
	v_pk_fma_f32 v[162:163], v[160:161], v[162:163], s[50:51] op_sel_hi:[1,1,0]
	v_pk_fma_f32 v[168:169], v[166:167], v[168:169], s[50:51] op_sel_hi:[1,1,0]
	v_add_f32_e32 v171, 1.0, v171
	v_pk_fma_f32 v[162:163], v[160:161], v[162:163], s[52:53] op_sel_hi:[1,1,0]
	v_pk_fma_f32 v[168:169], v[166:167], v[168:169], s[52:53] op_sel_hi:[1,1,0]
	v_add_f32_e32 v172, 1.0, v172
	v_pk_fma_f32 v[160:161], v[160:161], v[162:163], s[54:55] op_sel_hi:[1,1,0]
	v_pk_fma_f32 v[166:167], v[166:167], v[168:169], s[54:55] op_sel_hi:[1,1,0]
	v_add_f32_e32 v173, 1.0, v173
	v_pk_fma_f32 v[158:159], v[158:159], v[160:161], 0.5 op_sel_hi:[1,1,0]
	v_pk_fma_f32 v[164:165], v[164:165], v[166:167], 0.5 op_sel_hi:[1,1,0]
	v_rcp_f32_e32 v178, v170
	v_pk_mul_f32 v[128:129], v[128:129], v[158:159]
	v_pk_mul_f32 v[130:131], v[130:131], v[164:165]
	v_rcp_f32_e32 v179, v171
	v_rcp_f32_e32 v180, v172
	v_rcp_f32_e32 v181, v173
	v_pk_mul_f32 v[124:125], v[124:125], v[178:179]
	v_pk_mul_f32 v[126:127], v[126:127], v[180:181]
	v_med3_f32 v158, v120, -4.0, 4.0
	v_med3_f32 v164, v122, -4.0, 4.0
	v_mul_f32_e32 v170, 0xbfb8aa3b, v116
	v_med3_f32 v159, v121, -4.0, 4.0
	v_med3_f32 v165, v123, -4.0, 4.0
	v_mul_f32_e32 v171, 0xbfb8aa3b, v117
	v_pk_mul_f32 v[160:161], v[158:159], v[158:159]
	v_pk_mul_f32 v[166:167], v[164:165], v[164:165]
	v_mul_f32_e32 v172, 0xbfb8aa3b, v118
	v_pk_fma_f32 v[160:161], v[160:161], s[72:73], -1.0 op_sel_hi:[1,0,0]
	v_pk_fma_f32 v[166:167], v[166:167], s[72:73], -1.0 op_sel_hi:[1,0,0]
	v_mul_f32_e32 v173, 0xbfb8aa3b, v119
	v_pk_fma_f32 v[162:163], v[160:161], s[74:75], v[198:199] op_sel_hi:[1,0,0]
	v_pk_fma_f32 v[168:169], v[166:167], s[74:75], v[198:199] op_sel_hi:[1,0,0]
	v_exp_f32_e32 v170, v170
	v_pk_fma_f32 v[162:163], v[160:161], v[162:163], s[2:3] op_sel_hi:[1,1,0]
	v_pk_fma_f32 v[168:169], v[166:167], v[168:169], s[2:3] op_sel_hi:[1,1,0]
	v_exp_f32_e32 v171, v171
	v_pk_fma_f32 v[162:163], v[160:161], v[162:163], s[28:29] op_sel_hi:[1,1,0]
	v_pk_fma_f32 v[168:169], v[166:167], v[168:169], s[28:29] op_sel_hi:[1,1,0]
	v_exp_f32_e32 v172, v172
	v_pk_fma_f32 v[162:163], v[160:161], v[162:163], s[30:31] op_sel_hi:[1,1,0]
	v_pk_fma_f32 v[168:169], v[166:167], v[168:169], s[30:31] op_sel_hi:[1,1,0]
	v_exp_f32_e32 v173, v173
	v_pk_fma_f32 v[162:163], v[160:161], v[162:163], s[48:49] op_sel_hi:[1,1,0]
	v_pk_fma_f32 v[168:169], v[166:167], v[168:169], s[48:49] op_sel_hi:[1,1,0]
	v_add_f32_e32 v170, 1.0, v170
	v_pk_fma_f32 v[162:163], v[160:161], v[162:163], s[50:51] op_sel_hi:[1,1,0]
	v_pk_fma_f32 v[168:169], v[166:167], v[168:169], s[50:51] op_sel_hi:[1,1,0]
	v_add_f32_e32 v171, 1.0, v171
	v_pk_fma_f32 v[162:163], v[160:161], v[162:163], s[52:53] op_sel_hi:[1,1,0]
	v_pk_fma_f32 v[168:169], v[166:167], v[168:169], s[52:53] op_sel_hi:[1,1,0]
	v_add_f32_e32 v172, 1.0, v172
	v_pk_fma_f32 v[160:161], v[160:161], v[162:163], s[54:55] op_sel_hi:[1,1,0]
	v_pk_fma_f32 v[166:167], v[166:167], v[168:169], s[54:55] op_sel_hi:[1,1,0]
	v_add_f32_e32 v173, 1.0, v173
	v_pk_fma_f32 v[158:159], v[158:159], v[160:161], 0.5 op_sel_hi:[1,1,0]
	v_pk_fma_f32 v[164:165], v[164:165], v[166:167], 0.5 op_sel_hi:[1,1,0]
	v_rcp_f32_e32 v178, v170
	v_pk_mul_f32 v[120:121], v[120:121], v[158:159]
	v_pk_mul_f32 v[122:123], v[122:123], v[164:165]
	v_rcp_f32_e32 v179, v171
	v_rcp_f32_e32 v180, v172
	v_rcp_f32_e32 v181, v173
	v_pk_mul_f32 v[116:117], v[116:117], v[178:179]
	v_pk_mul_f32 v[118:119], v[118:119], v[180:181]
	v_pk_mul_f32 v[124:125], v[124:125], v[128:129]
	v_pk_mul_f32 v[126:127], v[126:127], v[130:131]
	v_pk_mul_f32 v[116:117], v[116:117], v[120:121]
	v_pk_mul_f32 v[118:119], v[118:119], v[122:123]
	v_cvt_pk_bf16_f32 v128, v124, v125
	v_cvt_pk_bf16_f32 v129, v126, v127
	v_cvt_pk_bf16_f32 v130, v116, v117
	v_cvt_pk_bf16_f32 v131, v118, v119
	global_store_dwordx4 v182, v[128:131], s[10:11]
	v_pk_mul_f32 v[112:113], v[112:113], v[238:239] op_sel_hi:[1,0]
	v_pk_mul_f32 v[114:115], v[114:115], v[238:239] op_sel_hi:[1,0]
	v_pk_mul_f32 v[104:105], v[104:105], v[238:239] op_sel_hi:[1,0]
	v_pk_mul_f32 v[106:107], v[106:107], v[238:239] op_sel_hi:[1,0]
	v_pk_mul_f32 v[108:109], v[108:109], v[238:239] op_sel_hi:[1,0]
	v_pk_mul_f32 v[110:111], v[110:111], v[238:239] op_sel_hi:[1,0]
	v_pk_mul_f32 v[100:101], v[100:101], v[238:239] op_sel_hi:[1,0]
	v_pk_mul_f32 v[102:103], v[102:103], v[238:239] op_sel_hi:[1,0]
	v_med3_f32 v158, v112, -4.0, 4.0
	v_med3_f32 v164, v114, -4.0, 4.0
	v_mul_f32_e32 v170, 0xbfb8aa3b, v108
	v_med3_f32 v159, v113, -4.0, 4.0
	v_med3_f32 v165, v115, -4.0, 4.0
	v_mul_f32_e32 v171, 0xbfb8aa3b, v109
	v_pk_mul_f32 v[160:161], v[158:159], v[158:159]
	v_pk_mul_f32 v[166:167], v[164:165], v[164:165]
	v_mul_f32_e32 v172, 0xbfb8aa3b, v110
	v_pk_fma_f32 v[160:161], v[160:161], s[72:73], -1.0 op_sel_hi:[1,0,0]
	v_pk_fma_f32 v[166:167], v[166:167], s[72:73], -1.0 op_sel_hi:[1,0,0]
	v_mul_f32_e32 v173, 0xbfb8aa3b, v111
	v_pk_fma_f32 v[162:163], v[160:161], s[74:75], v[198:199] op_sel_hi:[1,0,0]
	v_pk_fma_f32 v[168:169], v[166:167], s[74:75], v[198:199] op_sel_hi:[1,0,0]
	v_exp_f32_e32 v170, v170
	v_pk_fma_f32 v[162:163], v[160:161], v[162:163], s[2:3] op_sel_hi:[1,1,0]
	v_pk_fma_f32 v[168:169], v[166:167], v[168:169], s[2:3] op_sel_hi:[1,1,0]
	v_exp_f32_e32 v171, v171
	v_pk_fma_f32 v[162:163], v[160:161], v[162:163], s[28:29] op_sel_hi:[1,1,0]
	v_pk_fma_f32 v[168:169], v[166:167], v[168:169], s[28:29] op_sel_hi:[1,1,0]
	v_exp_f32_e32 v172, v172
	v_pk_fma_f32 v[162:163], v[160:161], v[162:163], s[30:31] op_sel_hi:[1,1,0]
	v_pk_fma_f32 v[168:169], v[166:167], v[168:169], s[30:31] op_sel_hi:[1,1,0]
	v_exp_f32_e32 v173, v173
	v_pk_fma_f32 v[162:163], v[160:161], v[162:163], s[48:49] op_sel_hi:[1,1,0]
	v_pk_fma_f32 v[168:169], v[166:167], v[168:169], s[48:49] op_sel_hi:[1,1,0]
	v_add_f32_e32 v170, 1.0, v170
	v_pk_fma_f32 v[162:163], v[160:161], v[162:163], s[50:51] op_sel_hi:[1,1,0]
	v_pk_fma_f32 v[168:169], v[166:167], v[168:169], s[50:51] op_sel_hi:[1,1,0]
	v_add_f32_e32 v171, 1.0, v171
	v_pk_fma_f32 v[162:163], v[160:161], v[162:163], s[52:53] op_sel_hi:[1,1,0]
	v_pk_fma_f32 v[168:169], v[166:167], v[168:169], s[52:53] op_sel_hi:[1,1,0]
	v_add_f32_e32 v172, 1.0, v172
	v_pk_fma_f32 v[160:161], v[160:161], v[162:163], s[54:55] op_sel_hi:[1,1,0]
	v_pk_fma_f32 v[166:167], v[166:167], v[168:169], s[54:55] op_sel_hi:[1,1,0]
	v_add_f32_e32 v173, 1.0, v173
	v_pk_fma_f32 v[158:159], v[158:159], v[160:161], 0.5 op_sel_hi:[1,1,0]
	v_pk_fma_f32 v[164:165], v[164:165], v[166:167], 0.5 op_sel_hi:[1,1,0]
	v_rcp_f32_e32 v178, v170
	v_pk_mul_f32 v[112:113], v[112:113], v[158:159]
	v_pk_mul_f32 v[114:115], v[114:115], v[164:165]
	v_rcp_f32_e32 v179, v171
	v_rcp_f32_e32 v180, v172
	v_rcp_f32_e32 v181, v173
	v_pk_mul_f32 v[108:109], v[108:109], v[178:179]
	v_pk_mul_f32 v[110:111], v[110:111], v[180:181]
	v_med3_f32 v158, v104, -4.0, 4.0
	v_med3_f32 v164, v106, -4.0, 4.0
	v_mul_f32_e32 v170, 0xbfb8aa3b, v100
	v_med3_f32 v159, v105, -4.0, 4.0
	v_med3_f32 v165, v107, -4.0, 4.0
	v_mul_f32_e32 v171, 0xbfb8aa3b, v101
	v_pk_mul_f32 v[160:161], v[158:159], v[158:159]
	v_pk_mul_f32 v[166:167], v[164:165], v[164:165]
	v_mul_f32_e32 v172, 0xbfb8aa3b, v102
	v_pk_fma_f32 v[160:161], v[160:161], s[72:73], -1.0 op_sel_hi:[1,0,0]
	v_pk_fma_f32 v[166:167], v[166:167], s[72:73], -1.0 op_sel_hi:[1,0,0]
	v_mul_f32_e32 v173, 0xbfb8aa3b, v103
	v_pk_fma_f32 v[162:163], v[160:161], s[74:75], v[198:199] op_sel_hi:[1,0,0]
	v_pk_fma_f32 v[168:169], v[166:167], s[74:75], v[198:199] op_sel_hi:[1,0,0]
	v_exp_f32_e32 v170, v170
	v_pk_fma_f32 v[162:163], v[160:161], v[162:163], s[2:3] op_sel_hi:[1,1,0]
	v_pk_fma_f32 v[168:169], v[166:167], v[168:169], s[2:3] op_sel_hi:[1,1,0]
	v_exp_f32_e32 v171, v171
	v_pk_fma_f32 v[162:163], v[160:161], v[162:163], s[28:29] op_sel_hi:[1,1,0]
	v_pk_fma_f32 v[168:169], v[166:167], v[168:169], s[28:29] op_sel_hi:[1,1,0]
	v_exp_f32_e32 v172, v172
	v_pk_fma_f32 v[162:163], v[160:161], v[162:163], s[30:31] op_sel_hi:[1,1,0]
	v_pk_fma_f32 v[168:169], v[166:167], v[168:169], s[30:31] op_sel_hi:[1,1,0]
	v_exp_f32_e32 v173, v173
	v_pk_fma_f32 v[162:163], v[160:161], v[162:163], s[48:49] op_sel_hi:[1,1,0]
	v_pk_fma_f32 v[168:169], v[166:167], v[168:169], s[48:49] op_sel_hi:[1,1,0]
	v_add_f32_e32 v170, 1.0, v170
	v_pk_fma_f32 v[162:163], v[160:161], v[162:163], s[50:51] op_sel_hi:[1,1,0]
	v_pk_fma_f32 v[168:169], v[166:167], v[168:169], s[50:51] op_sel_hi:[1,1,0]
	v_add_f32_e32 v171, 1.0, v171
	v_pk_fma_f32 v[162:163], v[160:161], v[162:163], s[52:53] op_sel_hi:[1,1,0]
	v_pk_fma_f32 v[168:169], v[166:167], v[168:169], s[52:53] op_sel_hi:[1,1,0]
	v_add_f32_e32 v172, 1.0, v172
	v_pk_fma_f32 v[160:161], v[160:161], v[162:163], s[54:55] op_sel_hi:[1,1,0]
	v_pk_fma_f32 v[166:167], v[166:167], v[168:169], s[54:55] op_sel_hi:[1,1,0]
	v_add_f32_e32 v173, 1.0, v173
	v_pk_fma_f32 v[158:159], v[158:159], v[160:161], 0.5 op_sel_hi:[1,1,0]
	v_pk_fma_f32 v[164:165], v[164:165], v[166:167], 0.5 op_sel_hi:[1,1,0]
	v_rcp_f32_e32 v178, v170
	v_pk_mul_f32 v[104:105], v[104:105], v[158:159]
	v_pk_mul_f32 v[106:107], v[106:107], v[164:165]
	v_rcp_f32_e32 v179, v171
	v_rcp_f32_e32 v180, v172
	v_rcp_f32_e32 v181, v173
	v_pk_mul_f32 v[100:101], v[100:101], v[178:179]
	v_pk_mul_f32 v[102:103], v[102:103], v[180:181]
	v_pk_mul_f32 v[108:109], v[108:109], v[112:113]
	v_pk_mul_f32 v[110:111], v[110:111], v[114:115]
	v_pk_mul_f32 v[100:101], v[100:101], v[104:105]
	v_pk_mul_f32 v[102:103], v[102:103], v[106:107]
	v_cvt_pk_bf16_f32 v112, v108, v109
	v_cvt_pk_bf16_f32 v113, v110, v111
	v_cvt_pk_bf16_f32 v114, v100, v101
	v_cvt_pk_bf16_f32 v115, v102, v103
	global_store_dwordx4 v183, v[112:115], s[10:11]
	v_pk_mul_f32 v[96:97], v[96:97], v[240:241] op_sel_hi:[1,0]
	v_pk_mul_f32 v[98:99], v[98:99], v[240:241] op_sel_hi:[1,0]
	v_pk_mul_f32 v[88:89], v[88:89], v[240:241] op_sel_hi:[1,0]
	v_pk_mul_f32 v[90:91], v[90:91], v[240:241] op_sel_hi:[1,0]
	v_pk_mul_f32 v[92:93], v[92:93], v[240:241] op_sel_hi:[1,0]
	v_pk_mul_f32 v[94:95], v[94:95], v[240:241] op_sel_hi:[1,0]
	v_pk_mul_f32 v[84:85], v[84:85], v[240:241] op_sel_hi:[1,0]
	v_pk_mul_f32 v[86:87], v[86:87], v[240:241] op_sel_hi:[1,0]
	v_med3_f32 v158, v96, -4.0, 4.0
	v_med3_f32 v164, v98, -4.0, 4.0
	v_mul_f32_e32 v170, 0xbfb8aa3b, v92
	v_med3_f32 v159, v97, -4.0, 4.0
	v_med3_f32 v165, v99, -4.0, 4.0
	v_mul_f32_e32 v171, 0xbfb8aa3b, v93
	v_pk_mul_f32 v[160:161], v[158:159], v[158:159]
	v_pk_mul_f32 v[166:167], v[164:165], v[164:165]
	v_mul_f32_e32 v172, 0xbfb8aa3b, v94
	v_pk_fma_f32 v[160:161], v[160:161], s[72:73], -1.0 op_sel_hi:[1,0,0]
	v_pk_fma_f32 v[166:167], v[166:167], s[72:73], -1.0 op_sel_hi:[1,0,0]
	v_mul_f32_e32 v173, 0xbfb8aa3b, v95
	v_pk_fma_f32 v[162:163], v[160:161], s[74:75], v[198:199] op_sel_hi:[1,0,0]
	v_pk_fma_f32 v[168:169], v[166:167], s[74:75], v[198:199] op_sel_hi:[1,0,0]
	v_exp_f32_e32 v170, v170
	v_pk_fma_f32 v[162:163], v[160:161], v[162:163], s[2:3] op_sel_hi:[1,1,0]
	v_pk_fma_f32 v[168:169], v[166:167], v[168:169], s[2:3] op_sel_hi:[1,1,0]
	v_exp_f32_e32 v171, v171
	v_pk_fma_f32 v[162:163], v[160:161], v[162:163], s[28:29] op_sel_hi:[1,1,0]
	v_pk_fma_f32 v[168:169], v[166:167], v[168:169], s[28:29] op_sel_hi:[1,1,0]
	v_exp_f32_e32 v172, v172
	v_pk_fma_f32 v[162:163], v[160:161], v[162:163], s[30:31] op_sel_hi:[1,1,0]
	v_pk_fma_f32 v[168:169], v[166:167], v[168:169], s[30:31] op_sel_hi:[1,1,0]
	v_exp_f32_e32 v173, v173
	v_pk_fma_f32 v[162:163], v[160:161], v[162:163], s[48:49] op_sel_hi:[1,1,0]
	v_pk_fma_f32 v[168:169], v[166:167], v[168:169], s[48:49] op_sel_hi:[1,1,0]
	v_add_f32_e32 v170, 1.0, v170
	v_pk_fma_f32 v[162:163], v[160:161], v[162:163], s[50:51] op_sel_hi:[1,1,0]
	v_pk_fma_f32 v[168:169], v[166:167], v[168:169], s[50:51] op_sel_hi:[1,1,0]
	v_add_f32_e32 v171, 1.0, v171
	v_pk_fma_f32 v[162:163], v[160:161], v[162:163], s[52:53] op_sel_hi:[1,1,0]
	v_pk_fma_f32 v[168:169], v[166:167], v[168:169], s[52:53] op_sel_hi:[1,1,0]
	v_add_f32_e32 v172, 1.0, v172
	v_pk_fma_f32 v[160:161], v[160:161], v[162:163], s[54:55] op_sel_hi:[1,1,0]
	v_pk_fma_f32 v[166:167], v[166:167], v[168:169], s[54:55] op_sel_hi:[1,1,0]
	v_add_f32_e32 v173, 1.0, v173
	v_pk_fma_f32 v[158:159], v[158:159], v[160:161], 0.5 op_sel_hi:[1,1,0]
	v_pk_fma_f32 v[164:165], v[164:165], v[166:167], 0.5 op_sel_hi:[1,1,0]
	v_rcp_f32_e32 v178, v170
	v_pk_mul_f32 v[96:97], v[96:97], v[158:159]
	v_pk_mul_f32 v[98:99], v[98:99], v[164:165]
	v_rcp_f32_e32 v179, v171
	v_rcp_f32_e32 v180, v172
	v_rcp_f32_e32 v181, v173
	v_pk_mul_f32 v[92:93], v[92:93], v[178:179]
	v_pk_mul_f32 v[94:95], v[94:95], v[180:181]
	v_med3_f32 v158, v88, -4.0, 4.0
	v_med3_f32 v164, v90, -4.0, 4.0
	v_mul_f32_e32 v170, 0xbfb8aa3b, v84
	v_med3_f32 v159, v89, -4.0, 4.0
	v_med3_f32 v165, v91, -4.0, 4.0
	v_mul_f32_e32 v171, 0xbfb8aa3b, v85
	v_pk_mul_f32 v[160:161], v[158:159], v[158:159]
	v_pk_mul_f32 v[166:167], v[164:165], v[164:165]
	v_mul_f32_e32 v172, 0xbfb8aa3b, v86
	v_pk_fma_f32 v[160:161], v[160:161], s[72:73], -1.0 op_sel_hi:[1,0,0]
	v_pk_fma_f32 v[166:167], v[166:167], s[72:73], -1.0 op_sel_hi:[1,0,0]
	v_mul_f32_e32 v173, 0xbfb8aa3b, v87
	v_pk_fma_f32 v[162:163], v[160:161], s[74:75], v[198:199] op_sel_hi:[1,0,0]
	v_pk_fma_f32 v[168:169], v[166:167], s[74:75], v[198:199] op_sel_hi:[1,0,0]
	v_exp_f32_e32 v170, v170
	v_pk_fma_f32 v[162:163], v[160:161], v[162:163], s[2:3] op_sel_hi:[1,1,0]
	v_pk_fma_f32 v[168:169], v[166:167], v[168:169], s[2:3] op_sel_hi:[1,1,0]
	v_exp_f32_e32 v171, v171
	v_pk_fma_f32 v[162:163], v[160:161], v[162:163], s[28:29] op_sel_hi:[1,1,0]
	v_pk_fma_f32 v[168:169], v[166:167], v[168:169], s[28:29] op_sel_hi:[1,1,0]
	v_exp_f32_e32 v172, v172
	v_pk_fma_f32 v[162:163], v[160:161], v[162:163], s[30:31] op_sel_hi:[1,1,0]
	v_pk_fma_f32 v[168:169], v[166:167], v[168:169], s[30:31] op_sel_hi:[1,1,0]
	v_exp_f32_e32 v173, v173
	v_pk_fma_f32 v[162:163], v[160:161], v[162:163], s[48:49] op_sel_hi:[1,1,0]
	v_pk_fma_f32 v[168:169], v[166:167], v[168:169], s[48:49] op_sel_hi:[1,1,0]
	v_add_f32_e32 v170, 1.0, v170
	v_pk_fma_f32 v[162:163], v[160:161], v[162:163], s[50:51] op_sel_hi:[1,1,0]
	v_pk_fma_f32 v[168:169], v[166:167], v[168:169], s[50:51] op_sel_hi:[1,1,0]
	v_add_f32_e32 v171, 1.0, v171
	v_pk_fma_f32 v[162:163], v[160:161], v[162:163], s[52:53] op_sel_hi:[1,1,0]
	v_pk_fma_f32 v[168:169], v[166:167], v[168:169], s[52:53] op_sel_hi:[1,1,0]
	v_add_f32_e32 v172, 1.0, v172
	v_pk_fma_f32 v[160:161], v[160:161], v[162:163], s[54:55] op_sel_hi:[1,1,0]
	v_pk_fma_f32 v[166:167], v[166:167], v[168:169], s[54:55] op_sel_hi:[1,1,0]
	v_add_f32_e32 v173, 1.0, v173
	v_pk_fma_f32 v[158:159], v[158:159], v[160:161], 0.5 op_sel_hi:[1,1,0]
	v_pk_fma_f32 v[164:165], v[164:165], v[166:167], 0.5 op_sel_hi:[1,1,0]
	v_rcp_f32_e32 v178, v170
	v_pk_mul_f32 v[88:89], v[88:89], v[158:159]
	v_pk_mul_f32 v[90:91], v[90:91], v[164:165]
	v_rcp_f32_e32 v179, v171
	v_rcp_f32_e32 v180, v172
	v_rcp_f32_e32 v181, v173
	v_pk_mul_f32 v[84:85], v[84:85], v[178:179]
	v_pk_mul_f32 v[86:87], v[86:87], v[180:181]
	v_pk_mul_f32 v[92:93], v[92:93], v[96:97]
	v_pk_mul_f32 v[94:95], v[94:95], v[98:99]
	v_pk_mul_f32 v[84:85], v[84:85], v[88:89]
	v_pk_mul_f32 v[86:87], v[86:87], v[90:91]
	v_cvt_pk_bf16_f32 v96, v92, v93
	v_cvt_pk_bf16_f32 v97, v94, v95
	v_cvt_pk_bf16_f32 v98, v84, v85
	v_cvt_pk_bf16_f32 v99, v86, v87
	global_store_dwordx4 v184, v[96:99], s[10:11]
	v_pk_mul_f32 v[80:81], v[80:81], v[242:243] op_sel_hi:[1,0]
	v_pk_mul_f32 v[82:83], v[82:83], v[242:243] op_sel_hi:[1,0]
	v_pk_mul_f32 v[72:73], v[72:73], v[242:243] op_sel_hi:[1,0]
	v_pk_mul_f32 v[74:75], v[74:75], v[242:243] op_sel_hi:[1,0]
	v_pk_mul_f32 v[76:77], v[76:77], v[242:243] op_sel_hi:[1,0]
	v_pk_mul_f32 v[78:79], v[78:79], v[242:243] op_sel_hi:[1,0]
	v_pk_mul_f32 v[68:69], v[68:69], v[242:243] op_sel_hi:[1,0]
	v_pk_mul_f32 v[70:71], v[70:71], v[242:243] op_sel_hi:[1,0]
	v_med3_f32 v158, v80, -4.0, 4.0
	v_med3_f32 v164, v82, -4.0, 4.0
	v_mul_f32_e32 v170, 0xbfb8aa3b, v76
	v_med3_f32 v159, v81, -4.0, 4.0
	v_med3_f32 v165, v83, -4.0, 4.0
	v_mul_f32_e32 v171, 0xbfb8aa3b, v77
	v_pk_mul_f32 v[160:161], v[158:159], v[158:159]
	v_pk_mul_f32 v[166:167], v[164:165], v[164:165]
	v_mul_f32_e32 v172, 0xbfb8aa3b, v78
	v_pk_fma_f32 v[160:161], v[160:161], s[72:73], -1.0 op_sel_hi:[1,0,0]
	v_pk_fma_f32 v[166:167], v[166:167], s[72:73], -1.0 op_sel_hi:[1,0,0]
	v_mul_f32_e32 v173, 0xbfb8aa3b, v79
	v_pk_fma_f32 v[162:163], v[160:161], s[74:75], v[198:199] op_sel_hi:[1,0,0]
	v_pk_fma_f32 v[168:169], v[166:167], s[74:75], v[198:199] op_sel_hi:[1,0,0]
	v_exp_f32_e32 v170, v170
	v_pk_fma_f32 v[162:163], v[160:161], v[162:163], s[2:3] op_sel_hi:[1,1,0]
	v_pk_fma_f32 v[168:169], v[166:167], v[168:169], s[2:3] op_sel_hi:[1,1,0]
	v_exp_f32_e32 v171, v171
	v_pk_fma_f32 v[162:163], v[160:161], v[162:163], s[28:29] op_sel_hi:[1,1,0]
	v_pk_fma_f32 v[168:169], v[166:167], v[168:169], s[28:29] op_sel_hi:[1,1,0]
	v_exp_f32_e32 v172, v172
	v_pk_fma_f32 v[162:163], v[160:161], v[162:163], s[30:31] op_sel_hi:[1,1,0]
	v_pk_fma_f32 v[168:169], v[166:167], v[168:169], s[30:31] op_sel_hi:[1,1,0]
	v_exp_f32_e32 v173, v173
	v_pk_fma_f32 v[162:163], v[160:161], v[162:163], s[48:49] op_sel_hi:[1,1,0]
	v_pk_fma_f32 v[168:169], v[166:167], v[168:169], s[48:49] op_sel_hi:[1,1,0]
	v_add_f32_e32 v170, 1.0, v170
	v_pk_fma_f32 v[162:163], v[160:161], v[162:163], s[50:51] op_sel_hi:[1,1,0]
	v_pk_fma_f32 v[168:169], v[166:167], v[168:169], s[50:51] op_sel_hi:[1,1,0]
	v_add_f32_e32 v171, 1.0, v171
	v_pk_fma_f32 v[162:163], v[160:161], v[162:163], s[52:53] op_sel_hi:[1,1,0]
	v_pk_fma_f32 v[168:169], v[166:167], v[168:169], s[52:53] op_sel_hi:[1,1,0]
	v_add_f32_e32 v172, 1.0, v172
	v_pk_fma_f32 v[160:161], v[160:161], v[162:163], s[54:55] op_sel_hi:[1,1,0]
	v_pk_fma_f32 v[166:167], v[166:167], v[168:169], s[54:55] op_sel_hi:[1,1,0]
	v_add_f32_e32 v173, 1.0, v173
	v_pk_fma_f32 v[158:159], v[158:159], v[160:161], 0.5 op_sel_hi:[1,1,0]
	v_pk_fma_f32 v[164:165], v[164:165], v[166:167], 0.5 op_sel_hi:[1,1,0]
	v_rcp_f32_e32 v178, v170
	v_pk_mul_f32 v[80:81], v[80:81], v[158:159]
	v_pk_mul_f32 v[82:83], v[82:83], v[164:165]
	v_rcp_f32_e32 v179, v171
	v_rcp_f32_e32 v180, v172
	v_rcp_f32_e32 v181, v173
	v_pk_mul_f32 v[76:77], v[76:77], v[178:179]
	v_pk_mul_f32 v[78:79], v[78:79], v[180:181]
	v_med3_f32 v158, v72, -4.0, 4.0
	v_med3_f32 v164, v74, -4.0, 4.0
	v_mul_f32_e32 v170, 0xbfb8aa3b, v68
	v_med3_f32 v159, v73, -4.0, 4.0
	v_med3_f32 v165, v75, -4.0, 4.0
	v_mul_f32_e32 v171, 0xbfb8aa3b, v69
	v_pk_mul_f32 v[160:161], v[158:159], v[158:159]
	v_pk_mul_f32 v[166:167], v[164:165], v[164:165]
	v_mul_f32_e32 v172, 0xbfb8aa3b, v70
	v_pk_fma_f32 v[160:161], v[160:161], s[72:73], -1.0 op_sel_hi:[1,0,0]
	v_pk_fma_f32 v[166:167], v[166:167], s[72:73], -1.0 op_sel_hi:[1,0,0]
	v_mul_f32_e32 v173, 0xbfb8aa3b, v71
	v_pk_fma_f32 v[162:163], v[160:161], s[74:75], v[198:199] op_sel_hi:[1,0,0]
	v_pk_fma_f32 v[168:169], v[166:167], s[74:75], v[198:199] op_sel_hi:[1,0,0]
	v_exp_f32_e32 v170, v170
	v_pk_fma_f32 v[162:163], v[160:161], v[162:163], s[2:3] op_sel_hi:[1,1,0]
	v_pk_fma_f32 v[168:169], v[166:167], v[168:169], s[2:3] op_sel_hi:[1,1,0]
	v_exp_f32_e32 v171, v171
	v_pk_fma_f32 v[162:163], v[160:161], v[162:163], s[28:29] op_sel_hi:[1,1,0]
	v_pk_fma_f32 v[168:169], v[166:167], v[168:169], s[28:29] op_sel_hi:[1,1,0]
	v_exp_f32_e32 v172, v172
	v_pk_fma_f32 v[162:163], v[160:161], v[162:163], s[30:31] op_sel_hi:[1,1,0]
	v_pk_fma_f32 v[168:169], v[166:167], v[168:169], s[30:31] op_sel_hi:[1,1,0]
	v_exp_f32_e32 v173, v173
	v_pk_fma_f32 v[162:163], v[160:161], v[162:163], s[48:49] op_sel_hi:[1,1,0]
	v_pk_fma_f32 v[168:169], v[166:167], v[168:169], s[48:49] op_sel_hi:[1,1,0]
	v_add_f32_e32 v170, 1.0, v170
	v_pk_fma_f32 v[162:163], v[160:161], v[162:163], s[50:51] op_sel_hi:[1,1,0]
	v_pk_fma_f32 v[168:169], v[166:167], v[168:169], s[50:51] op_sel_hi:[1,1,0]
	v_add_f32_e32 v171, 1.0, v171
	v_pk_fma_f32 v[162:163], v[160:161], v[162:163], s[52:53] op_sel_hi:[1,1,0]
	v_pk_fma_f32 v[168:169], v[166:167], v[168:169], s[52:53] op_sel_hi:[1,1,0]
	v_add_f32_e32 v172, 1.0, v172
	v_pk_fma_f32 v[160:161], v[160:161], v[162:163], s[54:55] op_sel_hi:[1,1,0]
	v_pk_fma_f32 v[166:167], v[166:167], v[168:169], s[54:55] op_sel_hi:[1,1,0]
	v_add_f32_e32 v173, 1.0, v173
	v_pk_fma_f32 v[158:159], v[158:159], v[160:161], 0.5 op_sel_hi:[1,1,0]
	v_pk_fma_f32 v[164:165], v[164:165], v[166:167], 0.5 op_sel_hi:[1,1,0]
	v_rcp_f32_e32 v178, v170
	v_pk_mul_f32 v[72:73], v[72:73], v[158:159]
	v_pk_mul_f32 v[74:75], v[74:75], v[164:165]
	v_rcp_f32_e32 v179, v171
	v_rcp_f32_e32 v180, v172
	v_rcp_f32_e32 v181, v173
	v_pk_mul_f32 v[68:69], v[68:69], v[178:179]
	v_pk_mul_f32 v[70:71], v[70:71], v[180:181]
	v_pk_mul_f32 v[76:77], v[76:77], v[80:81]
	v_pk_mul_f32 v[78:79], v[78:79], v[82:83]
	v_pk_mul_f32 v[68:69], v[68:69], v[72:73]
	v_pk_mul_f32 v[70:71], v[70:71], v[74:75]
	v_cvt_pk_bf16_f32 v80, v76, v77
	v_cvt_pk_bf16_f32 v81, v78, v79
	v_cvt_pk_bf16_f32 v82, v68, v69
	v_cvt_pk_bf16_f32 v83, v70, v71
	global_store_dwordx4 v185, v[80:83], s[10:11]
	v_pk_mul_f32 v[64:65], v[64:65], v[244:245] op_sel_hi:[1,0]
	v_pk_mul_f32 v[66:67], v[66:67], v[244:245] op_sel_hi:[1,0]
	v_pk_mul_f32 v[56:57], v[56:57], v[244:245] op_sel_hi:[1,0]
	v_pk_mul_f32 v[58:59], v[58:59], v[244:245] op_sel_hi:[1,0]
	v_pk_mul_f32 v[60:61], v[60:61], v[244:245] op_sel_hi:[1,0]
	v_pk_mul_f32 v[62:63], v[62:63], v[244:245] op_sel_hi:[1,0]
	v_pk_mul_f32 v[52:53], v[52:53], v[244:245] op_sel_hi:[1,0]
	v_pk_mul_f32 v[54:55], v[54:55], v[244:245] op_sel_hi:[1,0]
	v_med3_f32 v158, v64, -4.0, 4.0
	v_med3_f32 v164, v66, -4.0, 4.0
	v_mul_f32_e32 v170, 0xbfb8aa3b, v60
	v_med3_f32 v159, v65, -4.0, 4.0
	v_med3_f32 v165, v67, -4.0, 4.0
	v_mul_f32_e32 v171, 0xbfb8aa3b, v61
	v_pk_mul_f32 v[160:161], v[158:159], v[158:159]
	v_pk_mul_f32 v[166:167], v[164:165], v[164:165]
	v_mul_f32_e32 v172, 0xbfb8aa3b, v62
	v_pk_fma_f32 v[160:161], v[160:161], s[72:73], -1.0 op_sel_hi:[1,0,0]
	v_pk_fma_f32 v[166:167], v[166:167], s[72:73], -1.0 op_sel_hi:[1,0,0]
	v_mul_f32_e32 v173, 0xbfb8aa3b, v63
	v_pk_fma_f32 v[162:163], v[160:161], s[74:75], v[198:199] op_sel_hi:[1,0,0]
	v_pk_fma_f32 v[168:169], v[166:167], s[74:75], v[198:199] op_sel_hi:[1,0,0]
	v_exp_f32_e32 v170, v170
	v_pk_fma_f32 v[162:163], v[160:161], v[162:163], s[2:3] op_sel_hi:[1,1,0]
	v_pk_fma_f32 v[168:169], v[166:167], v[168:169], s[2:3] op_sel_hi:[1,1,0]
	v_exp_f32_e32 v171, v171
	v_pk_fma_f32 v[162:163], v[160:161], v[162:163], s[28:29] op_sel_hi:[1,1,0]
	v_pk_fma_f32 v[168:169], v[166:167], v[168:169], s[28:29] op_sel_hi:[1,1,0]
	v_exp_f32_e32 v172, v172
	v_pk_fma_f32 v[162:163], v[160:161], v[162:163], s[30:31] op_sel_hi:[1,1,0]
	v_pk_fma_f32 v[168:169], v[166:167], v[168:169], s[30:31] op_sel_hi:[1,1,0]
	v_exp_f32_e32 v173, v173
	v_pk_fma_f32 v[162:163], v[160:161], v[162:163], s[48:49] op_sel_hi:[1,1,0]
	v_pk_fma_f32 v[168:169], v[166:167], v[168:169], s[48:49] op_sel_hi:[1,1,0]
	v_add_f32_e32 v170, 1.0, v170
	v_pk_fma_f32 v[162:163], v[160:161], v[162:163], s[50:51] op_sel_hi:[1,1,0]
	v_pk_fma_f32 v[168:169], v[166:167], v[168:169], s[50:51] op_sel_hi:[1,1,0]
	v_add_f32_e32 v171, 1.0, v171
	v_pk_fma_f32 v[162:163], v[160:161], v[162:163], s[52:53] op_sel_hi:[1,1,0]
	v_pk_fma_f32 v[168:169], v[166:167], v[168:169], s[52:53] op_sel_hi:[1,1,0]
	v_add_f32_e32 v172, 1.0, v172
	v_pk_fma_f32 v[160:161], v[160:161], v[162:163], s[54:55] op_sel_hi:[1,1,0]
	v_pk_fma_f32 v[166:167], v[166:167], v[168:169], s[54:55] op_sel_hi:[1,1,0]
	v_add_f32_e32 v173, 1.0, v173
	v_pk_fma_f32 v[158:159], v[158:159], v[160:161], 0.5 op_sel_hi:[1,1,0]
	v_pk_fma_f32 v[164:165], v[164:165], v[166:167], 0.5 op_sel_hi:[1,1,0]
	v_rcp_f32_e32 v178, v170
	v_pk_mul_f32 v[64:65], v[64:65], v[158:159]
	v_pk_mul_f32 v[66:67], v[66:67], v[164:165]
	v_rcp_f32_e32 v179, v171
	v_rcp_f32_e32 v180, v172
	v_rcp_f32_e32 v181, v173
	v_pk_mul_f32 v[60:61], v[60:61], v[178:179]
	v_pk_mul_f32 v[62:63], v[62:63], v[180:181]
	v_med3_f32 v158, v56, -4.0, 4.0
	v_med3_f32 v164, v58, -4.0, 4.0
	v_mul_f32_e32 v170, 0xbfb8aa3b, v52
	v_med3_f32 v159, v57, -4.0, 4.0
	v_med3_f32 v165, v59, -4.0, 4.0
	v_mul_f32_e32 v171, 0xbfb8aa3b, v53
	v_pk_mul_f32 v[160:161], v[158:159], v[158:159]
	v_pk_mul_f32 v[166:167], v[164:165], v[164:165]
	v_mul_f32_e32 v172, 0xbfb8aa3b, v54
	v_pk_fma_f32 v[160:161], v[160:161], s[72:73], -1.0 op_sel_hi:[1,0,0]
	v_pk_fma_f32 v[166:167], v[166:167], s[72:73], -1.0 op_sel_hi:[1,0,0]
	v_mul_f32_e32 v173, 0xbfb8aa3b, v55
	v_pk_fma_f32 v[162:163], v[160:161], s[74:75], v[198:199] op_sel_hi:[1,0,0]
	v_pk_fma_f32 v[168:169], v[166:167], s[74:75], v[198:199] op_sel_hi:[1,0,0]
	v_exp_f32_e32 v170, v170
	v_pk_fma_f32 v[162:163], v[160:161], v[162:163], s[2:3] op_sel_hi:[1,1,0]
	v_pk_fma_f32 v[168:169], v[166:167], v[168:169], s[2:3] op_sel_hi:[1,1,0]
	v_exp_f32_e32 v171, v171
	v_pk_fma_f32 v[162:163], v[160:161], v[162:163], s[28:29] op_sel_hi:[1,1,0]
	v_pk_fma_f32 v[168:169], v[166:167], v[168:169], s[28:29] op_sel_hi:[1,1,0]
	v_exp_f32_e32 v172, v172
	v_pk_fma_f32 v[162:163], v[160:161], v[162:163], s[30:31] op_sel_hi:[1,1,0]
	v_pk_fma_f32 v[168:169], v[166:167], v[168:169], s[30:31] op_sel_hi:[1,1,0]
	v_exp_f32_e32 v173, v173
	v_pk_fma_f32 v[162:163], v[160:161], v[162:163], s[48:49] op_sel_hi:[1,1,0]
	v_pk_fma_f32 v[168:169], v[166:167], v[168:169], s[48:49] op_sel_hi:[1,1,0]
	v_add_f32_e32 v170, 1.0, v170
	v_pk_fma_f32 v[162:163], v[160:161], v[162:163], s[50:51] op_sel_hi:[1,1,0]
	v_pk_fma_f32 v[168:169], v[166:167], v[168:169], s[50:51] op_sel_hi:[1,1,0]
	v_add_f32_e32 v171, 1.0, v171
	v_pk_fma_f32 v[162:163], v[160:161], v[162:163], s[52:53] op_sel_hi:[1,1,0]
	v_pk_fma_f32 v[168:169], v[166:167], v[168:169], s[52:53] op_sel_hi:[1,1,0]
	v_add_f32_e32 v172, 1.0, v172
	v_pk_fma_f32 v[160:161], v[160:161], v[162:163], s[54:55] op_sel_hi:[1,1,0]
	v_pk_fma_f32 v[166:167], v[166:167], v[168:169], s[54:55] op_sel_hi:[1,1,0]
	v_add_f32_e32 v173, 1.0, v173
	v_pk_fma_f32 v[158:159], v[158:159], v[160:161], 0.5 op_sel_hi:[1,1,0]
	v_pk_fma_f32 v[164:165], v[164:165], v[166:167], 0.5 op_sel_hi:[1,1,0]
	v_rcp_f32_e32 v178, v170
	v_pk_mul_f32 v[56:57], v[56:57], v[158:159]
	v_pk_mul_f32 v[58:59], v[58:59], v[164:165]
	v_rcp_f32_e32 v179, v171
	v_rcp_f32_e32 v180, v172
	v_rcp_f32_e32 v181, v173
	v_pk_mul_f32 v[52:53], v[52:53], v[178:179]
	v_pk_mul_f32 v[54:55], v[54:55], v[180:181]
	v_pk_mul_f32 v[60:61], v[60:61], v[64:65]
	v_pk_mul_f32 v[62:63], v[62:63], v[66:67]
	v_pk_mul_f32 v[52:53], v[52:53], v[56:57]
	v_pk_mul_f32 v[54:55], v[54:55], v[58:59]
	v_cvt_pk_bf16_f32 v64, v60, v61
	v_cvt_pk_bf16_f32 v65, v62, v63
	v_cvt_pk_bf16_f32 v66, v52, v53
	v_cvt_pk_bf16_f32 v67, v54, v55
	global_store_dwordx4 v186, v[64:67], s[10:11]
	v_pk_mul_f32 v[48:49], v[48:49], v[246:247] op_sel_hi:[1,0]
	v_pk_mul_f32 v[50:51], v[50:51], v[246:247] op_sel_hi:[1,0]
	v_pk_mul_f32 v[40:41], v[40:41], v[246:247] op_sel_hi:[1,0]
	v_pk_mul_f32 v[42:43], v[42:43], v[246:247] op_sel_hi:[1,0]
	v_pk_mul_f32 v[44:45], v[44:45], v[246:247] op_sel_hi:[1,0]
	v_pk_mul_f32 v[46:47], v[46:47], v[246:247] op_sel_hi:[1,0]
	v_pk_mul_f32 v[36:37], v[36:37], v[246:247] op_sel_hi:[1,0]
	v_pk_mul_f32 v[38:39], v[38:39], v[246:247] op_sel_hi:[1,0]
	v_med3_f32 v158, v48, -4.0, 4.0
	v_med3_f32 v164, v50, -4.0, 4.0
	v_mul_f32_e32 v170, 0xbfb8aa3b, v44
	v_med3_f32 v159, v49, -4.0, 4.0
	v_med3_f32 v165, v51, -4.0, 4.0
	v_mul_f32_e32 v171, 0xbfb8aa3b, v45
	v_pk_mul_f32 v[160:161], v[158:159], v[158:159]
	v_pk_mul_f32 v[166:167], v[164:165], v[164:165]
	v_mul_f32_e32 v172, 0xbfb8aa3b, v46
	v_pk_fma_f32 v[160:161], v[160:161], s[72:73], -1.0 op_sel_hi:[1,0,0]
	v_pk_fma_f32 v[166:167], v[166:167], s[72:73], -1.0 op_sel_hi:[1,0,0]
	v_mul_f32_e32 v173, 0xbfb8aa3b, v47
	v_pk_fma_f32 v[162:163], v[160:161], s[74:75], v[198:199] op_sel_hi:[1,0,0]
	v_pk_fma_f32 v[168:169], v[166:167], s[74:75], v[198:199] op_sel_hi:[1,0,0]
	v_exp_f32_e32 v170, v170
	v_pk_fma_f32 v[162:163], v[160:161], v[162:163], s[2:3] op_sel_hi:[1,1,0]
	v_pk_fma_f32 v[168:169], v[166:167], v[168:169], s[2:3] op_sel_hi:[1,1,0]
	v_exp_f32_e32 v171, v171
	v_pk_fma_f32 v[162:163], v[160:161], v[162:163], s[28:29] op_sel_hi:[1,1,0]
	v_pk_fma_f32 v[168:169], v[166:167], v[168:169], s[28:29] op_sel_hi:[1,1,0]
	v_exp_f32_e32 v172, v172
	v_pk_fma_f32 v[162:163], v[160:161], v[162:163], s[30:31] op_sel_hi:[1,1,0]
	v_pk_fma_f32 v[168:169], v[166:167], v[168:169], s[30:31] op_sel_hi:[1,1,0]
	v_exp_f32_e32 v173, v173
	v_pk_fma_f32 v[162:163], v[160:161], v[162:163], s[48:49] op_sel_hi:[1,1,0]
	v_pk_fma_f32 v[168:169], v[166:167], v[168:169], s[48:49] op_sel_hi:[1,1,0]
	v_add_f32_e32 v170, 1.0, v170
	v_pk_fma_f32 v[162:163], v[160:161], v[162:163], s[50:51] op_sel_hi:[1,1,0]
	v_pk_fma_f32 v[168:169], v[166:167], v[168:169], s[50:51] op_sel_hi:[1,1,0]
	v_add_f32_e32 v171, 1.0, v171
	v_pk_fma_f32 v[162:163], v[160:161], v[162:163], s[52:53] op_sel_hi:[1,1,0]
	v_pk_fma_f32 v[168:169], v[166:167], v[168:169], s[52:53] op_sel_hi:[1,1,0]
	v_add_f32_e32 v172, 1.0, v172
	v_pk_fma_f32 v[160:161], v[160:161], v[162:163], s[54:55] op_sel_hi:[1,1,0]
	v_pk_fma_f32 v[166:167], v[166:167], v[168:169], s[54:55] op_sel_hi:[1,1,0]
	v_add_f32_e32 v173, 1.0, v173
	v_pk_fma_f32 v[158:159], v[158:159], v[160:161], 0.5 op_sel_hi:[1,1,0]
	v_pk_fma_f32 v[164:165], v[164:165], v[166:167], 0.5 op_sel_hi:[1,1,0]
	v_rcp_f32_e32 v178, v170
	v_pk_mul_f32 v[48:49], v[48:49], v[158:159]
	v_pk_mul_f32 v[50:51], v[50:51], v[164:165]
	v_rcp_f32_e32 v179, v171
	v_rcp_f32_e32 v180, v172
	v_rcp_f32_e32 v181, v173
	v_pk_mul_f32 v[44:45], v[44:45], v[178:179]
	v_pk_mul_f32 v[46:47], v[46:47], v[180:181]
	v_med3_f32 v158, v40, -4.0, 4.0
	v_med3_f32 v164, v42, -4.0, 4.0
	v_mul_f32_e32 v170, 0xbfb8aa3b, v36
	v_med3_f32 v159, v41, -4.0, 4.0
	v_med3_f32 v165, v43, -4.0, 4.0
	v_mul_f32_e32 v171, 0xbfb8aa3b, v37
	v_pk_mul_f32 v[160:161], v[158:159], v[158:159]
	v_pk_mul_f32 v[166:167], v[164:165], v[164:165]
	v_mul_f32_e32 v172, 0xbfb8aa3b, v38
	v_pk_fma_f32 v[160:161], v[160:161], s[72:73], -1.0 op_sel_hi:[1,0,0]
	v_pk_fma_f32 v[166:167], v[166:167], s[72:73], -1.0 op_sel_hi:[1,0,0]
	v_mul_f32_e32 v173, 0xbfb8aa3b, v39
	v_pk_fma_f32 v[162:163], v[160:161], s[74:75], v[198:199] op_sel_hi:[1,0,0]
	v_pk_fma_f32 v[168:169], v[166:167], s[74:75], v[198:199] op_sel_hi:[1,0,0]
	v_exp_f32_e32 v170, v170
	v_pk_fma_f32 v[162:163], v[160:161], v[162:163], s[2:3] op_sel_hi:[1,1,0]
	v_pk_fma_f32 v[168:169], v[166:167], v[168:169], s[2:3] op_sel_hi:[1,1,0]
	v_exp_f32_e32 v171, v171
	v_pk_fma_f32 v[162:163], v[160:161], v[162:163], s[28:29] op_sel_hi:[1,1,0]
	v_pk_fma_f32 v[168:169], v[166:167], v[168:169], s[28:29] op_sel_hi:[1,1,0]
	v_exp_f32_e32 v172, v172
	v_pk_fma_f32 v[162:163], v[160:161], v[162:163], s[30:31] op_sel_hi:[1,1,0]
	v_pk_fma_f32 v[168:169], v[166:167], v[168:169], s[30:31] op_sel_hi:[1,1,0]
	v_exp_f32_e32 v173, v173
	v_pk_fma_f32 v[162:163], v[160:161], v[162:163], s[48:49] op_sel_hi:[1,1,0]
	v_pk_fma_f32 v[168:169], v[166:167], v[168:169], s[48:49] op_sel_hi:[1,1,0]
	v_add_f32_e32 v170, 1.0, v170
	v_pk_fma_f32 v[162:163], v[160:161], v[162:163], s[50:51] op_sel_hi:[1,1,0]
	v_pk_fma_f32 v[168:169], v[166:167], v[168:169], s[50:51] op_sel_hi:[1,1,0]
	v_add_f32_e32 v171, 1.0, v171
	v_pk_fma_f32 v[162:163], v[160:161], v[162:163], s[52:53] op_sel_hi:[1,1,0]
	v_pk_fma_f32 v[168:169], v[166:167], v[168:169], s[52:53] op_sel_hi:[1,1,0]
	v_add_f32_e32 v172, 1.0, v172
	v_pk_fma_f32 v[160:161], v[160:161], v[162:163], s[54:55] op_sel_hi:[1,1,0]
	v_pk_fma_f32 v[166:167], v[166:167], v[168:169], s[54:55] op_sel_hi:[1,1,0]
	v_add_f32_e32 v173, 1.0, v173
	v_pk_fma_f32 v[158:159], v[158:159], v[160:161], 0.5 op_sel_hi:[1,1,0]
	v_pk_fma_f32 v[164:165], v[164:165], v[166:167], 0.5 op_sel_hi:[1,1,0]
	v_rcp_f32_e32 v178, v170
	v_pk_mul_f32 v[40:41], v[40:41], v[158:159]
	v_pk_mul_f32 v[42:43], v[42:43], v[164:165]
	v_rcp_f32_e32 v179, v171
	v_rcp_f32_e32 v180, v172
	v_rcp_f32_e32 v181, v173
	v_pk_mul_f32 v[36:37], v[36:37], v[178:179]
	v_pk_mul_f32 v[38:39], v[38:39], v[180:181]
	v_pk_mul_f32 v[44:45], v[44:45], v[48:49]
	v_pk_mul_f32 v[46:47], v[46:47], v[50:51]
	v_pk_mul_f32 v[36:37], v[36:37], v[40:41]
	v_pk_mul_f32 v[38:39], v[38:39], v[42:43]
	v_cvt_pk_bf16_f32 v48, v44, v45
	v_cvt_pk_bf16_f32 v49, v46, v47
	v_cvt_pk_bf16_f32 v50, v36, v37
	v_cvt_pk_bf16_f32 v51, v38, v39
	global_store_dwordx4 v187, v[48:51], s[10:11]
	v_pk_mul_f32 v[32:33], v[32:33], v[248:249] op_sel_hi:[1,0]
	v_pk_mul_f32 v[34:35], v[34:35], v[248:249] op_sel_hi:[1,0]
	v_pk_mul_f32 v[24:25], v[24:25], v[248:249] op_sel_hi:[1,0]
	v_pk_mul_f32 v[26:27], v[26:27], v[248:249] op_sel_hi:[1,0]
	v_pk_mul_f32 v[28:29], v[28:29], v[248:249] op_sel_hi:[1,0]
	v_pk_mul_f32 v[30:31], v[30:31], v[248:249] op_sel_hi:[1,0]
	v_pk_mul_f32 v[20:21], v[20:21], v[248:249] op_sel_hi:[1,0]
	v_pk_mul_f32 v[22:23], v[22:23], v[248:249] op_sel_hi:[1,0]
	v_med3_f32 v158, v32, -4.0, 4.0
	v_med3_f32 v164, v34, -4.0, 4.0
	v_mul_f32_e32 v170, 0xbfb8aa3b, v28
	v_med3_f32 v159, v33, -4.0, 4.0
	v_med3_f32 v165, v35, -4.0, 4.0
	v_mul_f32_e32 v171, 0xbfb8aa3b, v29
	v_pk_mul_f32 v[160:161], v[158:159], v[158:159]
	v_pk_mul_f32 v[166:167], v[164:165], v[164:165]
	v_mul_f32_e32 v172, 0xbfb8aa3b, v30
	v_pk_fma_f32 v[160:161], v[160:161], s[72:73], -1.0 op_sel_hi:[1,0,0]
	v_pk_fma_f32 v[166:167], v[166:167], s[72:73], -1.0 op_sel_hi:[1,0,0]
	v_mul_f32_e32 v173, 0xbfb8aa3b, v31
	v_pk_fma_f32 v[162:163], v[160:161], s[74:75], v[198:199] op_sel_hi:[1,0,0]
	v_pk_fma_f32 v[168:169], v[166:167], s[74:75], v[198:199] op_sel_hi:[1,0,0]
	v_exp_f32_e32 v170, v170
	v_pk_fma_f32 v[162:163], v[160:161], v[162:163], s[2:3] op_sel_hi:[1,1,0]
	v_pk_fma_f32 v[168:169], v[166:167], v[168:169], s[2:3] op_sel_hi:[1,1,0]
	v_exp_f32_e32 v171, v171
	v_pk_fma_f32 v[162:163], v[160:161], v[162:163], s[28:29] op_sel_hi:[1,1,0]
	v_pk_fma_f32 v[168:169], v[166:167], v[168:169], s[28:29] op_sel_hi:[1,1,0]
	v_exp_f32_e32 v172, v172
	v_pk_fma_f32 v[162:163], v[160:161], v[162:163], s[30:31] op_sel_hi:[1,1,0]
	v_pk_fma_f32 v[168:169], v[166:167], v[168:169], s[30:31] op_sel_hi:[1,1,0]
	v_exp_f32_e32 v173, v173
	v_pk_fma_f32 v[162:163], v[160:161], v[162:163], s[48:49] op_sel_hi:[1,1,0]
	v_pk_fma_f32 v[168:169], v[166:167], v[168:169], s[48:49] op_sel_hi:[1,1,0]
	v_add_f32_e32 v170, 1.0, v170
	v_pk_fma_f32 v[162:163], v[160:161], v[162:163], s[50:51] op_sel_hi:[1,1,0]
	v_pk_fma_f32 v[168:169], v[166:167], v[168:169], s[50:51] op_sel_hi:[1,1,0]
	v_add_f32_e32 v171, 1.0, v171
	v_pk_fma_f32 v[162:163], v[160:161], v[162:163], s[52:53] op_sel_hi:[1,1,0]
	v_pk_fma_f32 v[168:169], v[166:167], v[168:169], s[52:53] op_sel_hi:[1,1,0]
	v_add_f32_e32 v172, 1.0, v172
	v_pk_fma_f32 v[160:161], v[160:161], v[162:163], s[54:55] op_sel_hi:[1,1,0]
	v_pk_fma_f32 v[166:167], v[166:167], v[168:169], s[54:55] op_sel_hi:[1,1,0]
	v_add_f32_e32 v173, 1.0, v173
	v_pk_fma_f32 v[158:159], v[158:159], v[160:161], 0.5 op_sel_hi:[1,1,0]
	v_pk_fma_f32 v[164:165], v[164:165], v[166:167], 0.5 op_sel_hi:[1,1,0]
	v_rcp_f32_e32 v178, v170
	v_pk_mul_f32 v[32:33], v[32:33], v[158:159]
	v_pk_mul_f32 v[34:35], v[34:35], v[164:165]
	v_rcp_f32_e32 v179, v171
	v_rcp_f32_e32 v180, v172
	v_rcp_f32_e32 v181, v173
	v_pk_mul_f32 v[28:29], v[28:29], v[178:179]
	v_pk_mul_f32 v[30:31], v[30:31], v[180:181]
	v_med3_f32 v158, v24, -4.0, 4.0
	v_med3_f32 v164, v26, -4.0, 4.0
	v_mul_f32_e32 v170, 0xbfb8aa3b, v20
	v_med3_f32 v159, v25, -4.0, 4.0
	v_med3_f32 v165, v27, -4.0, 4.0
	v_mul_f32_e32 v171, 0xbfb8aa3b, v21
	v_pk_mul_f32 v[160:161], v[158:159], v[158:159]
	v_pk_mul_f32 v[166:167], v[164:165], v[164:165]
	v_mul_f32_e32 v172, 0xbfb8aa3b, v22
	v_pk_fma_f32 v[160:161], v[160:161], s[72:73], -1.0 op_sel_hi:[1,0,0]
	v_pk_fma_f32 v[166:167], v[166:167], s[72:73], -1.0 op_sel_hi:[1,0,0]
	v_mul_f32_e32 v173, 0xbfb8aa3b, v23
	v_pk_fma_f32 v[162:163], v[160:161], s[74:75], v[198:199] op_sel_hi:[1,0,0]
	v_pk_fma_f32 v[168:169], v[166:167], s[74:75], v[198:199] op_sel_hi:[1,0,0]
	v_exp_f32_e32 v170, v170
	v_pk_fma_f32 v[162:163], v[160:161], v[162:163], s[2:3] op_sel_hi:[1,1,0]
	v_pk_fma_f32 v[168:169], v[166:167], v[168:169], s[2:3] op_sel_hi:[1,1,0]
	v_exp_f32_e32 v171, v171
	v_pk_fma_f32 v[162:163], v[160:161], v[162:163], s[28:29] op_sel_hi:[1,1,0]
	v_pk_fma_f32 v[168:169], v[166:167], v[168:169], s[28:29] op_sel_hi:[1,1,0]
	v_exp_f32_e32 v172, v172
	v_pk_fma_f32 v[162:163], v[160:161], v[162:163], s[30:31] op_sel_hi:[1,1,0]
	v_pk_fma_f32 v[168:169], v[166:167], v[168:169], s[30:31] op_sel_hi:[1,1,0]
	v_exp_f32_e32 v173, v173
	v_pk_fma_f32 v[162:163], v[160:161], v[162:163], s[48:49] op_sel_hi:[1,1,0]
	v_pk_fma_f32 v[168:169], v[166:167], v[168:169], s[48:49] op_sel_hi:[1,1,0]
	v_add_f32_e32 v170, 1.0, v170
	v_pk_fma_f32 v[162:163], v[160:161], v[162:163], s[50:51] op_sel_hi:[1,1,0]
	v_pk_fma_f32 v[168:169], v[166:167], v[168:169], s[50:51] op_sel_hi:[1,1,0]
	v_add_f32_e32 v171, 1.0, v171
	v_pk_fma_f32 v[162:163], v[160:161], v[162:163], s[52:53] op_sel_hi:[1,1,0]
	v_pk_fma_f32 v[168:169], v[166:167], v[168:169], s[52:53] op_sel_hi:[1,1,0]
	v_add_f32_e32 v172, 1.0, v172
	v_pk_fma_f32 v[160:161], v[160:161], v[162:163], s[54:55] op_sel_hi:[1,1,0]
	v_pk_fma_f32 v[166:167], v[166:167], v[168:169], s[54:55] op_sel_hi:[1,1,0]
	v_add_f32_e32 v173, 1.0, v173
	v_pk_fma_f32 v[158:159], v[158:159], v[160:161], 0.5 op_sel_hi:[1,1,0]
	v_pk_fma_f32 v[164:165], v[164:165], v[166:167], 0.5 op_sel_hi:[1,1,0]
	v_rcp_f32_e32 v178, v170
	v_pk_mul_f32 v[24:25], v[24:25], v[158:159]
	v_pk_mul_f32 v[26:27], v[26:27], v[164:165]
	v_rcp_f32_e32 v179, v171
	v_rcp_f32_e32 v180, v172
	v_rcp_f32_e32 v181, v173
	v_pk_mul_f32 v[20:21], v[20:21], v[178:179]
	v_pk_mul_f32 v[22:23], v[22:23], v[180:181]
	v_pk_mul_f32 v[28:29], v[28:29], v[32:33]
	v_pk_mul_f32 v[30:31], v[30:31], v[34:35]
	v_pk_mul_f32 v[20:21], v[20:21], v[24:25]
	v_pk_mul_f32 v[22:23], v[22:23], v[26:27]
	v_cvt_pk_bf16_f32 v32, v28, v29
	v_cvt_pk_bf16_f32 v33, v30, v31
	v_cvt_pk_bf16_f32 v34, v20, v21
	v_cvt_pk_bf16_f32 v35, v22, v23
	global_store_dwordx4 v188, v[32:35], s[10:11]
	v_pk_mul_f32 v[16:17], v[16:17], v[250:251] op_sel_hi:[1,0]
	v_pk_mul_f32 v[18:19], v[18:19], v[250:251] op_sel_hi:[1,0]
	v_pk_mul_f32 v[8:9], v[8:9], v[250:251] op_sel_hi:[1,0]
	v_pk_mul_f32 v[10:11], v[10:11], v[250:251] op_sel_hi:[1,0]
	v_pk_mul_f32 v[12:13], v[12:13], v[250:251] op_sel_hi:[1,0]
	v_pk_mul_f32 v[14:15], v[14:15], v[250:251] op_sel_hi:[1,0]
	v_pk_mul_f32 v[4:5], v[4:5], v[250:251] op_sel_hi:[1,0]
	v_pk_mul_f32 v[6:7], v[6:7], v[250:251] op_sel_hi:[1,0]
	v_med3_f32 v158, v16, -4.0, 4.0
	v_med3_f32 v164, v18, -4.0, 4.0
	v_mul_f32_e32 v170, 0xbfb8aa3b, v12
	v_med3_f32 v159, v17, -4.0, 4.0
	v_med3_f32 v165, v19, -4.0, 4.0
	v_mul_f32_e32 v171, 0xbfb8aa3b, v13
	v_pk_mul_f32 v[160:161], v[158:159], v[158:159]
	v_pk_mul_f32 v[166:167], v[164:165], v[164:165]
	v_mul_f32_e32 v172, 0xbfb8aa3b, v14
	v_pk_fma_f32 v[160:161], v[160:161], s[72:73], -1.0 op_sel_hi:[1,0,0]
	v_pk_fma_f32 v[166:167], v[166:167], s[72:73], -1.0 op_sel_hi:[1,0,0]
	v_mul_f32_e32 v173, 0xbfb8aa3b, v15
	v_pk_fma_f32 v[162:163], v[160:161], s[74:75], v[198:199] op_sel_hi:[1,0,0]
	v_pk_fma_f32 v[168:169], v[166:167], s[74:75], v[198:199] op_sel_hi:[1,0,0]
	v_exp_f32_e32 v170, v170
	v_pk_fma_f32 v[162:163], v[160:161], v[162:163], s[2:3] op_sel_hi:[1,1,0]
	v_pk_fma_f32 v[168:169], v[166:167], v[168:169], s[2:3] op_sel_hi:[1,1,0]
	v_exp_f32_e32 v171, v171
	v_pk_fma_f32 v[162:163], v[160:161], v[162:163], s[28:29] op_sel_hi:[1,1,0]
	v_pk_fma_f32 v[168:169], v[166:167], v[168:169], s[28:29] op_sel_hi:[1,1,0]
	v_exp_f32_e32 v172, v172
	v_pk_fma_f32 v[162:163], v[160:161], v[162:163], s[30:31] op_sel_hi:[1,1,0]
	v_pk_fma_f32 v[168:169], v[166:167], v[168:169], s[30:31] op_sel_hi:[1,1,0]
	v_exp_f32_e32 v173, v173
	v_pk_fma_f32 v[162:163], v[160:161], v[162:163], s[48:49] op_sel_hi:[1,1,0]
	v_pk_fma_f32 v[168:169], v[166:167], v[168:169], s[48:49] op_sel_hi:[1,1,0]
	v_add_f32_e32 v170, 1.0, v170
	v_pk_fma_f32 v[162:163], v[160:161], v[162:163], s[50:51] op_sel_hi:[1,1,0]
	v_pk_fma_f32 v[168:169], v[166:167], v[168:169], s[50:51] op_sel_hi:[1,1,0]
	v_add_f32_e32 v171, 1.0, v171
	v_pk_fma_f32 v[162:163], v[160:161], v[162:163], s[52:53] op_sel_hi:[1,1,0]
	v_pk_fma_f32 v[168:169], v[166:167], v[168:169], s[52:53] op_sel_hi:[1,1,0]
	v_add_f32_e32 v172, 1.0, v172
	v_pk_fma_f32 v[160:161], v[160:161], v[162:163], s[54:55] op_sel_hi:[1,1,0]
	v_pk_fma_f32 v[166:167], v[166:167], v[168:169], s[54:55] op_sel_hi:[1,1,0]
	v_add_f32_e32 v173, 1.0, v173
	v_pk_fma_f32 v[158:159], v[158:159], v[160:161], 0.5 op_sel_hi:[1,1,0]
	v_pk_fma_f32 v[164:165], v[164:165], v[166:167], 0.5 op_sel_hi:[1,1,0]
	v_rcp_f32_e32 v178, v170
	v_pk_mul_f32 v[16:17], v[16:17], v[158:159]
	v_pk_mul_f32 v[18:19], v[18:19], v[164:165]
	v_rcp_f32_e32 v179, v171
	v_rcp_f32_e32 v180, v172
	v_rcp_f32_e32 v181, v173
	v_pk_mul_f32 v[12:13], v[12:13], v[178:179]
	v_pk_mul_f32 v[14:15], v[14:15], v[180:181]
	v_med3_f32 v158, v8, -4.0, 4.0
	v_med3_f32 v164, v10, -4.0, 4.0
	v_mul_f32_e32 v170, 0xbfb8aa3b, v4
	v_med3_f32 v159, v9, -4.0, 4.0
	v_med3_f32 v165, v11, -4.0, 4.0
	v_mul_f32_e32 v171, 0xbfb8aa3b, v5
	v_pk_mul_f32 v[160:161], v[158:159], v[158:159]
	v_pk_mul_f32 v[166:167], v[164:165], v[164:165]
	v_mul_f32_e32 v172, 0xbfb8aa3b, v6
	v_pk_fma_f32 v[160:161], v[160:161], s[72:73], -1.0 op_sel_hi:[1,0,0]
	v_pk_fma_f32 v[166:167], v[166:167], s[72:73], -1.0 op_sel_hi:[1,0,0]
	v_mul_f32_e32 v173, 0xbfb8aa3b, v7
	v_pk_fma_f32 v[162:163], v[160:161], s[74:75], v[198:199] op_sel_hi:[1,0,0]
	v_pk_fma_f32 v[168:169], v[166:167], s[74:75], v[198:199] op_sel_hi:[1,0,0]
	v_exp_f32_e32 v170, v170
	v_pk_fma_f32 v[162:163], v[160:161], v[162:163], s[2:3] op_sel_hi:[1,1,0]
	v_pk_fma_f32 v[168:169], v[166:167], v[168:169], s[2:3] op_sel_hi:[1,1,0]
	v_exp_f32_e32 v171, v171
	v_pk_fma_f32 v[162:163], v[160:161], v[162:163], s[28:29] op_sel_hi:[1,1,0]
	v_pk_fma_f32 v[168:169], v[166:167], v[168:169], s[28:29] op_sel_hi:[1,1,0]
	v_exp_f32_e32 v172, v172
	v_pk_fma_f32 v[162:163], v[160:161], v[162:163], s[30:31] op_sel_hi:[1,1,0]
	v_pk_fma_f32 v[168:169], v[166:167], v[168:169], s[30:31] op_sel_hi:[1,1,0]
	v_exp_f32_e32 v173, v173
	v_pk_fma_f32 v[162:163], v[160:161], v[162:163], s[48:49] op_sel_hi:[1,1,0]
	v_pk_fma_f32 v[168:169], v[166:167], v[168:169], s[48:49] op_sel_hi:[1,1,0]
	v_add_f32_e32 v170, 1.0, v170
	v_pk_fma_f32 v[162:163], v[160:161], v[162:163], s[50:51] op_sel_hi:[1,1,0]
	v_pk_fma_f32 v[168:169], v[166:167], v[168:169], s[50:51] op_sel_hi:[1,1,0]
	v_add_f32_e32 v171, 1.0, v171
	v_pk_fma_f32 v[162:163], v[160:161], v[162:163], s[52:53] op_sel_hi:[1,1,0]
	v_pk_fma_f32 v[168:169], v[166:167], v[168:169], s[52:53] op_sel_hi:[1,1,0]
	v_add_f32_e32 v172, 1.0, v172
	v_pk_fma_f32 v[160:161], v[160:161], v[162:163], s[54:55] op_sel_hi:[1,1,0]
	v_pk_fma_f32 v[166:167], v[166:167], v[168:169], s[54:55] op_sel_hi:[1,1,0]
	v_add_f32_e32 v173, 1.0, v173
	v_pk_fma_f32 v[158:159], v[158:159], v[160:161], 0.5 op_sel_hi:[1,1,0]
	v_pk_fma_f32 v[164:165], v[164:165], v[166:167], 0.5 op_sel_hi:[1,1,0]
	v_rcp_f32_e32 v178, v170
	v_pk_mul_f32 v[8:9], v[8:9], v[158:159]
	v_pk_mul_f32 v[10:11], v[10:11], v[164:165]
	v_rcp_f32_e32 v179, v171
	v_rcp_f32_e32 v180, v172
	v_rcp_f32_e32 v181, v173
	v_pk_mul_f32 v[4:5], v[4:5], v[178:179]
	v_pk_mul_f32 v[6:7], v[6:7], v[180:181]
	v_pk_mul_f32 v[12:13], v[12:13], v[16:17]
	v_pk_mul_f32 v[14:15], v[14:15], v[18:19]
	v_pk_mul_f32 v[4:5], v[4:5], v[8:9]
	v_pk_mul_f32 v[6:7], v[6:7], v[10:11]
	v_cvt_pk_bf16_f32 v16, v12, v13
	v_cvt_pk_bf16_f32 v17, v14, v15
	v_cvt_pk_bf16_f32 v18, v4, v5
	v_cvt_pk_bf16_f32 v19, v6, v7
	global_store_dwordx4 v189, v[16:19], s[10:11]
	s_andn2_b64 vcc, exec, s[6:7]
	s_mov_b64 s[0:1], -1
	s_cbranch_vccnz .LBB0_442
